# PQ GEMM main loop rewritten: LDS-DMA 3-stage ring + swizzle; activation section batched
# speedup vs baseline: 1.1089x; 1.0069x over previous
.LBB0_1810:
	s_lshr_b32 s10, s9, 1
	s_and_b32 s10, s10, 0x78
	s_or_b32 s10, s10, s67
	s_waitcnt vmcnt(0)
	s_lshl_b32 s13, s10, 8
	s_lshl_b32 s6, s9, 7
	s_and_b32 s10, s6, 0x780
	s_and_b32 s7, s6, 0x7800
	s_and_b32 s19, s8, 0x780
	s_or_b32 s22, s75, s7
	s_mov_b32 s23, 0
	s_mov_b64 s[6:7], s[86:87]
	s_lshr_b32 s21, s13, 21
	s_lshl_b32 s20, s13, 11
	s_add_u32 s50, s70, s20
	s_addc_u32 s51, s71, s21
	s_lshr_b32 s21, s10, 21
	s_lshl_b32 s20, s10, 11
	s_add_u32 s52, s0, s20
	s_addc_u32 s53, s1, s21
	v_lshrrev_b32_e32 v40, 6, v179
	s_nop 0
	v_readfirstlane_b32 s60, v40
	v_and_b32_e32 v41, 63, v179
	v_lshrrev_b32_e32 v42, 2, v41
	v_lshrrev_b32_e32 v43, 2, v42
	v_sub_u32_e32 v43, 0, v43
	v_and_b32_e32 v43, 3, v43
	v_xor_b32_e32 v43, v43, v41
	v_and_b32_e32 v43, 3, v43
	v_lshlrev_b32_e32 v43, 4, v43
	s_lshl_b32 s61, s60, 6
	v_add_u32_e32 v40, s61, v42
	v_lshl_add_u32 v10, v40, 11, v43
	v_add_u32_e32 v11, 0x8000, v10
	v_add_u32_e32 v12, 0x10000, v10
	v_add_u32_e32 v13, 0x18000, v10
	s_lshl_b32 s61, s60, 5
	v_add_u32_e32 v40, s61, v42
	v_lshl_add_u32 v14, v40, 11, v43
	v_add_u32_e32 v15, 0x8000, v14
	v_and_b32_e32 v40, 15, v179
	v_bfe_u32 v41, v179, 4, 2
	v_lshrrev_b32_e32 v42, 2, v40
	v_sub_u32_e32 v42, 0, v42
	v_and_b32_e32 v42, 3, v42
	v_xor_b32_e32 v41, v41, v42
	v_lshlrev_b32_e32 v41, 4, v41
	v_lshl_add_u32 v17, v40, 6, v41
	s_lshl_b32 s61, s60, 12
	v_add_u32_e32 v16, s61, v17
	v_add_u32_e32 v17, 16384, v17
	s_lshl_b32 s57, s60, 12
	s_lshl_b32 s58, s60, 11
	s_add_u32 s58, s58, 16384
	v_mov_b32_e32 v174, 0
	v_mov_b32_e32 v175, 0
	v_mov_b32_e32 v176, 0
	v_mov_b32_e32 v177, 0
	v_mov_b32_e32 v170, 0
	v_mov_b32_e32 v171, 0
	v_mov_b32_e32 v172, 0
	v_mov_b32_e32 v173, 0
	v_mov_b32_e32 v166, 0
	v_mov_b32_e32 v167, 0
	v_mov_b32_e32 v168, 0
	v_mov_b32_e32 v169, 0
	v_mov_b32_e32 v162, 0
	v_mov_b32_e32 v163, 0
	v_mov_b32_e32 v164, 0
	v_mov_b32_e32 v165, 0
	v_mov_b32_e32 v158, 0
	v_mov_b32_e32 v159, 0
	v_mov_b32_e32 v160, 0
	v_mov_b32_e32 v161, 0
	v_mov_b32_e32 v154, 0
	v_mov_b32_e32 v155, 0
	v_mov_b32_e32 v156, 0
	v_mov_b32_e32 v157, 0
	v_mov_b32_e32 v150, 0
	v_mov_b32_e32 v151, 0
	v_mov_b32_e32 v152, 0
	v_mov_b32_e32 v153, 0
	v_mov_b32_e32 v138, 0
	v_mov_b32_e32 v139, 0
	v_mov_b32_e32 v140, 0
	v_mov_b32_e32 v141, 0
	v_mov_b32_e32 v134, 0
	v_mov_b32_e32 v135, 0
	v_mov_b32_e32 v136, 0
	v_mov_b32_e32 v137, 0
	v_mov_b32_e32 v130, 0
	v_mov_b32_e32 v131, 0
	v_mov_b32_e32 v132, 0
	v_mov_b32_e32 v133, 0
	v_mov_b32_e32 v126, 0
	v_mov_b32_e32 v127, 0
	v_mov_b32_e32 v128, 0
	v_mov_b32_e32 v129, 0
	v_mov_b32_e32 v118, 0
	v_mov_b32_e32 v119, 0
	v_mov_b32_e32 v120, 0
	v_mov_b32_e32 v121, 0
	v_mov_b32_e32 v110, 0
	v_mov_b32_e32 v111, 0
	v_mov_b32_e32 v112, 0
	v_mov_b32_e32 v113, 0
	v_mov_b32_e32 v106, 0
	v_mov_b32_e32 v107, 0
	v_mov_b32_e32 v108, 0
	v_mov_b32_e32 v109, 0
	v_mov_b32_e32 v102, 0
	v_mov_b32_e32 v103, 0
	v_mov_b32_e32 v104, 0
	v_mov_b32_e32 v105, 0
	v_mov_b32_e32 v98, 0
	v_mov_b32_e32 v99, 0
	v_mov_b32_e32 v100, 0
	v_mov_b32_e32 v101, 0
	v_mov_b32_e32 v86, 0
	v_mov_b32_e32 v87, 0
	v_mov_b32_e32 v88, 0
	v_mov_b32_e32 v89, 0
	v_mov_b32_e32 v82, 0
	v_mov_b32_e32 v83, 0
	v_mov_b32_e32 v84, 0
	v_mov_b32_e32 v85, 0
	v_mov_b32_e32 v78, 0
	v_mov_b32_e32 v79, 0
	v_mov_b32_e32 v80, 0
	v_mov_b32_e32 v81, 0
	v_mov_b32_e32 v74, 0
	v_mov_b32_e32 v75, 0
	v_mov_b32_e32 v76, 0
	v_mov_b32_e32 v77, 0
	v_mov_b32_e32 v70, 0
	v_mov_b32_e32 v71, 0
	v_mov_b32_e32 v72, 0
	v_mov_b32_e32 v73, 0
	v_mov_b32_e32 v58, 0
	v_mov_b32_e32 v59, 0
	v_mov_b32_e32 v60, 0
	v_mov_b32_e32 v61, 0
	v_mov_b32_e32 v54, 0
	v_mov_b32_e32 v55, 0
	v_mov_b32_e32 v56, 0
	v_mov_b32_e32 v57, 0
	v_mov_b32_e32 v50, 0
	v_mov_b32_e32 v51, 0
	v_mov_b32_e32 v52, 0
	v_mov_b32_e32 v53, 0
	v_mov_b32_e32 v46, 0
	v_mov_b32_e32 v47, 0
	v_mov_b32_e32 v48, 0
	v_mov_b32_e32 v49, 0
	v_mov_b32_e32 v34, 0
	v_mov_b32_e32 v35, 0
	v_mov_b32_e32 v36, 0
	v_mov_b32_e32 v37, 0
	v_mov_b32_e32 v30, 0
	v_mov_b32_e32 v31, 0
	v_mov_b32_e32 v32, 0
	v_mov_b32_e32 v33, 0
	v_mov_b32_e32 v26, 0
	v_mov_b32_e32 v27, 0
	v_mov_b32_e32 v28, 0
	v_mov_b32_e32 v29, 0
	v_mov_b32_e32 v22, 0
	v_mov_b32_e32 v23, 0
	v_mov_b32_e32 v24, 0
	v_mov_b32_e32 v25, 0
	v_mov_b32_e32 v18, 0
	v_mov_b32_e32 v19, 0
	v_mov_b32_e32 v20, 0
	v_mov_b32_e32 v21, 0
	v_mov_b32_e32 v6, 0
	v_mov_b32_e32 v7, 0
	v_mov_b32_e32 v8, 0
	v_mov_b32_e32 v9, 0
	v_mov_b32_e32 v2, 0
	v_mov_b32_e32 v3, 0
	v_mov_b32_e32 v4, 0
	v_mov_b32_e32 v5, 0
	s_mov_b32 s55, 0
	s_mov_b32 s56, 0
	s_barrier
	s_add_u32 s59, s56, s57
	s_mov_b32 m0, s59
	s_nop 0
	global_load_lds_dwordx4 v10, s[50:51]
	s_add_u32 m0, s59, 1024
	s_nop 0
	global_load_lds_dwordx4 v11, s[50:51]
	s_add_u32 m0, s59, 2048
	s_nop 0
	global_load_lds_dwordx4 v12, s[50:51]
	s_add_u32 m0, s59, 3072
	s_nop 0
	global_load_lds_dwordx4 v13, s[50:51]
	s_add_u32 s59, s56, s58
	s_mov_b32 m0, s59
	s_nop 0
	global_load_lds_dwordx4 v14, s[52:53]
	s_add_u32 m0, s59, 1024
	s_nop 0
	global_load_lds_dwordx4 v15, s[52:53]
	s_add_u32 s50, s50, 64
	s_addc_u32 s51, s51, 0
	s_add_u32 s52, s52, 64
	s_addc_u32 s53, s53, 0
	s_mov_b32 s56, 24576
	s_add_u32 s59, s56, s57
	s_mov_b32 m0, s59
	s_nop 0
	global_load_lds_dwordx4 v10, s[50:51]
	s_add_u32 m0, s59, 1024
	s_nop 0
	global_load_lds_dwordx4 v11, s[50:51]
	s_add_u32 m0, s59, 2048
	s_nop 0
	global_load_lds_dwordx4 v12, s[50:51]
	s_add_u32 m0, s59, 3072
	s_nop 0
	global_load_lds_dwordx4 v13, s[50:51]
	s_add_u32 s59, s56, s58
	s_mov_b32 m0, s59
	s_nop 0
	global_load_lds_dwordx4 v14, s[52:53]
	s_add_u32 m0, s59, 1024
	s_nop 0
	global_load_lds_dwordx4 v15, s[52:53]
	s_add_u32 s50, s50, 64
	s_addc_u32 s51, s51, 0
	s_add_u32 s52, s52, 64
	s_addc_u32 s53, s53, 0
	s_mov_b32 s56, 49152
	s_mov_b32 s54, 30
.Lg_pq_loop:
	s_waitcnt vmcnt(6)
	s_barrier
	s_add_u32 s59, s56, s57
	s_mov_b32 m0, s59
	s_nop 0
	global_load_lds_dwordx4 v10, s[50:51]
	s_add_u32 m0, s59, 1024
	s_nop 0
	global_load_lds_dwordx4 v11, s[50:51]
	s_add_u32 m0, s59, 2048
	s_nop 0
	global_load_lds_dwordx4 v12, s[50:51]
	s_add_u32 m0, s59, 3072
	s_nop 0
	global_load_lds_dwordx4 v13, s[50:51]
	s_add_u32 s59, s56, s58
	s_mov_b32 m0, s59
	s_nop 0
	global_load_lds_dwordx4 v14, s[52:53]
	s_add_u32 m0, s59, 1024
	s_nop 0
	global_load_lds_dwordx4 v15, s[52:53]
	s_add_u32 s50, s50, 64
	s_addc_u32 s51, s51, 0
	s_add_u32 s52, s52, 64
	s_addc_u32 s53, s53, 0
	v_add_u32_e32 v38, s55, v16
	v_add_u32_e32 v39, s55, v17
	ds_read_b128 v[180:183], v38
	ds_read_b128 v[184:187], v38 offset:1024
	ds_read_b128 v[188:191], v38 offset:2048
	ds_read_b128 v[192:195], v38 offset:3072
	ds_read_b128 v[196:199], v39
	ds_read_b128 v[200:203], v39 offset:1024
	ds_read_b128 v[204:207], v39 offset:2048
	ds_read_b128 v[216:219], v39 offset:3072
	ds_read_b128 v[226:229], v39 offset:4096
	ds_read_b128 v[230:233], v39 offset:5120
	ds_read_b128 v[234:237], v39 offset:6144
	ds_read_b128 v[238:241], v39 offset:7168
	s_waitcnt lgkmcnt(7)
	v_mfma_f32_16x16x32_bf16 v[174:177], v[196:199], v[180:183], v[174:177]
	v_mfma_f32_16x16x32_bf16 v[134:137], v[196:199], v[184:187], v[134:137]
	v_mfma_f32_16x16x32_bf16 v[86:89], v[196:199], v[188:191], v[86:89]
	v_mfma_f32_16x16x32_bf16 v[46:49], v[196:199], v[192:195], v[46:49]
	s_waitcnt lgkmcnt(6)
	v_mfma_f32_16x16x32_bf16 v[170:173], v[200:203], v[180:183], v[170:173]
	v_mfma_f32_16x16x32_bf16 v[130:133], v[200:203], v[184:187], v[130:133]
	v_mfma_f32_16x16x32_bf16 v[82:85], v[200:203], v[188:191], v[82:85]
	v_mfma_f32_16x16x32_bf16 v[34:37], v[200:203], v[192:195], v[34:37]
	s_waitcnt lgkmcnt(5)
	v_mfma_f32_16x16x32_bf16 v[166:169], v[204:207], v[180:183], v[166:169]
	v_mfma_f32_16x16x32_bf16 v[126:129], v[204:207], v[184:187], v[126:129]
	v_mfma_f32_16x16x32_bf16 v[78:81], v[204:207], v[188:191], v[78:81]
	v_mfma_f32_16x16x32_bf16 v[30:33], v[204:207], v[192:195], v[30:33]
	s_waitcnt lgkmcnt(4)
	v_mfma_f32_16x16x32_bf16 v[162:165], v[216:219], v[180:183], v[162:165]
	v_mfma_f32_16x16x32_bf16 v[118:121], v[216:219], v[184:187], v[118:121]
	v_mfma_f32_16x16x32_bf16 v[74:77], v[216:219], v[188:191], v[74:77]
	v_mfma_f32_16x16x32_bf16 v[26:29], v[216:219], v[192:195], v[26:29]
	s_waitcnt lgkmcnt(3)
	v_mfma_f32_16x16x32_bf16 v[158:161], v[226:229], v[180:183], v[158:161]
	v_mfma_f32_16x16x32_bf16 v[110:113], v[226:229], v[184:187], v[110:113]
	v_mfma_f32_16x16x32_bf16 v[70:73], v[226:229], v[188:191], v[70:73]
	v_mfma_f32_16x16x32_bf16 v[22:25], v[226:229], v[192:195], v[22:25]
	s_waitcnt lgkmcnt(2)
	v_mfma_f32_16x16x32_bf16 v[154:157], v[230:233], v[180:183], v[154:157]
	v_mfma_f32_16x16x32_bf16 v[106:109], v[230:233], v[184:187], v[106:109]
	v_mfma_f32_16x16x32_bf16 v[58:61], v[230:233], v[188:191], v[58:61]
	v_mfma_f32_16x16x32_bf16 v[18:21], v[230:233], v[192:195], v[18:21]
	s_waitcnt lgkmcnt(1)
	v_mfma_f32_16x16x32_bf16 v[150:153], v[234:237], v[180:183], v[150:153]
	v_mfma_f32_16x16x32_bf16 v[102:105], v[234:237], v[184:187], v[102:105]
	v_mfma_f32_16x16x32_bf16 v[54:57], v[234:237], v[188:191], v[54:57]
	v_mfma_f32_16x16x32_bf16 v[6:9], v[234:237], v[192:195], v[6:9]
	s_waitcnt lgkmcnt(0)
	v_mfma_f32_16x16x32_bf16 v[138:141], v[238:241], v[180:183], v[138:141]
	v_mfma_f32_16x16x32_bf16 v[98:101], v[238:241], v[184:187], v[98:101]
	v_mfma_f32_16x16x32_bf16 v[50:53], v[238:241], v[188:191], v[50:53]
	v_mfma_f32_16x16x32_bf16 v[2:5], v[238:241], v[192:195], v[2:5]
	s_add_u32 s55, s55, 24576
	s_cmp_lt_u32 s55, 73728
	s_cselect_b32 s55, s55, 0
	s_add_u32 s56, s56, 24576
	s_cmp_lt_u32 s56, 73728
	s_cselect_b32 s56, s56, 0
	s_sub_u32 s54, s54, 1
	s_cmp_lg_u32 s54, 0
	s_cbranch_scc1 .Lg_pq_loop
	s_waitcnt vmcnt(6)
	s_barrier
	v_add_u32_e32 v38, s55, v16
	v_add_u32_e32 v39, s55, v17
	ds_read_b128 v[180:183], v38
	ds_read_b128 v[184:187], v38 offset:1024
	ds_read_b128 v[188:191], v38 offset:2048
	ds_read_b128 v[192:195], v38 offset:3072
	ds_read_b128 v[196:199], v39
	ds_read_b128 v[200:203], v39 offset:1024
	ds_read_b128 v[204:207], v39 offset:2048
	ds_read_b128 v[216:219], v39 offset:3072
	ds_read_b128 v[226:229], v39 offset:4096
	ds_read_b128 v[230:233], v39 offset:5120
	ds_read_b128 v[234:237], v39 offset:6144
	ds_read_b128 v[238:241], v39 offset:7168
	s_waitcnt lgkmcnt(7)
	v_mfma_f32_16x16x32_bf16 v[174:177], v[196:199], v[180:183], v[174:177]
	v_mfma_f32_16x16x32_bf16 v[134:137], v[196:199], v[184:187], v[134:137]
	v_mfma_f32_16x16x32_bf16 v[86:89], v[196:199], v[188:191], v[86:89]
	v_mfma_f32_16x16x32_bf16 v[46:49], v[196:199], v[192:195], v[46:49]
	s_waitcnt lgkmcnt(6)
	v_mfma_f32_16x16x32_bf16 v[170:173], v[200:203], v[180:183], v[170:173]
	v_mfma_f32_16x16x32_bf16 v[130:133], v[200:203], v[184:187], v[130:133]
	v_mfma_f32_16x16x32_bf16 v[82:85], v[200:203], v[188:191], v[82:85]
	v_mfma_f32_16x16x32_bf16 v[34:37], v[200:203], v[192:195], v[34:37]
	s_waitcnt lgkmcnt(5)
	v_mfma_f32_16x16x32_bf16 v[166:169], v[204:207], v[180:183], v[166:169]
	v_mfma_f32_16x16x32_bf16 v[126:129], v[204:207], v[184:187], v[126:129]
	v_mfma_f32_16x16x32_bf16 v[78:81], v[204:207], v[188:191], v[78:81]
	v_mfma_f32_16x16x32_bf16 v[30:33], v[204:207], v[192:195], v[30:33]
	s_waitcnt lgkmcnt(4)
	v_mfma_f32_16x16x32_bf16 v[162:165], v[216:219], v[180:183], v[162:165]
	v_mfma_f32_16x16x32_bf16 v[118:121], v[216:219], v[184:187], v[118:121]
	v_mfma_f32_16x16x32_bf16 v[74:77], v[216:219], v[188:191], v[74:77]
	v_mfma_f32_16x16x32_bf16 v[26:29], v[216:219], v[192:195], v[26:29]
	s_waitcnt lgkmcnt(3)
	v_mfma_f32_16x16x32_bf16 v[158:161], v[226:229], v[180:183], v[158:161]
	v_mfma_f32_16x16x32_bf16 v[110:113], v[226:229], v[184:187], v[110:113]
	v_mfma_f32_16x16x32_bf16 v[70:73], v[226:229], v[188:191], v[70:73]
	v_mfma_f32_16x16x32_bf16 v[22:25], v[226:229], v[192:195], v[22:25]
	s_waitcnt lgkmcnt(2)
	v_mfma_f32_16x16x32_bf16 v[154:157], v[230:233], v[180:183], v[154:157]
	v_mfma_f32_16x16x32_bf16 v[106:109], v[230:233], v[184:187], v[106:109]
	v_mfma_f32_16x16x32_bf16 v[58:61], v[230:233], v[188:191], v[58:61]
	v_mfma_f32_16x16x32_bf16 v[18:21], v[230:233], v[192:195], v[18:21]
	s_waitcnt lgkmcnt(1)
	v_mfma_f32_16x16x32_bf16 v[150:153], v[234:237], v[180:183], v[150:153]
	v_mfma_f32_16x16x32_bf16 v[102:105], v[234:237], v[184:187], v[102:105]
	v_mfma_f32_16x16x32_bf16 v[54:57], v[234:237], v[188:191], v[54:57]
	v_mfma_f32_16x16x32_bf16 v[6:9], v[234:237], v[192:195], v[6:9]
	s_waitcnt lgkmcnt(0)
	v_mfma_f32_16x16x32_bf16 v[138:141], v[238:241], v[180:183], v[138:141]
	v_mfma_f32_16x16x32_bf16 v[98:101], v[238:241], v[184:187], v[98:101]
	v_mfma_f32_16x16x32_bf16 v[50:53], v[238:241], v[188:191], v[50:53]
	v_mfma_f32_16x16x32_bf16 v[2:5], v[238:241], v[192:195], v[2:5]
	s_add_u32 s55, s55, 24576
	s_cmp_lt_u32 s55, 73728
	s_cselect_b32 s55, s55, 0
	s_add_u32 s56, s56, 24576
	s_cmp_lt_u32 s56, 73728
	s_cselect_b32 s56, s56, 0
	s_waitcnt vmcnt(0)
	s_barrier
	v_add_u32_e32 v38, s55, v16
	v_add_u32_e32 v39, s55, v17
	ds_read_b128 v[180:183], v38
	ds_read_b128 v[184:187], v38 offset:1024
	ds_read_b128 v[188:191], v38 offset:2048
	ds_read_b128 v[192:195], v38 offset:3072
	ds_read_b128 v[196:199], v39
	ds_read_b128 v[200:203], v39 offset:1024
	ds_read_b128 v[204:207], v39 offset:2048
	ds_read_b128 v[216:219], v39 offset:3072
	ds_read_b128 v[226:229], v39 offset:4096
	ds_read_b128 v[230:233], v39 offset:5120
	ds_read_b128 v[234:237], v39 offset:6144
	ds_read_b128 v[238:241], v39 offset:7168
	s_waitcnt lgkmcnt(7)
	v_mfma_f32_16x16x32_bf16 v[174:177], v[196:199], v[180:183], v[174:177]
	v_mfma_f32_16x16x32_bf16 v[134:137], v[196:199], v[184:187], v[134:137]
	v_mfma_f32_16x16x32_bf16 v[86:89], v[196:199], v[188:191], v[86:89]
	v_mfma_f32_16x16x32_bf16 v[46:49], v[196:199], v[192:195], v[46:49]
	s_waitcnt lgkmcnt(6)
	v_mfma_f32_16x16x32_bf16 v[170:173], v[200:203], v[180:183], v[170:173]
	v_mfma_f32_16x16x32_bf16 v[130:133], v[200:203], v[184:187], v[130:133]
	v_mfma_f32_16x16x32_bf16 v[82:85], v[200:203], v[188:191], v[82:85]
	v_mfma_f32_16x16x32_bf16 v[34:37], v[200:203], v[192:195], v[34:37]
	s_waitcnt lgkmcnt(5)
	v_mfma_f32_16x16x32_bf16 v[166:169], v[204:207], v[180:183], v[166:169]
	v_mfma_f32_16x16x32_bf16 v[126:129], v[204:207], v[184:187], v[126:129]
	v_mfma_f32_16x16x32_bf16 v[78:81], v[204:207], v[188:191], v[78:81]
	v_mfma_f32_16x16x32_bf16 v[30:33], v[204:207], v[192:195], v[30:33]
	s_waitcnt lgkmcnt(4)
	v_mfma_f32_16x16x32_bf16 v[162:165], v[216:219], v[180:183], v[162:165]
	v_mfma_f32_16x16x32_bf16 v[118:121], v[216:219], v[184:187], v[118:121]
	v_mfma_f32_16x16x32_bf16 v[74:77], v[216:219], v[188:191], v[74:77]
	v_mfma_f32_16x16x32_bf16 v[26:29], v[216:219], v[192:195], v[26:29]
	s_waitcnt lgkmcnt(3)
	v_mfma_f32_16x16x32_bf16 v[158:161], v[226:229], v[180:183], v[158:161]
	v_mfma_f32_16x16x32_bf16 v[110:113], v[226:229], v[184:187], v[110:113]
	v_mfma_f32_16x16x32_bf16 v[70:73], v[226:229], v[188:191], v[70:73]
	v_mfma_f32_16x16x32_bf16 v[22:25], v[226:229], v[192:195], v[22:25]
	s_waitcnt lgkmcnt(2)
	v_mfma_f32_16x16x32_bf16 v[154:157], v[230:233], v[180:183], v[154:157]
	v_mfma_f32_16x16x32_bf16 v[106:109], v[230:233], v[184:187], v[106:109]
	v_mfma_f32_16x16x32_bf16 v[58:61], v[230:233], v[188:191], v[58:61]
	v_mfma_f32_16x16x32_bf16 v[18:21], v[230:233], v[192:195], v[18:21]
	s_waitcnt lgkmcnt(1)
	v_mfma_f32_16x16x32_bf16 v[150:153], v[234:237], v[180:183], v[150:153]
	v_mfma_f32_16x16x32_bf16 v[102:105], v[234:237], v[184:187], v[102:105]
	v_mfma_f32_16x16x32_bf16 v[54:57], v[234:237], v[188:191], v[54:57]
	v_mfma_f32_16x16x32_bf16 v[6:9], v[234:237], v[192:195], v[6:9]
	s_waitcnt lgkmcnt(0)
	v_mfma_f32_16x16x32_bf16 v[138:141], v[238:241], v[180:183], v[138:141]
	v_mfma_f32_16x16x32_bf16 v[98:101], v[238:241], v[184:187], v[98:101]
	v_mfma_f32_16x16x32_bf16 v[50:53], v[238:241], v[188:191], v[50:53]
	v_mfma_f32_16x16x32_bf16 v[2:5], v[238:241], v[192:195], v[2:5]
	s_branch .LBB0_1809

.Lu_cloop:
	s_waitcnt vmcnt(16)
	ds_write_b128 v168, v[2:5]
	ds_write_b128 v168, v[6:9] offset:1024
	s_waitcnt lgkmcnt(2)
	v_lshl_add_u32 v174, v150, 10, v166
	global_load_dwordx4 v[2:5], v174, s[50:51]
	v_lshl_add_u32 v175, v151, 10, v167
	global_load_dwordx4 v[6:9], v175, s[50:51]
	ds_read_b128 v[180:183], v169
	ds_read_b128 v[184:187], v170
	s_waitcnt vmcnt(16)
	ds_write_b128 v168, v[10:13]
	ds_write_b128 v168, v[14:17] offset:1024
	v_lshl_add_u32 v176, v152, 10, v166
	global_load_dwordx4 v[10:13], v176, s[50:51]
	v_lshl_add_u32 v177, v153, 10, v167
	global_load_dwordx4 v[14:17], v177, s[50:51]
	ds_read_b128 v[188:191], v169
	ds_read_b128 v[192:195], v170
	s_waitcnt lgkmcnt(4)
	v_mfma_f32_16x16x32_fp8_fp8 v[196:199], v[180:181], v[134:135], 0
	v_mfma_f32_16x16x32_fp8_fp8 v[196:199], v[182:183], v[136:137], v[196:199]
	v_mfma_f32_16x16x32_fp8_fp8 v[196:199], v[184:185], v[138:139], v[196:199]
	v_mfma_f32_16x16x32_fp8_fp8 v[196:199], v[186:187], v[140:141], v[196:199]
	s_waitcnt vmcnt(16)
	ds_write_b128 v168, v[18:21]
	ds_write_b128 v168, v[22:25] offset:1024
	v_lshl_add_u32 v174, v154, 10, v166
	global_load_dwordx4 v[18:21], v174, s[50:51]
	v_lshl_add_u32 v175, v155, 10, v167
	global_load_dwordx4 v[22:25], v175, s[50:51]
	ds_read_b128 v[180:183], v169
	ds_read_b128 v[184:187], v170
	s_waitcnt lgkmcnt(4)
	v_mfma_f32_16x16x32_fp8_fp8 v[200:203], v[188:189], v[134:135], 0
	v_mfma_f32_16x16x32_fp8_fp8 v[200:203], v[190:191], v[136:137], v[200:203]
	v_mfma_f32_16x16x32_fp8_fp8 v[200:203], v[192:193], v[138:139], v[200:203]
	v_mfma_f32_16x16x32_fp8_fp8 v[200:203], v[194:195], v[140:141], v[200:203]
	v_cndmask_b32_e64 v226, v196, v198, s[54:55]
	v_cndmask_b32_e64 v227, v197, v199, s[54:55]
	s_waitcnt vmcnt(16)
	ds_write_b128 v168, v[26:29]
	ds_write_b128 v168, v[30:33] offset:1024
	v_lshl_add_u32 v176, v156, 10, v166
	global_load_dwordx4 v[26:29], v176, s[50:51]
	v_lshl_add_u32 v177, v157, 10, v167
	global_load_dwordx4 v[30:33], v177, s[50:51]
	ds_read_b128 v[188:191], v169
	ds_read_b128 v[192:195], v170
	s_waitcnt lgkmcnt(4)
	v_mfma_f32_16x16x32_fp8_fp8 v[204:207], v[180:181], v[134:135], 0
	v_mfma_f32_16x16x32_fp8_fp8 v[204:207], v[182:183], v[136:137], v[204:207]
	v_mfma_f32_16x16x32_fp8_fp8 v[204:207], v[184:185], v[138:139], v[204:207]
	v_mfma_f32_16x16x32_fp8_fp8 v[204:207], v[186:187], v[140:141], v[204:207]
	v_cndmask_b32_e64 v228, v200, v202, s[54:55]
	v_cndmask_b32_e64 v229, v201, v203, s[54:55]
	v_cndmask_b32_e64 v230, v226, v228, s[56:57]
	v_cndmask_b32_e64 v231, v227, v229, s[56:57]
	s_waitcnt vmcnt(16)
	ds_write_b128 v168, v[34:37]
	ds_write_b128 v168, v[38:41] offset:1024
	v_lshl_add_u32 v174, v158, 10, v166
	global_load_dwordx4 v[34:37], v174, s[50:51]
	v_lshl_add_u32 v175, v159, 10, v167
	global_load_dwordx4 v[38:41], v175, s[50:51]
	ds_read_b128 v[180:183], v169
	ds_read_b128 v[184:187], v170
	s_waitcnt lgkmcnt(4)
	v_mfma_f32_16x16x32_fp8_fp8 v[216:219], v[188:189], v[134:135], 0
	v_mfma_f32_16x16x32_fp8_fp8 v[216:219], v[190:191], v[136:137], v[216:219]
	v_mfma_f32_16x16x32_fp8_fp8 v[216:219], v[192:193], v[138:139], v[216:219]
	v_mfma_f32_16x16x32_fp8_fp8 v[216:219], v[194:195], v[140:141], v[216:219]
	v_cndmask_b32_e64 v226, v204, v206, s[54:55]
	v_cndmask_b32_e64 v227, v205, v207, s[54:55]
	s_waitcnt vmcnt(16)
	ds_write_b128 v168, v[42:45]
	ds_write_b128 v168, v[46:49] offset:1024
	v_lshl_add_u32 v176, v160, 10, v166
	global_load_dwordx4 v[42:45], v176, s[50:51]
	v_lshl_add_u32 v177, v161, 10, v167
	global_load_dwordx4 v[46:49], v177, s[50:51]
	ds_read_b128 v[188:191], v169
	ds_read_b128 v[192:195], v170
	s_waitcnt lgkmcnt(4)
	v_mfma_f32_16x16x32_fp8_fp8 v[196:199], v[180:181], v[134:135], 0
	v_mfma_f32_16x16x32_fp8_fp8 v[196:199], v[182:183], v[136:137], v[196:199]
	v_mfma_f32_16x16x32_fp8_fp8 v[196:199], v[184:185], v[138:139], v[196:199]
	v_mfma_f32_16x16x32_fp8_fp8 v[196:199], v[186:187], v[140:141], v[196:199]
	v_cndmask_b32_e64 v228, v216, v218, s[54:55]
	v_cndmask_b32_e64 v229, v217, v219, s[54:55]
	v_cndmask_b32_e64 v232, v226, v228, s[56:57]
	v_cndmask_b32_e64 v233, v227, v229, s[56:57]
	s_waitcnt vmcnt(16)
	ds_write_b128 v168, v[50:53]
	ds_write_b128 v168, v[54:57] offset:1024
	v_lshl_add_u32 v174, v162, 10, v166
	global_load_dwordx4 v[50:53], v174, s[50:51]
	v_lshl_add_u32 v175, v163, 10, v167
	global_load_dwordx4 v[54:57], v175, s[50:51]
	ds_read_b128 v[180:183], v169
	ds_read_b128 v[184:187], v170
	s_waitcnt lgkmcnt(4)
	v_mfma_f32_16x16x32_fp8_fp8 v[200:203], v[188:189], v[134:135], 0
	v_mfma_f32_16x16x32_fp8_fp8 v[200:203], v[190:191], v[136:137], v[200:203]
	v_mfma_f32_16x16x32_fp8_fp8 v[200:203], v[192:193], v[138:139], v[200:203]
	v_mfma_f32_16x16x32_fp8_fp8 v[200:203], v[194:195], v[140:141], v[200:203]
	v_cndmask_b32_e64 v226, v196, v198, s[54:55]
	v_cndmask_b32_e64 v227, v197, v199, s[54:55]
	s_waitcnt vmcnt(16)
	ds_write_b128 v168, v[58:61]
	ds_write_b128 v168, v[62:65] offset:1024
	v_lshl_add_u32 v176, v164, 10, v166
	global_load_dwordx4 v[58:61], v176, s[50:51]
	v_lshl_add_u32 v177, v165, 10, v167
	global_load_dwordx4 v[62:65], v177, s[50:51]
	ds_read_b128 v[188:191], v169
	ds_read_b128 v[192:195], v170
	s_waitcnt lgkmcnt(4)
	v_mfma_f32_16x16x32_fp8_fp8 v[204:207], v[180:181], v[134:135], 0
	v_mfma_f32_16x16x32_fp8_fp8 v[204:207], v[182:183], v[136:137], v[204:207]
	v_mfma_f32_16x16x32_fp8_fp8 v[204:207], v[184:185], v[138:139], v[204:207]
	v_mfma_f32_16x16x32_fp8_fp8 v[204:207], v[186:187], v[140:141], v[204:207]
	v_cndmask_b32_e64 v228, v200, v202, s[54:55]
	v_cndmask_b32_e64 v229, v201, v203, s[54:55]
	v_cndmask_b32_e64 v234, v226, v228, s[56:57]
	v_cndmask_b32_e64 v235, v227, v229, s[56:57]
	s_waitcnt lgkmcnt(0)
	v_mfma_f32_16x16x32_fp8_fp8 v[216:219], v[188:189], v[134:135], 0
	v_mfma_f32_16x16x32_fp8_fp8 v[216:219], v[190:191], v[136:137], v[216:219]
	v_mfma_f32_16x16x32_fp8_fp8 v[216:219], v[192:193], v[138:139], v[216:219]
	v_mfma_f32_16x16x32_fp8_fp8 v[216:219], v[194:195], v[140:141], v[216:219]
	v_add_u32_e32 v0, 1024, v172
	ds_read2_b32 v[150:151], v0 offset0:0 offset1:8
	ds_read2_b32 v[152:153], v0 offset0:16 offset1:24
	ds_read2_b32 v[154:155], v0 offset0:32 offset1:40
	ds_read2_b32 v[156:157], v0 offset0:48 offset1:56
	ds_read2_b32 v[158:159], v0 offset0:64 offset1:72
	ds_read2_b32 v[160:161], v0 offset0:80 offset1:88
	ds_read2_b32 v[162:163], v0 offset0:96 offset1:104
	ds_read2_b32 v[164:165], v0 offset0:112 offset1:120
	v_add_u32_e32 v171, s80, v171
	global_load_dwordx4 v[134:137], v171, s[52:53]
	global_load_dwordx4 v[138:141], v171, s[52:53] offset:16
	v_cndmask_b32_e64 v226, v204, v206, s[54:55]
	v_cndmask_b32_e64 v227, v205, v207, s[54:55]
	v_cndmask_b32_e64 v228, v216, v218, s[54:55]
	v_cndmask_b32_e64 v229, v217, v219, s[54:55]
	v_cndmask_b32_e64 v236, v226, v228, s[56:57]
	v_cndmask_b32_e64 v237, v227, v229, s[56:57]
	v_cndmask_b32_e64 v226, v230, v232, s[58:59]
	v_cndmask_b32_e64 v228, v234, v236, s[58:59]
	v_cndmask_b32_e64 v227, v231, v233, s[58:59]
	v_cndmask_b32_e64 v229, v235, v237, s[58:59]
	v_cndmask_b32_e64 v226, v226, v228, s[60:61]
	v_cndmask_b32_e64 v227, v227, v229, s[60:61]
	v_add_f32_e32 v242, v242, v226
	v_add_f32_e32 v243, v243, v227
	s_waitcnt vmcnt(16)
	ds_write_b128 v168, v[2:5]
	ds_write_b128 v168, v[6:9] offset:1024
	s_waitcnt lgkmcnt(2)
	v_lshl_add_u32 v174, v150, 10, v166
	global_load_dwordx4 v[2:5], v174, s[50:51]
	v_lshl_add_u32 v175, v151, 10, v167
	global_load_dwordx4 v[6:9], v175, s[50:51]
	ds_read_b128 v[180:183], v169
	ds_read_b128 v[184:187], v170
	s_waitcnt vmcnt(16)
	ds_write_b128 v168, v[10:13]
	ds_write_b128 v168, v[14:17] offset:1024
	v_lshl_add_u32 v176, v152, 10, v166
	global_load_dwordx4 v[10:13], v176, s[50:51]
	v_lshl_add_u32 v177, v153, 10, v167
	global_load_dwordx4 v[14:17], v177, s[50:51]
	ds_read_b128 v[188:191], v169
	ds_read_b128 v[192:195], v170
	s_waitcnt lgkmcnt(4)
	v_mfma_f32_16x16x32_fp8_fp8 v[196:199], v[180:181], v[142:143], 0
	v_mfma_f32_16x16x32_fp8_fp8 v[196:199], v[182:183], v[144:145], v[196:199]
	v_mfma_f32_16x16x32_fp8_fp8 v[196:199], v[184:185], v[146:147], v[196:199]
	v_mfma_f32_16x16x32_fp8_fp8 v[196:199], v[186:187], v[148:149], v[196:199]
	s_waitcnt vmcnt(16)
	ds_write_b128 v168, v[18:21]
	ds_write_b128 v168, v[22:25] offset:1024
	v_lshl_add_u32 v174, v154, 10, v166
	global_load_dwordx4 v[18:21], v174, s[50:51]
	v_lshl_add_u32 v175, v155, 10, v167
	global_load_dwordx4 v[22:25], v175, s[50:51]
	ds_read_b128 v[180:183], v169
	ds_read_b128 v[184:187], v170
	s_waitcnt lgkmcnt(4)
	v_mfma_f32_16x16x32_fp8_fp8 v[200:203], v[188:189], v[142:143], 0
	v_mfma_f32_16x16x32_fp8_fp8 v[200:203], v[190:191], v[144:145], v[200:203]
	v_mfma_f32_16x16x32_fp8_fp8 v[200:203], v[192:193], v[146:147], v[200:203]
	v_mfma_f32_16x16x32_fp8_fp8 v[200:203], v[194:195], v[148:149], v[200:203]
	v_cndmask_b32_e64 v226, v196, v198, s[54:55]
	v_cndmask_b32_e64 v227, v197, v199, s[54:55]
	s_waitcnt vmcnt(16)
	ds_write_b128 v168, v[26:29]
	ds_write_b128 v168, v[30:33] offset:1024
	v_lshl_add_u32 v176, v156, 10, v166
	global_load_dwordx4 v[26:29], v176, s[50:51]
	v_lshl_add_u32 v177, v157, 10, v167
	global_load_dwordx4 v[30:33], v177, s[50:51]
	ds_read_b128 v[188:191], v169
	ds_read_b128 v[192:195], v170
	s_waitcnt lgkmcnt(4)
	v_mfma_f32_16x16x32_fp8_fp8 v[204:207], v[180:181], v[142:143], 0
	v_mfma_f32_16x16x32_fp8_fp8 v[204:207], v[182:183], v[144:145], v[204:207]
	v_mfma_f32_16x16x32_fp8_fp8 v[204:207], v[184:185], v[146:147], v[204:207]
	v_mfma_f32_16x16x32_fp8_fp8 v[204:207], v[186:187], v[148:149], v[204:207]
	v_cndmask_b32_e64 v228, v200, v202, s[54:55]
	v_cndmask_b32_e64 v229, v201, v203, s[54:55]
	v_cndmask_b32_e64 v230, v226, v228, s[56:57]
	v_cndmask_b32_e64 v231, v227, v229, s[56:57]
	s_waitcnt vmcnt(16)
	ds_write_b128 v168, v[34:37]
	ds_write_b128 v168, v[38:41] offset:1024
	v_lshl_add_u32 v174, v158, 10, v166
	global_load_dwordx4 v[34:37], v174, s[50:51]
	v_lshl_add_u32 v175, v159, 10, v167
	global_load_dwordx4 v[38:41], v175, s[50:51]
	ds_read_b128 v[180:183], v169
	ds_read_b128 v[184:187], v170
	s_waitcnt lgkmcnt(4)
	v_mfma_f32_16x16x32_fp8_fp8 v[216:219], v[188:189], v[142:143], 0
	v_mfma_f32_16x16x32_fp8_fp8 v[216:219], v[190:191], v[144:145], v[216:219]
	v_mfma_f32_16x16x32_fp8_fp8 v[216:219], v[192:193], v[146:147], v[216:219]
	v_mfma_f32_16x16x32_fp8_fp8 v[216:219], v[194:195], v[148:149], v[216:219]
	v_cndmask_b32_e64 v226, v204, v206, s[54:55]
	v_cndmask_b32_e64 v227, v205, v207, s[54:55]
	s_waitcnt vmcnt(16)
	ds_write_b128 v168, v[42:45]
	ds_write_b128 v168, v[46:49] offset:1024
	v_lshl_add_u32 v176, v160, 10, v166
	global_load_dwordx4 v[42:45], v176, s[50:51]
	v_lshl_add_u32 v177, v161, 10, v167
	global_load_dwordx4 v[46:49], v177, s[50:51]
	ds_read_b128 v[188:191], v169
	ds_read_b128 v[192:195], v170
	s_waitcnt lgkmcnt(4)
	v_mfma_f32_16x16x32_fp8_fp8 v[196:199], v[180:181], v[142:143], 0
	v_mfma_f32_16x16x32_fp8_fp8 v[196:199], v[182:183], v[144:145], v[196:199]
	v_mfma_f32_16x16x32_fp8_fp8 v[196:199], v[184:185], v[146:147], v[196:199]
	v_mfma_f32_16x16x32_fp8_fp8 v[196:199], v[186:187], v[148:149], v[196:199]
	v_cndmask_b32_e64 v228, v216, v218, s[54:55]
	v_cndmask_b32_e64 v229, v217, v219, s[54:55]
	v_cndmask_b32_e64 v232, v226, v228, s[56:57]
	v_cndmask_b32_e64 v233, v227, v229, s[56:57]
	s_waitcnt vmcnt(16)
	ds_write_b128 v168, v[50:53]
	ds_write_b128 v168, v[54:57] offset:1024
	v_lshl_add_u32 v174, v162, 10, v166
	global_load_dwordx4 v[50:53], v174, s[50:51]
	v_lshl_add_u32 v175, v163, 10, v167
	global_load_dwordx4 v[54:57], v175, s[50:51]
	ds_read_b128 v[180:183], v169
	ds_read_b128 v[184:187], v170
	s_waitcnt lgkmcnt(4)
	v_mfma_f32_16x16x32_fp8_fp8 v[200:203], v[188:189], v[142:143], 0
	v_mfma_f32_16x16x32_fp8_fp8 v[200:203], v[190:191], v[144:145], v[200:203]
	v_mfma_f32_16x16x32_fp8_fp8 v[200:203], v[192:193], v[146:147], v[200:203]
	v_mfma_f32_16x16x32_fp8_fp8 v[200:203], v[194:195], v[148:149], v[200:203]
	v_cndmask_b32_e64 v226, v196, v198, s[54:55]
	v_cndmask_b32_e64 v227, v197, v199, s[54:55]
	s_waitcnt vmcnt(16)
	ds_write_b128 v168, v[58:61]
	ds_write_b128 v168, v[62:65] offset:1024
	v_lshl_add_u32 v176, v164, 10, v166
	global_load_dwordx4 v[58:61], v176, s[50:51]
	v_lshl_add_u32 v177, v165, 10, v167
	global_load_dwordx4 v[62:65], v177, s[50:51]
	ds_read_b128 v[188:191], v169
	ds_read_b128 v[192:195], v170
	s_waitcnt lgkmcnt(4)
	v_mfma_f32_16x16x32_fp8_fp8 v[204:207], v[180:181], v[142:143], 0
	v_mfma_f32_16x16x32_fp8_fp8 v[204:207], v[182:183], v[144:145], v[204:207]
	v_mfma_f32_16x16x32_fp8_fp8 v[204:207], v[184:185], v[146:147], v[204:207]
	v_mfma_f32_16x16x32_fp8_fp8 v[204:207], v[186:187], v[148:149], v[204:207]
	v_cndmask_b32_e64 v228, v200, v202, s[54:55]
	v_cndmask_b32_e64 v229, v201, v203, s[54:55]
	v_cndmask_b32_e64 v234, v226, v228, s[56:57]
	v_cndmask_b32_e64 v235, v227, v229, s[56:57]
	s_waitcnt lgkmcnt(0)
	v_mfma_f32_16x16x32_fp8_fp8 v[216:219], v[188:189], v[142:143], 0
	v_mfma_f32_16x16x32_fp8_fp8 v[216:219], v[190:191], v[144:145], v[216:219]
	v_mfma_f32_16x16x32_fp8_fp8 v[216:219], v[192:193], v[146:147], v[216:219]
	v_mfma_f32_16x16x32_fp8_fp8 v[216:219], v[194:195], v[148:149], v[216:219]
	v_add_u32_e32 v0, 1536, v172
	ds_read2_b32 v[150:151], v0 offset0:0 offset1:8
	ds_read2_b32 v[152:153], v0 offset0:16 offset1:24
	ds_read2_b32 v[154:155], v0 offset0:32 offset1:40
	ds_read2_b32 v[156:157], v0 offset0:48 offset1:56
	ds_read2_b32 v[158:159], v0 offset0:64 offset1:72
	ds_read2_b32 v[160:161], v0 offset0:80 offset1:88
	ds_read2_b32 v[162:163], v0 offset0:96 offset1:104
	ds_read2_b32 v[164:165], v0 offset0:112 offset1:120
	v_add_u32_e32 v171, s80, v171
	global_load_dwordx4 v[142:145], v171, s[52:53]
	global_load_dwordx4 v[146:149], v171, s[52:53] offset:16
	v_cndmask_b32_e64 v226, v204, v206, s[54:55]
	v_cndmask_b32_e64 v227, v205, v207, s[54:55]
	v_cndmask_b32_e64 v228, v216, v218, s[54:55]
	v_cndmask_b32_e64 v229, v217, v219, s[54:55]
	v_cndmask_b32_e64 v236, v226, v228, s[56:57]
	v_cndmask_b32_e64 v237, v227, v229, s[56:57]
	v_cndmask_b32_e64 v226, v230, v232, s[58:59]
	v_cndmask_b32_e64 v228, v234, v236, s[58:59]
	v_cndmask_b32_e64 v227, v231, v233, s[58:59]
	v_cndmask_b32_e64 v229, v235, v237, s[58:59]
	v_cndmask_b32_e64 v226, v226, v228, s[60:61]
	v_cndmask_b32_e64 v227, v227, v229, s[60:61]
	v_add_f32_e32 v244, v244, v226
	v_add_f32_e32 v245, v245, v227
	s_waitcnt vmcnt(16)
	ds_write_b128 v168, v[2:5]
	ds_write_b128 v168, v[6:9] offset:1024
	s_waitcnt lgkmcnt(2)
	v_lshl_add_u32 v174, v150, 10, v166
	global_load_dwordx4 v[2:5], v174, s[50:51]
	v_lshl_add_u32 v175, v151, 10, v167
	global_load_dwordx4 v[6:9], v175, s[50:51]
	ds_read_b128 v[180:183], v169
	ds_read_b128 v[184:187], v170
	s_waitcnt vmcnt(16)
	ds_write_b128 v168, v[10:13]
	ds_write_b128 v168, v[14:17] offset:1024
	v_lshl_add_u32 v176, v152, 10, v166
	global_load_dwordx4 v[10:13], v176, s[50:51]
	v_lshl_add_u32 v177, v153, 10, v167
	global_load_dwordx4 v[14:17], v177, s[50:51]
	ds_read_b128 v[188:191], v169
	ds_read_b128 v[192:195], v170
	s_waitcnt lgkmcnt(4)
	v_mfma_f32_16x16x32_fp8_fp8 v[196:199], v[180:181], v[134:135], 0
	v_mfma_f32_16x16x32_fp8_fp8 v[196:199], v[182:183], v[136:137], v[196:199]
	v_mfma_f32_16x16x32_fp8_fp8 v[196:199], v[184:185], v[138:139], v[196:199]
	v_mfma_f32_16x16x32_fp8_fp8 v[196:199], v[186:187], v[140:141], v[196:199]
	s_waitcnt vmcnt(16)
	ds_write_b128 v168, v[18:21]
	ds_write_b128 v168, v[22:25] offset:1024
	v_lshl_add_u32 v174, v154, 10, v166
	global_load_dwordx4 v[18:21], v174, s[50:51]
	v_lshl_add_u32 v175, v155, 10, v167
	global_load_dwordx4 v[22:25], v175, s[50:51]
	ds_read_b128 v[180:183], v169
	ds_read_b128 v[184:187], v170
	s_waitcnt lgkmcnt(4)
	v_mfma_f32_16x16x32_fp8_fp8 v[200:203], v[188:189], v[134:135], 0
	v_mfma_f32_16x16x32_fp8_fp8 v[200:203], v[190:191], v[136:137], v[200:203]
	v_mfma_f32_16x16x32_fp8_fp8 v[200:203], v[192:193], v[138:139], v[200:203]
	v_mfma_f32_16x16x32_fp8_fp8 v[200:203], v[194:195], v[140:141], v[200:203]
	v_cndmask_b32_e64 v226, v196, v198, s[54:55]
	v_cndmask_b32_e64 v227, v197, v199, s[54:55]
	s_waitcnt vmcnt(16)
	ds_write_b128 v168, v[26:29]
	ds_write_b128 v168, v[30:33] offset:1024
	v_lshl_add_u32 v176, v156, 10, v166
	global_load_dwordx4 v[26:29], v176, s[50:51]
	v_lshl_add_u32 v177, v157, 10, v167
	global_load_dwordx4 v[30:33], v177, s[50:51]
	ds_read_b128 v[188:191], v169
	ds_read_b128 v[192:195], v170
	s_waitcnt lgkmcnt(4)
	v_mfma_f32_16x16x32_fp8_fp8 v[204:207], v[180:181], v[134:135], 0
	v_mfma_f32_16x16x32_fp8_fp8 v[204:207], v[182:183], v[136:137], v[204:207]
	v_mfma_f32_16x16x32_fp8_fp8 v[204:207], v[184:185], v[138:139], v[204:207]
	v_mfma_f32_16x16x32_fp8_fp8 v[204:207], v[186:187], v[140:141], v[204:207]
	v_cndmask_b32_e64 v228, v200, v202, s[54:55]
	v_cndmask_b32_e64 v229, v201, v203, s[54:55]
	v_cndmask_b32_e64 v230, v226, v228, s[56:57]
	v_cndmask_b32_e64 v231, v227, v229, s[56:57]
	s_waitcnt vmcnt(16)
	ds_write_b128 v168, v[34:37]
	ds_write_b128 v168, v[38:41] offset:1024
	v_lshl_add_u32 v174, v158, 10, v166
	global_load_dwordx4 v[34:37], v174, s[50:51]
	v_lshl_add_u32 v175, v159, 10, v167
	global_load_dwordx4 v[38:41], v175, s[50:51]
	ds_read_b128 v[180:183], v169
	ds_read_b128 v[184:187], v170
	s_waitcnt lgkmcnt(4)
	v_mfma_f32_16x16x32_fp8_fp8 v[216:219], v[188:189], v[134:135], 0
	v_mfma_f32_16x16x32_fp8_fp8 v[216:219], v[190:191], v[136:137], v[216:219]
	v_mfma_f32_16x16x32_fp8_fp8 v[216:219], v[192:193], v[138:139], v[216:219]
	v_mfma_f32_16x16x32_fp8_fp8 v[216:219], v[194:195], v[140:141], v[216:219]
	v_cndmask_b32_e64 v226, v204, v206, s[54:55]
	v_cndmask_b32_e64 v227, v205, v207, s[54:55]
	s_waitcnt vmcnt(16)
	ds_write_b128 v168, v[42:45]
	ds_write_b128 v168, v[46:49] offset:1024
	v_lshl_add_u32 v176, v160, 10, v166
	global_load_dwordx4 v[42:45], v176, s[50:51]
	v_lshl_add_u32 v177, v161, 10, v167
	global_load_dwordx4 v[46:49], v177, s[50:51]
	ds_read_b128 v[188:191], v169
	ds_read_b128 v[192:195], v170
	s_waitcnt lgkmcnt(4)
	v_mfma_f32_16x16x32_fp8_fp8 v[196:199], v[180:181], v[134:135], 0
	v_mfma_f32_16x16x32_fp8_fp8 v[196:199], v[182:183], v[136:137], v[196:199]
	v_mfma_f32_16x16x32_fp8_fp8 v[196:199], v[184:185], v[138:139], v[196:199]
	v_mfma_f32_16x16x32_fp8_fp8 v[196:199], v[186:187], v[140:141], v[196:199]
	v_cndmask_b32_e64 v228, v216, v218, s[54:55]
	v_cndmask_b32_e64 v229, v217, v219, s[54:55]
	v_cndmask_b32_e64 v232, v226, v228, s[56:57]
	v_cndmask_b32_e64 v233, v227, v229, s[56:57]
	s_waitcnt vmcnt(16)
	ds_write_b128 v168, v[50:53]
	ds_write_b128 v168, v[54:57] offset:1024
	v_lshl_add_u32 v174, v162, 10, v166
	global_load_dwordx4 v[50:53], v174, s[50:51]
	v_lshl_add_u32 v175, v163, 10, v167
	global_load_dwordx4 v[54:57], v175, s[50:51]
	ds_read_b128 v[180:183], v169
	ds_read_b128 v[184:187], v170
	s_waitcnt lgkmcnt(4)
	v_mfma_f32_16x16x32_fp8_fp8 v[200:203], v[188:189], v[134:135], 0
	v_mfma_f32_16x16x32_fp8_fp8 v[200:203], v[190:191], v[136:137], v[200:203]
	v_mfma_f32_16x16x32_fp8_fp8 v[200:203], v[192:193], v[138:139], v[200:203]
	v_mfma_f32_16x16x32_fp8_fp8 v[200:203], v[194:195], v[140:141], v[200:203]
	v_cndmask_b32_e64 v226, v196, v198, s[54:55]
	v_cndmask_b32_e64 v227, v197, v199, s[54:55]
	s_waitcnt vmcnt(16)
	ds_write_b128 v168, v[58:61]
	ds_write_b128 v168, v[62:65] offset:1024
	v_lshl_add_u32 v176, v164, 10, v166
	global_load_dwordx4 v[58:61], v176, s[50:51]
	v_lshl_add_u32 v177, v165, 10, v167
	global_load_dwordx4 v[62:65], v177, s[50:51]
	ds_read_b128 v[188:191], v169
	ds_read_b128 v[192:195], v170
	s_waitcnt lgkmcnt(4)
	v_mfma_f32_16x16x32_fp8_fp8 v[204:207], v[180:181], v[134:135], 0
	v_mfma_f32_16x16x32_fp8_fp8 v[204:207], v[182:183], v[136:137], v[204:207]
	v_mfma_f32_16x16x32_fp8_fp8 v[204:207], v[184:185], v[138:139], v[204:207]
	v_mfma_f32_16x16x32_fp8_fp8 v[204:207], v[186:187], v[140:141], v[204:207]
	v_cndmask_b32_e64 v228, v200, v202, s[54:55]
	v_cndmask_b32_e64 v229, v201, v203, s[54:55]
	v_cndmask_b32_e64 v234, v226, v228, s[56:57]
	v_cndmask_b32_e64 v235, v227, v229, s[56:57]
	s_waitcnt lgkmcnt(0)
	v_mfma_f32_16x16x32_fp8_fp8 v[216:219], v[188:189], v[134:135], 0
	v_mfma_f32_16x16x32_fp8_fp8 v[216:219], v[190:191], v[136:137], v[216:219]
	v_mfma_f32_16x16x32_fp8_fp8 v[216:219], v[192:193], v[138:139], v[216:219]
	v_mfma_f32_16x16x32_fp8_fp8 v[216:219], v[194:195], v[140:141], v[216:219]
	v_add_u32_e32 v0, 2048, v172
	ds_read2_b32 v[150:151], v0 offset0:0 offset1:8
	ds_read2_b32 v[152:153], v0 offset0:16 offset1:24
	ds_read2_b32 v[154:155], v0 offset0:32 offset1:40
	ds_read2_b32 v[156:157], v0 offset0:48 offset1:56
	ds_read2_b32 v[158:159], v0 offset0:64 offset1:72
	ds_read2_b32 v[160:161], v0 offset0:80 offset1:88
	ds_read2_b32 v[162:163], v0 offset0:96 offset1:104
	ds_read2_b32 v[164:165], v0 offset0:112 offset1:120
	v_add_u32_e32 v171, s80, v171
	global_load_dwordx4 v[134:137], v171, s[52:53]
	global_load_dwordx4 v[138:141], v171, s[52:53] offset:16
	v_cndmask_b32_e64 v226, v204, v206, s[54:55]
	v_cndmask_b32_e64 v227, v205, v207, s[54:55]
	v_cndmask_b32_e64 v228, v216, v218, s[54:55]
	v_cndmask_b32_e64 v229, v217, v219, s[54:55]
	v_cndmask_b32_e64 v236, v226, v228, s[56:57]
	v_cndmask_b32_e64 v237, v227, v229, s[56:57]
	v_cndmask_b32_e64 v226, v230, v232, s[58:59]
	v_cndmask_b32_e64 v228, v234, v236, s[58:59]
	v_cndmask_b32_e64 v227, v231, v233, s[58:59]
	v_cndmask_b32_e64 v229, v235, v237, s[58:59]
	v_cndmask_b32_e64 v226, v226, v228, s[60:61]
	v_cndmask_b32_e64 v227, v227, v229, s[60:61]
	v_add_f32_e32 v246, v246, v226
	v_add_f32_e32 v247, v247, v227
	s_waitcnt vmcnt(16)
	ds_write_b128 v168, v[2:5]
	ds_write_b128 v168, v[6:9] offset:1024
	s_waitcnt lgkmcnt(2)
	v_lshl_add_u32 v174, v150, 10, v166
	global_load_dwordx4 v[2:5], v174, s[50:51]
	v_lshl_add_u32 v175, v151, 10, v167
	global_load_dwordx4 v[6:9], v175, s[50:51]
	ds_read_b128 v[180:183], v169
	ds_read_b128 v[184:187], v170
	s_waitcnt vmcnt(16)
	ds_write_b128 v168, v[10:13]
	ds_write_b128 v168, v[14:17] offset:1024
	v_lshl_add_u32 v176, v152, 10, v166
	global_load_dwordx4 v[10:13], v176, s[50:51]
	v_lshl_add_u32 v177, v153, 10, v167
	global_load_dwordx4 v[14:17], v177, s[50:51]
	ds_read_b128 v[188:191], v169
	ds_read_b128 v[192:195], v170
	s_waitcnt lgkmcnt(4)
	v_mfma_f32_16x16x32_fp8_fp8 v[196:199], v[180:181], v[142:143], 0
	v_mfma_f32_16x16x32_fp8_fp8 v[196:199], v[182:183], v[144:145], v[196:199]
	v_mfma_f32_16x16x32_fp8_fp8 v[196:199], v[184:185], v[146:147], v[196:199]
	v_mfma_f32_16x16x32_fp8_fp8 v[196:199], v[186:187], v[148:149], v[196:199]
	s_waitcnt vmcnt(16)
	ds_write_b128 v168, v[18:21]
	ds_write_b128 v168, v[22:25] offset:1024
	v_lshl_add_u32 v174, v154, 10, v166
	global_load_dwordx4 v[18:21], v174, s[50:51]
	v_lshl_add_u32 v175, v155, 10, v167
	global_load_dwordx4 v[22:25], v175, s[50:51]
	ds_read_b128 v[180:183], v169
	ds_read_b128 v[184:187], v170
	s_waitcnt lgkmcnt(4)
	v_mfma_f32_16x16x32_fp8_fp8 v[200:203], v[188:189], v[142:143], 0
	v_mfma_f32_16x16x32_fp8_fp8 v[200:203], v[190:191], v[144:145], v[200:203]
	v_mfma_f32_16x16x32_fp8_fp8 v[200:203], v[192:193], v[146:147], v[200:203]
	v_mfma_f32_16x16x32_fp8_fp8 v[200:203], v[194:195], v[148:149], v[200:203]
	v_cndmask_b32_e64 v226, v196, v198, s[54:55]
	v_cndmask_b32_e64 v227, v197, v199, s[54:55]
	s_waitcnt vmcnt(16)
	ds_write_b128 v168, v[26:29]
	ds_write_b128 v168, v[30:33] offset:1024
	v_lshl_add_u32 v176, v156, 10, v166
	global_load_dwordx4 v[26:29], v176, s[50:51]
	v_lshl_add_u32 v177, v157, 10, v167
	global_load_dwordx4 v[30:33], v177, s[50:51]
	ds_read_b128 v[188:191], v169
	ds_read_b128 v[192:195], v170
	s_waitcnt lgkmcnt(4)
	v_mfma_f32_16x16x32_fp8_fp8 v[204:207], v[180:181], v[142:143], 0
	v_mfma_f32_16x16x32_fp8_fp8 v[204:207], v[182:183], v[144:145], v[204:207]
	v_mfma_f32_16x16x32_fp8_fp8 v[204:207], v[184:185], v[146:147], v[204:207]
	v_mfma_f32_16x16x32_fp8_fp8 v[204:207], v[186:187], v[148:149], v[204:207]
	v_cndmask_b32_e64 v228, v200, v202, s[54:55]
	v_cndmask_b32_e64 v229, v201, v203, s[54:55]
	v_cndmask_b32_e64 v230, v226, v228, s[56:57]
	v_cndmask_b32_e64 v231, v227, v229, s[56:57]
	s_waitcnt vmcnt(16)
	ds_write_b128 v168, v[34:37]
	ds_write_b128 v168, v[38:41] offset:1024
	v_lshl_add_u32 v174, v158, 10, v166
	global_load_dwordx4 v[34:37], v174, s[50:51]
	v_lshl_add_u32 v175, v159, 10, v167
	global_load_dwordx4 v[38:41], v175, s[50:51]
	ds_read_b128 v[180:183], v169
	ds_read_b128 v[184:187], v170
	s_waitcnt lgkmcnt(4)
	v_mfma_f32_16x16x32_fp8_fp8 v[216:219], v[188:189], v[142:143], 0
	v_mfma_f32_16x16x32_fp8_fp8 v[216:219], v[190:191], v[144:145], v[216:219]
	v_mfma_f32_16x16x32_fp8_fp8 v[216:219], v[192:193], v[146:147], v[216:219]
	v_mfma_f32_16x16x32_fp8_fp8 v[216:219], v[194:195], v[148:149], v[216:219]
	v_cndmask_b32_e64 v226, v204, v206, s[54:55]
	v_cndmask_b32_e64 v227, v205, v207, s[54:55]
	s_waitcnt vmcnt(16)
	ds_write_b128 v168, v[42:45]
	ds_write_b128 v168, v[46:49] offset:1024
	v_lshl_add_u32 v176, v160, 10, v166
	global_load_dwordx4 v[42:45], v176, s[50:51]
	v_lshl_add_u32 v177, v161, 10, v167
	global_load_dwordx4 v[46:49], v177, s[50:51]
	ds_read_b128 v[188:191], v169
	ds_read_b128 v[192:195], v170
	s_waitcnt lgkmcnt(4)
	v_mfma_f32_16x16x32_fp8_fp8 v[196:199], v[180:181], v[142:143], 0
	v_mfma_f32_16x16x32_fp8_fp8 v[196:199], v[182:183], v[144:145], v[196:199]
	v_mfma_f32_16x16x32_fp8_fp8 v[196:199], v[184:185], v[146:147], v[196:199]
	v_mfma_f32_16x16x32_fp8_fp8 v[196:199], v[186:187], v[148:149], v[196:199]
	v_cndmask_b32_e64 v228, v216, v218, s[54:55]
	v_cndmask_b32_e64 v229, v217, v219, s[54:55]
	v_cndmask_b32_e64 v232, v226, v228, s[56:57]
	v_cndmask_b32_e64 v233, v227, v229, s[56:57]
	s_waitcnt vmcnt(16)
	ds_write_b128 v168, v[50:53]
	ds_write_b128 v168, v[54:57] offset:1024
	v_lshl_add_u32 v174, v162, 10, v166
	global_load_dwordx4 v[50:53], v174, s[50:51]
	v_lshl_add_u32 v175, v163, 10, v167
	global_load_dwordx4 v[54:57], v175, s[50:51]
	ds_read_b128 v[180:183], v169
	ds_read_b128 v[184:187], v170
	s_waitcnt lgkmcnt(4)
	v_mfma_f32_16x16x32_fp8_fp8 v[200:203], v[188:189], v[142:143], 0
	v_mfma_f32_16x16x32_fp8_fp8 v[200:203], v[190:191], v[144:145], v[200:203]
	v_mfma_f32_16x16x32_fp8_fp8 v[200:203], v[192:193], v[146:147], v[200:203]
	v_mfma_f32_16x16x32_fp8_fp8 v[200:203], v[194:195], v[148:149], v[200:203]
	v_cndmask_b32_e64 v226, v196, v198, s[54:55]
	v_cndmask_b32_e64 v227, v197, v199, s[54:55]
	s_waitcnt vmcnt(16)
	ds_write_b128 v168, v[58:61]
	ds_write_b128 v168, v[62:65] offset:1024
	v_lshl_add_u32 v176, v164, 10, v166
	global_load_dwordx4 v[58:61], v176, s[50:51]
	v_lshl_add_u32 v177, v165, 10, v167
	global_load_dwordx4 v[62:65], v177, s[50:51]
	ds_read_b128 v[188:191], v169
	ds_read_b128 v[192:195], v170
	s_waitcnt lgkmcnt(4)
	v_mfma_f32_16x16x32_fp8_fp8 v[204:207], v[180:181], v[142:143], 0
	v_mfma_f32_16x16x32_fp8_fp8 v[204:207], v[182:183], v[144:145], v[204:207]
	v_mfma_f32_16x16x32_fp8_fp8 v[204:207], v[184:185], v[146:147], v[204:207]
	v_mfma_f32_16x16x32_fp8_fp8 v[204:207], v[186:187], v[148:149], v[204:207]
	v_cndmask_b32_e64 v228, v200, v202, s[54:55]
	v_cndmask_b32_e64 v229, v201, v203, s[54:55]
	v_cndmask_b32_e64 v234, v226, v228, s[56:57]
	v_cndmask_b32_e64 v235, v227, v229, s[56:57]
	s_waitcnt lgkmcnt(0)
	v_mfma_f32_16x16x32_fp8_fp8 v[216:219], v[188:189], v[142:143], 0
	v_mfma_f32_16x16x32_fp8_fp8 v[216:219], v[190:191], v[144:145], v[216:219]
	v_mfma_f32_16x16x32_fp8_fp8 v[216:219], v[192:193], v[146:147], v[216:219]
	v_mfma_f32_16x16x32_fp8_fp8 v[216:219], v[194:195], v[148:149], v[216:219]
	v_add_u32_e32 v0, 2560, v172
	ds_read2_b32 v[150:151], v0 offset0:0 offset1:8
	ds_read2_b32 v[152:153], v0 offset0:16 offset1:24
	ds_read2_b32 v[154:155], v0 offset0:32 offset1:40
	ds_read2_b32 v[156:157], v0 offset0:48 offset1:56
	ds_read2_b32 v[158:159], v0 offset0:64 offset1:72
	ds_read2_b32 v[160:161], v0 offset0:80 offset1:88
	ds_read2_b32 v[162:163], v0 offset0:96 offset1:104
	ds_read2_b32 v[164:165], v0 offset0:112 offset1:120
	v_add_u32_e32 v171, s80, v171
	global_load_dwordx4 v[142:145], v171, s[52:53]
	global_load_dwordx4 v[146:149], v171, s[52:53] offset:16
	v_cndmask_b32_e64 v226, v204, v206, s[54:55]
	v_cndmask_b32_e64 v227, v205, v207, s[54:55]
	v_cndmask_b32_e64 v228, v216, v218, s[54:55]
	v_cndmask_b32_e64 v229, v217, v219, s[54:55]
	v_cndmask_b32_e64 v236, v226, v228, s[56:57]
	v_cndmask_b32_e64 v237, v227, v229, s[56:57]
	v_cndmask_b32_e64 v226, v230, v232, s[58:59]
	v_cndmask_b32_e64 v228, v234, v236, s[58:59]
	v_cndmask_b32_e64 v227, v231, v233, s[58:59]
	v_cndmask_b32_e64 v229, v235, v237, s[58:59]
	v_cndmask_b32_e64 v226, v226, v228, s[60:61]
	v_cndmask_b32_e64 v227, v227, v229, s[60:61]
	v_add_f32_e32 v248, v248, v226
	v_add_f32_e32 v249, v249, v227
	s_waitcnt vmcnt(16)
	ds_write_b128 v168, v[2:5]
	ds_write_b128 v168, v[6:9] offset:1024
	s_waitcnt lgkmcnt(2)
	v_lshl_add_u32 v174, v150, 10, v166
	global_load_dwordx4 v[2:5], v174, s[50:51]
	v_lshl_add_u32 v175, v151, 10, v167
	global_load_dwordx4 v[6:9], v175, s[50:51]
	ds_read_b128 v[180:183], v169
	ds_read_b128 v[184:187], v170
	s_waitcnt vmcnt(16)
	ds_write_b128 v168, v[10:13]
	ds_write_b128 v168, v[14:17] offset:1024
	v_lshl_add_u32 v176, v152, 10, v166
	global_load_dwordx4 v[10:13], v176, s[50:51]
	v_lshl_add_u32 v177, v153, 10, v167
	global_load_dwordx4 v[14:17], v177, s[50:51]
	ds_read_b128 v[188:191], v169
	ds_read_b128 v[192:195], v170
	s_waitcnt lgkmcnt(4)
	v_mfma_f32_16x16x32_fp8_fp8 v[196:199], v[180:181], v[134:135], 0
	v_mfma_f32_16x16x32_fp8_fp8 v[196:199], v[182:183], v[136:137], v[196:199]
	v_mfma_f32_16x16x32_fp8_fp8 v[196:199], v[184:185], v[138:139], v[196:199]
	v_mfma_f32_16x16x32_fp8_fp8 v[196:199], v[186:187], v[140:141], v[196:199]
	s_waitcnt vmcnt(16)
	ds_write_b128 v168, v[18:21]
	ds_write_b128 v168, v[22:25] offset:1024
	v_lshl_add_u32 v174, v154, 10, v166
	global_load_dwordx4 v[18:21], v174, s[50:51]
	v_lshl_add_u32 v175, v155, 10, v167
	global_load_dwordx4 v[22:25], v175, s[50:51]
	ds_read_b128 v[180:183], v169
	ds_read_b128 v[184:187], v170
	s_waitcnt lgkmcnt(4)
	v_mfma_f32_16x16x32_fp8_fp8 v[200:203], v[188:189], v[134:135], 0
	v_mfma_f32_16x16x32_fp8_fp8 v[200:203], v[190:191], v[136:137], v[200:203]
	v_mfma_f32_16x16x32_fp8_fp8 v[200:203], v[192:193], v[138:139], v[200:203]
	v_mfma_f32_16x16x32_fp8_fp8 v[200:203], v[194:195], v[140:141], v[200:203]
	v_cndmask_b32_e64 v226, v196, v198, s[54:55]
	v_cndmask_b32_e64 v227, v197, v199, s[54:55]
	s_waitcnt vmcnt(16)
	ds_write_b128 v168, v[26:29]
	ds_write_b128 v168, v[30:33] offset:1024
	v_lshl_add_u32 v176, v156, 10, v166
	global_load_dwordx4 v[26:29], v176, s[50:51]
	v_lshl_add_u32 v177, v157, 10, v167
	global_load_dwordx4 v[30:33], v177, s[50:51]
	ds_read_b128 v[188:191], v169
	ds_read_b128 v[192:195], v170
	s_waitcnt lgkmcnt(4)
	v_mfma_f32_16x16x32_fp8_fp8 v[204:207], v[180:181], v[134:135], 0
	v_mfma_f32_16x16x32_fp8_fp8 v[204:207], v[182:183], v[136:137], v[204:207]
	v_mfma_f32_16x16x32_fp8_fp8 v[204:207], v[184:185], v[138:139], v[204:207]
	v_mfma_f32_16x16x32_fp8_fp8 v[204:207], v[186:187], v[140:141], v[204:207]
	v_cndmask_b32_e64 v228, v200, v202, s[54:55]
	v_cndmask_b32_e64 v229, v201, v203, s[54:55]
	v_cndmask_b32_e64 v230, v226, v228, s[56:57]
	v_cndmask_b32_e64 v231, v227, v229, s[56:57]
	s_waitcnt vmcnt(16)
	ds_write_b128 v168, v[34:37]
	ds_write_b128 v168, v[38:41] offset:1024
	v_lshl_add_u32 v174, v158, 10, v166
	global_load_dwordx4 v[34:37], v174, s[50:51]
	v_lshl_add_u32 v175, v159, 10, v167
	global_load_dwordx4 v[38:41], v175, s[50:51]
	ds_read_b128 v[180:183], v169
	ds_read_b128 v[184:187], v170
	s_waitcnt lgkmcnt(4)
	v_mfma_f32_16x16x32_fp8_fp8 v[216:219], v[188:189], v[134:135], 0
	v_mfma_f32_16x16x32_fp8_fp8 v[216:219], v[190:191], v[136:137], v[216:219]
	v_mfma_f32_16x16x32_fp8_fp8 v[216:219], v[192:193], v[138:139], v[216:219]
	v_mfma_f32_16x16x32_fp8_fp8 v[216:219], v[194:195], v[140:141], v[216:219]
	v_cndmask_b32_e64 v226, v204, v206, s[54:55]
	v_cndmask_b32_e64 v227, v205, v207, s[54:55]
	s_waitcnt vmcnt(16)
	ds_write_b128 v168, v[42:45]
	ds_write_b128 v168, v[46:49] offset:1024
	v_lshl_add_u32 v176, v160, 10, v166
	global_load_dwordx4 v[42:45], v176, s[50:51]
	v_lshl_add_u32 v177, v161, 10, v167
	global_load_dwordx4 v[46:49], v177, s[50:51]
	ds_read_b128 v[188:191], v169
	ds_read_b128 v[192:195], v170
	s_waitcnt lgkmcnt(4)
	v_mfma_f32_16x16x32_fp8_fp8 v[196:199], v[180:181], v[134:135], 0
	v_mfma_f32_16x16x32_fp8_fp8 v[196:199], v[182:183], v[136:137], v[196:199]
	v_mfma_f32_16x16x32_fp8_fp8 v[196:199], v[184:185], v[138:139], v[196:199]
	v_mfma_f32_16x16x32_fp8_fp8 v[196:199], v[186:187], v[140:141], v[196:199]
	v_cndmask_b32_e64 v228, v216, v218, s[54:55]
	v_cndmask_b32_e64 v229, v217, v219, s[54:55]
	v_cndmask_b32_e64 v232, v226, v228, s[56:57]
	v_cndmask_b32_e64 v233, v227, v229, s[56:57]
	s_waitcnt vmcnt(16)
	ds_write_b128 v168, v[50:53]
	ds_write_b128 v168, v[54:57] offset:1024
	v_lshl_add_u32 v174, v162, 10, v166
	global_load_dwordx4 v[50:53], v174, s[50:51]
	v_lshl_add_u32 v175, v163, 10, v167
	global_load_dwordx4 v[54:57], v175, s[50:51]
	ds_read_b128 v[180:183], v169
	ds_read_b128 v[184:187], v170
	s_waitcnt lgkmcnt(4)
	v_mfma_f32_16x16x32_fp8_fp8 v[200:203], v[188:189], v[134:135], 0
	v_mfma_f32_16x16x32_fp8_fp8 v[200:203], v[190:191], v[136:137], v[200:203]
	v_mfma_f32_16x16x32_fp8_fp8 v[200:203], v[192:193], v[138:139], v[200:203]
	v_mfma_f32_16x16x32_fp8_fp8 v[200:203], v[194:195], v[140:141], v[200:203]
	v_cndmask_b32_e64 v226, v196, v198, s[54:55]
	v_cndmask_b32_e64 v227, v197, v199, s[54:55]
	s_waitcnt vmcnt(16)
	ds_write_b128 v168, v[58:61]
	ds_write_b128 v168, v[62:65] offset:1024
	v_lshl_add_u32 v176, v164, 10, v166
	global_load_dwordx4 v[58:61], v176, s[50:51]
	v_lshl_add_u32 v177, v165, 10, v167
	global_load_dwordx4 v[62:65], v177, s[50:51]
	ds_read_b128 v[188:191], v169
	ds_read_b128 v[192:195], v170
	s_waitcnt lgkmcnt(4)
	v_mfma_f32_16x16x32_fp8_fp8 v[204:207], v[180:181], v[134:135], 0
	v_mfma_f32_16x16x32_fp8_fp8 v[204:207], v[182:183], v[136:137], v[204:207]
	v_mfma_f32_16x16x32_fp8_fp8 v[204:207], v[184:185], v[138:139], v[204:207]
	v_mfma_f32_16x16x32_fp8_fp8 v[204:207], v[186:187], v[140:141], v[204:207]
	v_cndmask_b32_e64 v228, v200, v202, s[54:55]
	v_cndmask_b32_e64 v229, v201, v203, s[54:55]
	v_cndmask_b32_e64 v234, v226, v228, s[56:57]
	v_cndmask_b32_e64 v235, v227, v229, s[56:57]
	s_waitcnt lgkmcnt(0)
	v_mfma_f32_16x16x32_fp8_fp8 v[216:219], v[188:189], v[134:135], 0
	v_mfma_f32_16x16x32_fp8_fp8 v[216:219], v[190:191], v[136:137], v[216:219]
	v_mfma_f32_16x16x32_fp8_fp8 v[216:219], v[192:193], v[138:139], v[216:219]
	v_mfma_f32_16x16x32_fp8_fp8 v[216:219], v[194:195], v[140:141], v[216:219]
	v_add_u32_e32 v0, 3072, v172
	ds_read2_b32 v[150:151], v0 offset0:0 offset1:8
	ds_read2_b32 v[152:153], v0 offset0:16 offset1:24
	ds_read2_b32 v[154:155], v0 offset0:32 offset1:40
	ds_read2_b32 v[156:157], v0 offset0:48 offset1:56
	ds_read2_b32 v[158:159], v0 offset0:64 offset1:72
	ds_read2_b32 v[160:161], v0 offset0:80 offset1:88
	ds_read2_b32 v[162:163], v0 offset0:96 offset1:104
	ds_read2_b32 v[164:165], v0 offset0:112 offset1:120
	v_add_u32_e32 v171, s80, v171
	global_load_dwordx4 v[134:137], v171, s[52:53]
	global_load_dwordx4 v[138:141], v171, s[52:53] offset:16
	v_cndmask_b32_e64 v226, v204, v206, s[54:55]
	v_cndmask_b32_e64 v227, v205, v207, s[54:55]
	v_cndmask_b32_e64 v228, v216, v218, s[54:55]
	v_cndmask_b32_e64 v229, v217, v219, s[54:55]
	v_cndmask_b32_e64 v236, v226, v228, s[56:57]
	v_cndmask_b32_e64 v237, v227, v229, s[56:57]
	v_cndmask_b32_e64 v226, v230, v232, s[58:59]
	v_cndmask_b32_e64 v228, v234, v236, s[58:59]
	v_cndmask_b32_e64 v227, v231, v233, s[58:59]
	v_cndmask_b32_e64 v229, v235, v237, s[58:59]
	v_cndmask_b32_e64 v226, v226, v228, s[60:61]
	v_cndmask_b32_e64 v227, v227, v229, s[60:61]
	v_add_f32_e32 v238, v238, v226
	v_add_f32_e32 v239, v239, v227
	s_waitcnt vmcnt(16)
	ds_write_b128 v168, v[2:5]
	ds_write_b128 v168, v[6:9] offset:1024
	s_waitcnt lgkmcnt(2)
	v_lshl_add_u32 v174, v150, 10, v166
	global_load_dwordx4 v[2:5], v174, s[50:51]
	v_lshl_add_u32 v175, v151, 10, v167
	global_load_dwordx4 v[6:9], v175, s[50:51]
	ds_read_b128 v[180:183], v169
	ds_read_b128 v[184:187], v170
	s_waitcnt vmcnt(16)
	ds_write_b128 v168, v[10:13]
	ds_write_b128 v168, v[14:17] offset:1024
	v_lshl_add_u32 v176, v152, 10, v166
	global_load_dwordx4 v[10:13], v176, s[50:51]
	v_lshl_add_u32 v177, v153, 10, v167
	global_load_dwordx4 v[14:17], v177, s[50:51]
	ds_read_b128 v[188:191], v169
	ds_read_b128 v[192:195], v170
	s_waitcnt lgkmcnt(4)
	v_mfma_f32_16x16x32_fp8_fp8 v[196:199], v[180:181], v[142:143], 0
	v_mfma_f32_16x16x32_fp8_fp8 v[196:199], v[182:183], v[144:145], v[196:199]
	v_mfma_f32_16x16x32_fp8_fp8 v[196:199], v[184:185], v[146:147], v[196:199]
	v_mfma_f32_16x16x32_fp8_fp8 v[196:199], v[186:187], v[148:149], v[196:199]
	s_waitcnt vmcnt(16)
	ds_write_b128 v168, v[18:21]
	ds_write_b128 v168, v[22:25] offset:1024
	v_lshl_add_u32 v174, v154, 10, v166
	global_load_dwordx4 v[18:21], v174, s[50:51]
	v_lshl_add_u32 v175, v155, 10, v167
	global_load_dwordx4 v[22:25], v175, s[50:51]
	ds_read_b128 v[180:183], v169
	ds_read_b128 v[184:187], v170
	s_waitcnt lgkmcnt(4)
	v_mfma_f32_16x16x32_fp8_fp8 v[200:203], v[188:189], v[142:143], 0
	v_mfma_f32_16x16x32_fp8_fp8 v[200:203], v[190:191], v[144:145], v[200:203]
	v_mfma_f32_16x16x32_fp8_fp8 v[200:203], v[192:193], v[146:147], v[200:203]
	v_mfma_f32_16x16x32_fp8_fp8 v[200:203], v[194:195], v[148:149], v[200:203]
	v_cndmask_b32_e64 v226, v196, v198, s[54:55]
	v_cndmask_b32_e64 v227, v197, v199, s[54:55]
	s_waitcnt vmcnt(16)
	ds_write_b128 v168, v[26:29]
	ds_write_b128 v168, v[30:33] offset:1024
	v_lshl_add_u32 v176, v156, 10, v166
	global_load_dwordx4 v[26:29], v176, s[50:51]
	v_lshl_add_u32 v177, v157, 10, v167
	global_load_dwordx4 v[30:33], v177, s[50:51]
	ds_read_b128 v[188:191], v169
	ds_read_b128 v[192:195], v170
	s_waitcnt lgkmcnt(4)
	v_mfma_f32_16x16x32_fp8_fp8 v[204:207], v[180:181], v[142:143], 0
	v_mfma_f32_16x16x32_fp8_fp8 v[204:207], v[182:183], v[144:145], v[204:207]
	v_mfma_f32_16x16x32_fp8_fp8 v[204:207], v[184:185], v[146:147], v[204:207]
	v_mfma_f32_16x16x32_fp8_fp8 v[204:207], v[186:187], v[148:149], v[204:207]
	v_cndmask_b32_e64 v228, v200, v202, s[54:55]
	v_cndmask_b32_e64 v229, v201, v203, s[54:55]
	v_cndmask_b32_e64 v230, v226, v228, s[56:57]
	v_cndmask_b32_e64 v231, v227, v229, s[56:57]
	s_waitcnt vmcnt(16)
	ds_write_b128 v168, v[34:37]
	ds_write_b128 v168, v[38:41] offset:1024
	v_lshl_add_u32 v174, v158, 10, v166
	global_load_dwordx4 v[34:37], v174, s[50:51]
	v_lshl_add_u32 v175, v159, 10, v167
	global_load_dwordx4 v[38:41], v175, s[50:51]
	ds_read_b128 v[180:183], v169
	ds_read_b128 v[184:187], v170
	s_waitcnt lgkmcnt(4)
	v_mfma_f32_16x16x32_fp8_fp8 v[216:219], v[188:189], v[142:143], 0
	v_mfma_f32_16x16x32_fp8_fp8 v[216:219], v[190:191], v[144:145], v[216:219]
	v_mfma_f32_16x16x32_fp8_fp8 v[216:219], v[192:193], v[146:147], v[216:219]
	v_mfma_f32_16x16x32_fp8_fp8 v[216:219], v[194:195], v[148:149], v[216:219]
	v_cndmask_b32_e64 v226, v204, v206, s[54:55]
	v_cndmask_b32_e64 v227, v205, v207, s[54:55]
	s_waitcnt vmcnt(16)
	ds_write_b128 v168, v[42:45]
	ds_write_b128 v168, v[46:49] offset:1024
	v_lshl_add_u32 v176, v160, 10, v166
	global_load_dwordx4 v[42:45], v176, s[50:51]
	v_lshl_add_u32 v177, v161, 10, v167
	global_load_dwordx4 v[46:49], v177, s[50:51]
	ds_read_b128 v[188:191], v169
	ds_read_b128 v[192:195], v170
	s_waitcnt lgkmcnt(4)
	v_mfma_f32_16x16x32_fp8_fp8 v[196:199], v[180:181], v[142:143], 0
	v_mfma_f32_16x16x32_fp8_fp8 v[196:199], v[182:183], v[144:145], v[196:199]
	v_mfma_f32_16x16x32_fp8_fp8 v[196:199], v[184:185], v[146:147], v[196:199]
	v_mfma_f32_16x16x32_fp8_fp8 v[196:199], v[186:187], v[148:149], v[196:199]
	v_cndmask_b32_e64 v228, v216, v218, s[54:55]
	v_cndmask_b32_e64 v229, v217, v219, s[54:55]
	v_cndmask_b32_e64 v232, v226, v228, s[56:57]
	v_cndmask_b32_e64 v233, v227, v229, s[56:57]
	s_waitcnt vmcnt(16)
	ds_write_b128 v168, v[50:53]
	ds_write_b128 v168, v[54:57] offset:1024
	v_lshl_add_u32 v174, v162, 10, v166
	global_load_dwordx4 v[50:53], v174, s[50:51]
	v_lshl_add_u32 v175, v163, 10, v167
	global_load_dwordx4 v[54:57], v175, s[50:51]
	ds_read_b128 v[180:183], v169
	ds_read_b128 v[184:187], v170
	s_waitcnt lgkmcnt(4)
	v_mfma_f32_16x16x32_fp8_fp8 v[200:203], v[188:189], v[142:143], 0
	v_mfma_f32_16x16x32_fp8_fp8 v[200:203], v[190:191], v[144:145], v[200:203]
	v_mfma_f32_16x16x32_fp8_fp8 v[200:203], v[192:193], v[146:147], v[200:203]
	v_mfma_f32_16x16x32_fp8_fp8 v[200:203], v[194:195], v[148:149], v[200:203]
	v_cndmask_b32_e64 v226, v196, v198, s[54:55]
	v_cndmask_b32_e64 v227, v197, v199, s[54:55]
	s_waitcnt vmcnt(16)
	ds_write_b128 v168, v[58:61]
	ds_write_b128 v168, v[62:65] offset:1024
	v_lshl_add_u32 v176, v164, 10, v166
	global_load_dwordx4 v[58:61], v176, s[50:51]
	v_lshl_add_u32 v177, v165, 10, v167
	global_load_dwordx4 v[62:65], v177, s[50:51]
	ds_read_b128 v[188:191], v169
	ds_read_b128 v[192:195], v170
	s_waitcnt lgkmcnt(4)
	v_mfma_f32_16x16x32_fp8_fp8 v[204:207], v[180:181], v[142:143], 0
	v_mfma_f32_16x16x32_fp8_fp8 v[204:207], v[182:183], v[144:145], v[204:207]
	v_mfma_f32_16x16x32_fp8_fp8 v[204:207], v[184:185], v[146:147], v[204:207]
	v_mfma_f32_16x16x32_fp8_fp8 v[204:207], v[186:187], v[148:149], v[204:207]
	v_cndmask_b32_e64 v228, v200, v202, s[54:55]
	v_cndmask_b32_e64 v229, v201, v203, s[54:55]
	v_cndmask_b32_e64 v234, v226, v228, s[56:57]
	v_cndmask_b32_e64 v235, v227, v229, s[56:57]
	s_waitcnt lgkmcnt(0)
	v_mfma_f32_16x16x32_fp8_fp8 v[216:219], v[188:189], v[142:143], 0
	v_mfma_f32_16x16x32_fp8_fp8 v[216:219], v[190:191], v[144:145], v[216:219]
	v_mfma_f32_16x16x32_fp8_fp8 v[216:219], v[192:193], v[146:147], v[216:219]
	v_mfma_f32_16x16x32_fp8_fp8 v[216:219], v[194:195], v[148:149], v[216:219]
	v_add_u32_e32 v0, 3584, v172
	ds_read2_b32 v[150:151], v0 offset0:0 offset1:8
	ds_read2_b32 v[152:153], v0 offset0:16 offset1:24
	ds_read2_b32 v[154:155], v0 offset0:32 offset1:40
	ds_read2_b32 v[156:157], v0 offset0:48 offset1:56
	ds_read2_b32 v[158:159], v0 offset0:64 offset1:72
	ds_read2_b32 v[160:161], v0 offset0:80 offset1:88
	ds_read2_b32 v[162:163], v0 offset0:96 offset1:104
	ds_read2_b32 v[164:165], v0 offset0:112 offset1:120
	v_add_u32_e32 v171, s80, v171
	global_load_dwordx4 v[142:145], v171, s[52:53]
	global_load_dwordx4 v[146:149], v171, s[52:53] offset:16
	v_cndmask_b32_e64 v226, v204, v206, s[54:55]
	v_cndmask_b32_e64 v227, v205, v207, s[54:55]
	v_cndmask_b32_e64 v228, v216, v218, s[54:55]
	v_cndmask_b32_e64 v229, v217, v219, s[54:55]
	v_cndmask_b32_e64 v236, v226, v228, s[56:57]
	v_cndmask_b32_e64 v237, v227, v229, s[56:57]
	v_cndmask_b32_e64 v226, v230, v232, s[58:59]
	v_cndmask_b32_e64 v228, v234, v236, s[58:59]
	v_cndmask_b32_e64 v227, v231, v233, s[58:59]
	v_cndmask_b32_e64 v229, v235, v237, s[58:59]
	v_cndmask_b32_e64 v226, v226, v228, s[60:61]
	v_cndmask_b32_e64 v227, v227, v229, s[60:61]
	v_add_f32_e32 v240, v240, v226
	v_add_f32_e32 v241, v241, v227
	s_waitcnt vmcnt(16)
	ds_write_b128 v168, v[2:5]
	ds_write_b128 v168, v[6:9] offset:1024
	s_waitcnt lgkmcnt(2)
	v_lshl_add_u32 v174, v150, 10, v166
	global_load_dwordx4 v[2:5], v174, s[50:51]
	v_lshl_add_u32 v175, v151, 10, v167
	global_load_dwordx4 v[6:9], v175, s[50:51]
	ds_read_b128 v[180:183], v169
	ds_read_b128 v[184:187], v170
	s_waitcnt vmcnt(16)
	ds_write_b128 v168, v[10:13]
	ds_write_b128 v168, v[14:17] offset:1024
	v_lshl_add_u32 v176, v152, 10, v166
	global_load_dwordx4 v[10:13], v176, s[50:51]
	v_lshl_add_u32 v177, v153, 10, v167
	global_load_dwordx4 v[14:17], v177, s[50:51]
	ds_read_b128 v[188:191], v169
	ds_read_b128 v[192:195], v170
	s_waitcnt lgkmcnt(4)
	v_mfma_f32_16x16x32_fp8_fp8 v[196:199], v[180:181], v[134:135], 0
	v_mfma_f32_16x16x32_fp8_fp8 v[196:199], v[182:183], v[136:137], v[196:199]
	v_mfma_f32_16x16x32_fp8_fp8 v[196:199], v[184:185], v[138:139], v[196:199]
	v_mfma_f32_16x16x32_fp8_fp8 v[196:199], v[186:187], v[140:141], v[196:199]
	s_waitcnt vmcnt(16)
	ds_write_b128 v168, v[18:21]
	ds_write_b128 v168, v[22:25] offset:1024
	v_lshl_add_u32 v174, v154, 10, v166
	global_load_dwordx4 v[18:21], v174, s[50:51]
	v_lshl_add_u32 v175, v155, 10, v167
	global_load_dwordx4 v[22:25], v175, s[50:51]
	ds_read_b128 v[180:183], v169
	ds_read_b128 v[184:187], v170
	s_waitcnt lgkmcnt(4)
	v_mfma_f32_16x16x32_fp8_fp8 v[200:203], v[188:189], v[134:135], 0
	v_mfma_f32_16x16x32_fp8_fp8 v[200:203], v[190:191], v[136:137], v[200:203]
	v_mfma_f32_16x16x32_fp8_fp8 v[200:203], v[192:193], v[138:139], v[200:203]
	v_mfma_f32_16x16x32_fp8_fp8 v[200:203], v[194:195], v[140:141], v[200:203]
	v_cndmask_b32_e64 v226, v196, v198, s[54:55]
	v_cndmask_b32_e64 v227, v197, v199, s[54:55]
	s_waitcnt vmcnt(16)
	ds_write_b128 v168, v[26:29]
	ds_write_b128 v168, v[30:33] offset:1024
	v_lshl_add_u32 v176, v156, 10, v166
	global_load_dwordx4 v[26:29], v176, s[50:51]
	v_lshl_add_u32 v177, v157, 10, v167
	global_load_dwordx4 v[30:33], v177, s[50:51]
	ds_read_b128 v[188:191], v169
	ds_read_b128 v[192:195], v170
	s_waitcnt lgkmcnt(4)
	v_mfma_f32_16x16x32_fp8_fp8 v[204:207], v[180:181], v[134:135], 0
	v_mfma_f32_16x16x32_fp8_fp8 v[204:207], v[182:183], v[136:137], v[204:207]
	v_mfma_f32_16x16x32_fp8_fp8 v[204:207], v[184:185], v[138:139], v[204:207]
	v_mfma_f32_16x16x32_fp8_fp8 v[204:207], v[186:187], v[140:141], v[204:207]
	v_cndmask_b32_e64 v228, v200, v202, s[54:55]
	v_cndmask_b32_e64 v229, v201, v203, s[54:55]
	v_cndmask_b32_e64 v230, v226, v228, s[56:57]
	v_cndmask_b32_e64 v231, v227, v229, s[56:57]
	s_waitcnt vmcnt(16)
	ds_write_b128 v168, v[34:37]
	ds_write_b128 v168, v[38:41] offset:1024
	v_lshl_add_u32 v174, v158, 10, v166
	global_load_dwordx4 v[34:37], v174, s[50:51]
	v_lshl_add_u32 v175, v159, 10, v167
	global_load_dwordx4 v[38:41], v175, s[50:51]
	ds_read_b128 v[180:183], v169
	ds_read_b128 v[184:187], v170
	s_waitcnt lgkmcnt(4)
	v_mfma_f32_16x16x32_fp8_fp8 v[216:219], v[188:189], v[134:135], 0
	v_mfma_f32_16x16x32_fp8_fp8 v[216:219], v[190:191], v[136:137], v[216:219]
	v_mfma_f32_16x16x32_fp8_fp8 v[216:219], v[192:193], v[138:139], v[216:219]
	v_mfma_f32_16x16x32_fp8_fp8 v[216:219], v[194:195], v[140:141], v[216:219]
	v_cndmask_b32_e64 v226, v204, v206, s[54:55]
	v_cndmask_b32_e64 v227, v205, v207, s[54:55]
	s_waitcnt vmcnt(16)
	ds_write_b128 v168, v[42:45]
	ds_write_b128 v168, v[46:49] offset:1024
	v_lshl_add_u32 v176, v160, 10, v166
	global_load_dwordx4 v[42:45], v176, s[50:51]
	v_lshl_add_u32 v177, v161, 10, v167
	global_load_dwordx4 v[46:49], v177, s[50:51]
	ds_read_b128 v[188:191], v169
	ds_read_b128 v[192:195], v170
	s_waitcnt lgkmcnt(4)
	v_mfma_f32_16x16x32_fp8_fp8 v[196:199], v[180:181], v[134:135], 0
	v_mfma_f32_16x16x32_fp8_fp8 v[196:199], v[182:183], v[136:137], v[196:199]
	v_mfma_f32_16x16x32_fp8_fp8 v[196:199], v[184:185], v[138:139], v[196:199]
	v_mfma_f32_16x16x32_fp8_fp8 v[196:199], v[186:187], v[140:141], v[196:199]
	v_cndmask_b32_e64 v228, v216, v218, s[54:55]
	v_cndmask_b32_e64 v229, v217, v219, s[54:55]
	v_cndmask_b32_e64 v232, v226, v228, s[56:57]
	v_cndmask_b32_e64 v233, v227, v229, s[56:57]
	s_waitcnt vmcnt(16)
	ds_write_b128 v168, v[50:53]
	ds_write_b128 v168, v[54:57] offset:1024
	v_lshl_add_u32 v174, v162, 10, v166
	global_load_dwordx4 v[50:53], v174, s[50:51]
	v_lshl_add_u32 v175, v163, 10, v167
	global_load_dwordx4 v[54:57], v175, s[50:51]
	ds_read_b128 v[180:183], v169
	ds_read_b128 v[184:187], v170
	s_waitcnt lgkmcnt(4)
	v_mfma_f32_16x16x32_fp8_fp8 v[200:203], v[188:189], v[134:135], 0
	v_mfma_f32_16x16x32_fp8_fp8 v[200:203], v[190:191], v[136:137], v[200:203]
	v_mfma_f32_16x16x32_fp8_fp8 v[200:203], v[192:193], v[138:139], v[200:203]
	v_mfma_f32_16x16x32_fp8_fp8 v[200:203], v[194:195], v[140:141], v[200:203]
	v_cndmask_b32_e64 v226, v196, v198, s[54:55]
	v_cndmask_b32_e64 v227, v197, v199, s[54:55]
	s_waitcnt vmcnt(16)
	ds_write_b128 v168, v[58:61]
	ds_write_b128 v168, v[62:65] offset:1024
	v_lshl_add_u32 v176, v164, 10, v166
	global_load_dwordx4 v[58:61], v176, s[50:51]
	v_lshl_add_u32 v177, v165, 10, v167
	global_load_dwordx4 v[62:65], v177, s[50:51]
	ds_read_b128 v[188:191], v169
	ds_read_b128 v[192:195], v170
	s_waitcnt lgkmcnt(4)
	v_mfma_f32_16x16x32_fp8_fp8 v[204:207], v[180:181], v[134:135], 0
	v_mfma_f32_16x16x32_fp8_fp8 v[204:207], v[182:183], v[136:137], v[204:207]
	v_mfma_f32_16x16x32_fp8_fp8 v[204:207], v[184:185], v[138:139], v[204:207]
	v_mfma_f32_16x16x32_fp8_fp8 v[204:207], v[186:187], v[140:141], v[204:207]
	v_cndmask_b32_e64 v228, v200, v202, s[54:55]
	v_cndmask_b32_e64 v229, v201, v203, s[54:55]
	v_cndmask_b32_e64 v234, v226, v228, s[56:57]
	v_cndmask_b32_e64 v235, v227, v229, s[56:57]
	s_waitcnt lgkmcnt(0)
	v_mfma_f32_16x16x32_fp8_fp8 v[216:219], v[188:189], v[134:135], 0
	v_mfma_f32_16x16x32_fp8_fp8 v[216:219], v[190:191], v[136:137], v[216:219]
	v_mfma_f32_16x16x32_fp8_fp8 v[216:219], v[192:193], v[138:139], v[216:219]
	v_mfma_f32_16x16x32_fp8_fp8 v[216:219], v[194:195], v[140:141], v[216:219]
	v_add_u32_e32 v0, 4096, v172
	ds_read2_b32 v[150:151], v0 offset0:0 offset1:8
	ds_read2_b32 v[152:153], v0 offset0:16 offset1:24
	ds_read2_b32 v[154:155], v0 offset0:32 offset1:40
	ds_read2_b32 v[156:157], v0 offset0:48 offset1:56
	ds_read2_b32 v[158:159], v0 offset0:64 offset1:72
	ds_read2_b32 v[160:161], v0 offset0:80 offset1:88
	ds_read2_b32 v[162:163], v0 offset0:96 offset1:104
	ds_read2_b32 v[164:165], v0 offset0:112 offset1:120
	v_add_u32_e32 v171, s80, v171
	global_load_dwordx4 v[134:137], v171, s[52:53]
	global_load_dwordx4 v[138:141], v171, s[52:53] offset:16
	v_cndmask_b32_e64 v226, v204, v206, s[54:55]
	v_cndmask_b32_e64 v227, v205, v207, s[54:55]
	v_cndmask_b32_e64 v228, v216, v218, s[54:55]
	v_cndmask_b32_e64 v229, v217, v219, s[54:55]
	v_cndmask_b32_e64 v236, v226, v228, s[56:57]
	v_cndmask_b32_e64 v237, v227, v229, s[56:57]
	v_cndmask_b32_e64 v226, v230, v232, s[58:59]
	v_cndmask_b32_e64 v228, v234, v236, s[58:59]
	v_cndmask_b32_e64 v227, v231, v233, s[58:59]
	v_cndmask_b32_e64 v229, v235, v237, s[58:59]
	v_cndmask_b32_e64 v226, v226, v228, s[60:61]
	v_cndmask_b32_e64 v227, v227, v229, s[60:61]
	v_add_f32_e32 v94, v94, v226
	v_add_f32_e32 v95, v95, v227
	s_waitcnt vmcnt(16)
	ds_write_b128 v168, v[2:5]
	ds_write_b128 v168, v[6:9] offset:1024
	s_waitcnt lgkmcnt(2)
	v_lshl_add_u32 v174, v150, 10, v166
	global_load_dwordx4 v[2:5], v174, s[50:51]
	v_lshl_add_u32 v175, v151, 10, v167
	global_load_dwordx4 v[6:9], v175, s[50:51]
	ds_read_b128 v[180:183], v169
	ds_read_b128 v[184:187], v170
	s_waitcnt vmcnt(16)
	ds_write_b128 v168, v[10:13]
	ds_write_b128 v168, v[14:17] offset:1024
	v_lshl_add_u32 v176, v152, 10, v166
	global_load_dwordx4 v[10:13], v176, s[50:51]
	v_lshl_add_u32 v177, v153, 10, v167
	global_load_dwordx4 v[14:17], v177, s[50:51]
	ds_read_b128 v[188:191], v169
	ds_read_b128 v[192:195], v170
	s_waitcnt lgkmcnt(4)
	v_mfma_f32_16x16x32_fp8_fp8 v[196:199], v[180:181], v[142:143], 0
	v_mfma_f32_16x16x32_fp8_fp8 v[196:199], v[182:183], v[144:145], v[196:199]
	v_mfma_f32_16x16x32_fp8_fp8 v[196:199], v[184:185], v[146:147], v[196:199]
	v_mfma_f32_16x16x32_fp8_fp8 v[196:199], v[186:187], v[148:149], v[196:199]
	s_waitcnt vmcnt(16)
	ds_write_b128 v168, v[18:21]
	ds_write_b128 v168, v[22:25] offset:1024
	v_lshl_add_u32 v174, v154, 10, v166
	global_load_dwordx4 v[18:21], v174, s[50:51]
	v_lshl_add_u32 v175, v155, 10, v167
	global_load_dwordx4 v[22:25], v175, s[50:51]
	ds_read_b128 v[180:183], v169
	ds_read_b128 v[184:187], v170
	s_waitcnt lgkmcnt(4)
	v_mfma_f32_16x16x32_fp8_fp8 v[200:203], v[188:189], v[142:143], 0
	v_mfma_f32_16x16x32_fp8_fp8 v[200:203], v[190:191], v[144:145], v[200:203]
	v_mfma_f32_16x16x32_fp8_fp8 v[200:203], v[192:193], v[146:147], v[200:203]
	v_mfma_f32_16x16x32_fp8_fp8 v[200:203], v[194:195], v[148:149], v[200:203]
	v_cndmask_b32_e64 v226, v196, v198, s[54:55]
	v_cndmask_b32_e64 v227, v197, v199, s[54:55]
	s_waitcnt vmcnt(16)
	ds_write_b128 v168, v[26:29]
	ds_write_b128 v168, v[30:33] offset:1024
	v_lshl_add_u32 v176, v156, 10, v166
	global_load_dwordx4 v[26:29], v176, s[50:51]
	v_lshl_add_u32 v177, v157, 10, v167
	global_load_dwordx4 v[30:33], v177, s[50:51]
	ds_read_b128 v[188:191], v169
	ds_read_b128 v[192:195], v170
	s_waitcnt lgkmcnt(4)
	v_mfma_f32_16x16x32_fp8_fp8 v[204:207], v[180:181], v[142:143], 0
	v_mfma_f32_16x16x32_fp8_fp8 v[204:207], v[182:183], v[144:145], v[204:207]
	v_mfma_f32_16x16x32_fp8_fp8 v[204:207], v[184:185], v[146:147], v[204:207]
	v_mfma_f32_16x16x32_fp8_fp8 v[204:207], v[186:187], v[148:149], v[204:207]
	v_cndmask_b32_e64 v228, v200, v202, s[54:55]
	v_cndmask_b32_e64 v229, v201, v203, s[54:55]
	v_cndmask_b32_e64 v230, v226, v228, s[56:57]
	v_cndmask_b32_e64 v231, v227, v229, s[56:57]
	s_waitcnt vmcnt(16)
	ds_write_b128 v168, v[34:37]
	ds_write_b128 v168, v[38:41] offset:1024
	v_lshl_add_u32 v174, v158, 10, v166
	global_load_dwordx4 v[34:37], v174, s[50:51]
	v_lshl_add_u32 v175, v159, 10, v167
	global_load_dwordx4 v[38:41], v175, s[50:51]
	ds_read_b128 v[180:183], v169
	ds_read_b128 v[184:187], v170
	s_waitcnt lgkmcnt(4)
	v_mfma_f32_16x16x32_fp8_fp8 v[216:219], v[188:189], v[142:143], 0
	v_mfma_f32_16x16x32_fp8_fp8 v[216:219], v[190:191], v[144:145], v[216:219]
	v_mfma_f32_16x16x32_fp8_fp8 v[216:219], v[192:193], v[146:147], v[216:219]
	v_mfma_f32_16x16x32_fp8_fp8 v[216:219], v[194:195], v[148:149], v[216:219]
	v_cndmask_b32_e64 v226, v204, v206, s[54:55]
	v_cndmask_b32_e64 v227, v205, v207, s[54:55]
	s_waitcnt vmcnt(16)
	ds_write_b128 v168, v[42:45]
	ds_write_b128 v168, v[46:49] offset:1024
	v_lshl_add_u32 v176, v160, 10, v166
	global_load_dwordx4 v[42:45], v176, s[50:51]
	v_lshl_add_u32 v177, v161, 10, v167
	global_load_dwordx4 v[46:49], v177, s[50:51]
	ds_read_b128 v[188:191], v169
	ds_read_b128 v[192:195], v170
	s_waitcnt lgkmcnt(4)
	v_mfma_f32_16x16x32_fp8_fp8 v[196:199], v[180:181], v[142:143], 0
	v_mfma_f32_16x16x32_fp8_fp8 v[196:199], v[182:183], v[144:145], v[196:199]
	v_mfma_f32_16x16x32_fp8_fp8 v[196:199], v[184:185], v[146:147], v[196:199]
	v_mfma_f32_16x16x32_fp8_fp8 v[196:199], v[186:187], v[148:149], v[196:199]
	v_cndmask_b32_e64 v228, v216, v218, s[54:55]
	v_cndmask_b32_e64 v229, v217, v219, s[54:55]
	v_cndmask_b32_e64 v232, v226, v228, s[56:57]
	v_cndmask_b32_e64 v233, v227, v229, s[56:57]
	s_waitcnt vmcnt(16)
	ds_write_b128 v168, v[50:53]
	ds_write_b128 v168, v[54:57] offset:1024
	v_lshl_add_u32 v174, v162, 10, v166
	global_load_dwordx4 v[50:53], v174, s[50:51]
	v_lshl_add_u32 v175, v163, 10, v167
	global_load_dwordx4 v[54:57], v175, s[50:51]
	ds_read_b128 v[180:183], v169
	ds_read_b128 v[184:187], v170
	s_waitcnt lgkmcnt(4)
	v_mfma_f32_16x16x32_fp8_fp8 v[200:203], v[188:189], v[142:143], 0
	v_mfma_f32_16x16x32_fp8_fp8 v[200:203], v[190:191], v[144:145], v[200:203]
	v_mfma_f32_16x16x32_fp8_fp8 v[200:203], v[192:193], v[146:147], v[200:203]
	v_mfma_f32_16x16x32_fp8_fp8 v[200:203], v[194:195], v[148:149], v[200:203]
	v_cndmask_b32_e64 v226, v196, v198, s[54:55]
	v_cndmask_b32_e64 v227, v197, v199, s[54:55]
	s_waitcnt vmcnt(16)
	ds_write_b128 v168, v[58:61]
	ds_write_b128 v168, v[62:65] offset:1024
	v_lshl_add_u32 v176, v164, 10, v166
	global_load_dwordx4 v[58:61], v176, s[50:51]
	v_lshl_add_u32 v177, v165, 10, v167
	global_load_dwordx4 v[62:65], v177, s[50:51]
	ds_read_b128 v[188:191], v169
	ds_read_b128 v[192:195], v170
	s_waitcnt lgkmcnt(4)
	v_mfma_f32_16x16x32_fp8_fp8 v[204:207], v[180:181], v[142:143], 0
	v_mfma_f32_16x16x32_fp8_fp8 v[204:207], v[182:183], v[144:145], v[204:207]
	v_mfma_f32_16x16x32_fp8_fp8 v[204:207], v[184:185], v[146:147], v[204:207]
	v_mfma_f32_16x16x32_fp8_fp8 v[204:207], v[186:187], v[148:149], v[204:207]
	v_cndmask_b32_e64 v228, v200, v202, s[54:55]
	v_cndmask_b32_e64 v229, v201, v203, s[54:55]
	v_cndmask_b32_e64 v234, v226, v228, s[56:57]
	v_cndmask_b32_e64 v235, v227, v229, s[56:57]
	s_waitcnt lgkmcnt(0)
	v_mfma_f32_16x16x32_fp8_fp8 v[216:219], v[188:189], v[142:143], 0
	v_mfma_f32_16x16x32_fp8_fp8 v[216:219], v[190:191], v[144:145], v[216:219]
	v_mfma_f32_16x16x32_fp8_fp8 v[216:219], v[192:193], v[146:147], v[216:219]
	v_mfma_f32_16x16x32_fp8_fp8 v[216:219], v[194:195], v[148:149], v[216:219]
	v_add_u32_e32 v0, 4608, v172
	ds_read2_b32 v[150:151], v0 offset0:0 offset1:8
	ds_read2_b32 v[152:153], v0 offset0:16 offset1:24
	ds_read2_b32 v[154:155], v0 offset0:32 offset1:40
	ds_read2_b32 v[156:157], v0 offset0:48 offset1:56
	ds_read2_b32 v[158:159], v0 offset0:64 offset1:72
	ds_read2_b32 v[160:161], v0 offset0:80 offset1:88
	ds_read2_b32 v[162:163], v0 offset0:96 offset1:104
	ds_read2_b32 v[164:165], v0 offset0:112 offset1:120
	v_add_u32_e32 v171, s80, v171
	global_load_dwordx4 v[142:145], v171, s[52:53]
	global_load_dwordx4 v[146:149], v171, s[52:53] offset:16
	v_cndmask_b32_e64 v226, v204, v206, s[54:55]
	v_cndmask_b32_e64 v227, v205, v207, s[54:55]
	v_cndmask_b32_e64 v228, v216, v218, s[54:55]
	v_cndmask_b32_e64 v229, v217, v219, s[54:55]
	v_cndmask_b32_e64 v236, v226, v228, s[56:57]
	v_cndmask_b32_e64 v237, v227, v229, s[56:57]
	v_cndmask_b32_e64 v226, v230, v232, s[58:59]
	v_cndmask_b32_e64 v228, v234, v236, s[58:59]
	v_cndmask_b32_e64 v227, v231, v233, s[58:59]
	v_cndmask_b32_e64 v229, v235, v237, s[58:59]
	v_cndmask_b32_e64 v226, v226, v228, s[60:61]
	v_cndmask_b32_e64 v227, v227, v229, s[60:61]
	v_add_f32_e32 v96, v96, v226
	v_add_f32_e32 v97, v97, v227
	s_waitcnt vmcnt(16)
	ds_write_b128 v168, v[2:5]
	ds_write_b128 v168, v[6:9] offset:1024
	s_waitcnt lgkmcnt(2)
	v_lshl_add_u32 v174, v150, 10, v166
	global_load_dwordx4 v[2:5], v174, s[50:51]
	v_lshl_add_u32 v175, v151, 10, v167
	global_load_dwordx4 v[6:9], v175, s[50:51]
	ds_read_b128 v[180:183], v169
	ds_read_b128 v[184:187], v170
	s_waitcnt vmcnt(16)
	ds_write_b128 v168, v[10:13]
	ds_write_b128 v168, v[14:17] offset:1024
	v_lshl_add_u32 v176, v152, 10, v166
	global_load_dwordx4 v[10:13], v176, s[50:51]
	v_lshl_add_u32 v177, v153, 10, v167
	global_load_dwordx4 v[14:17], v177, s[50:51]
	ds_read_b128 v[188:191], v169
	ds_read_b128 v[192:195], v170
	s_waitcnt lgkmcnt(4)
	v_mfma_f32_16x16x32_fp8_fp8 v[196:199], v[180:181], v[134:135], 0
	v_mfma_f32_16x16x32_fp8_fp8 v[196:199], v[182:183], v[136:137], v[196:199]
	v_mfma_f32_16x16x32_fp8_fp8 v[196:199], v[184:185], v[138:139], v[196:199]
	v_mfma_f32_16x16x32_fp8_fp8 v[196:199], v[186:187], v[140:141], v[196:199]
	s_waitcnt vmcnt(16)
	ds_write_b128 v168, v[18:21]
	ds_write_b128 v168, v[22:25] offset:1024
	v_lshl_add_u32 v174, v154, 10, v166
	global_load_dwordx4 v[18:21], v174, s[50:51]
	v_lshl_add_u32 v175, v155, 10, v167
	global_load_dwordx4 v[22:25], v175, s[50:51]
	ds_read_b128 v[180:183], v169
	ds_read_b128 v[184:187], v170
	s_waitcnt lgkmcnt(4)
	v_mfma_f32_16x16x32_fp8_fp8 v[200:203], v[188:189], v[134:135], 0
	v_mfma_f32_16x16x32_fp8_fp8 v[200:203], v[190:191], v[136:137], v[200:203]
	v_mfma_f32_16x16x32_fp8_fp8 v[200:203], v[192:193], v[138:139], v[200:203]
	v_mfma_f32_16x16x32_fp8_fp8 v[200:203], v[194:195], v[140:141], v[200:203]
	v_cndmask_b32_e64 v226, v196, v198, s[54:55]
	v_cndmask_b32_e64 v227, v197, v199, s[54:55]
	s_waitcnt vmcnt(16)
	ds_write_b128 v168, v[26:29]
	ds_write_b128 v168, v[30:33] offset:1024
	v_lshl_add_u32 v176, v156, 10, v166
	global_load_dwordx4 v[26:29], v176, s[50:51]
	v_lshl_add_u32 v177, v157, 10, v167
	global_load_dwordx4 v[30:33], v177, s[50:51]
	ds_read_b128 v[188:191], v169
	ds_read_b128 v[192:195], v170
	s_waitcnt lgkmcnt(4)
	v_mfma_f32_16x16x32_fp8_fp8 v[204:207], v[180:181], v[134:135], 0
	v_mfma_f32_16x16x32_fp8_fp8 v[204:207], v[182:183], v[136:137], v[204:207]
	v_mfma_f32_16x16x32_fp8_fp8 v[204:207], v[184:185], v[138:139], v[204:207]
	v_mfma_f32_16x16x32_fp8_fp8 v[204:207], v[186:187], v[140:141], v[204:207]
	v_cndmask_b32_e64 v228, v200, v202, s[54:55]
	v_cndmask_b32_e64 v229, v201, v203, s[54:55]
	v_cndmask_b32_e64 v230, v226, v228, s[56:57]
	v_cndmask_b32_e64 v231, v227, v229, s[56:57]
	s_waitcnt vmcnt(16)
	ds_write_b128 v168, v[34:37]
	ds_write_b128 v168, v[38:41] offset:1024
	v_lshl_add_u32 v174, v158, 10, v166
	global_load_dwordx4 v[34:37], v174, s[50:51]
	v_lshl_add_u32 v175, v159, 10, v167
	global_load_dwordx4 v[38:41], v175, s[50:51]
	ds_read_b128 v[180:183], v169
	ds_read_b128 v[184:187], v170
	s_waitcnt lgkmcnt(4)
	v_mfma_f32_16x16x32_fp8_fp8 v[216:219], v[188:189], v[134:135], 0
	v_mfma_f32_16x16x32_fp8_fp8 v[216:219], v[190:191], v[136:137], v[216:219]
	v_mfma_f32_16x16x32_fp8_fp8 v[216:219], v[192:193], v[138:139], v[216:219]
	v_mfma_f32_16x16x32_fp8_fp8 v[216:219], v[194:195], v[140:141], v[216:219]
	v_cndmask_b32_e64 v226, v204, v206, s[54:55]
	v_cndmask_b32_e64 v227, v205, v207, s[54:55]
	s_waitcnt vmcnt(16)
	ds_write_b128 v168, v[42:45]
	ds_write_b128 v168, v[46:49] offset:1024
	v_lshl_add_u32 v176, v160, 10, v166
	global_load_dwordx4 v[42:45], v176, s[50:51]
	v_lshl_add_u32 v177, v161, 10, v167
	global_load_dwordx4 v[46:49], v177, s[50:51]
	ds_read_b128 v[188:191], v169
	ds_read_b128 v[192:195], v170
	s_waitcnt lgkmcnt(4)
	v_mfma_f32_16x16x32_fp8_fp8 v[196:199], v[180:181], v[134:135], 0
	v_mfma_f32_16x16x32_fp8_fp8 v[196:199], v[182:183], v[136:137], v[196:199]
	v_mfma_f32_16x16x32_fp8_fp8 v[196:199], v[184:185], v[138:139], v[196:199]
	v_mfma_f32_16x16x32_fp8_fp8 v[196:199], v[186:187], v[140:141], v[196:199]
	v_cndmask_b32_e64 v228, v216, v218, s[54:55]
	v_cndmask_b32_e64 v229, v217, v219, s[54:55]
	v_cndmask_b32_e64 v232, v226, v228, s[56:57]
	v_cndmask_b32_e64 v233, v227, v229, s[56:57]
	s_waitcnt vmcnt(16)
	ds_write_b128 v168, v[50:53]
	ds_write_b128 v168, v[54:57] offset:1024
	v_lshl_add_u32 v174, v162, 10, v166
	global_load_dwordx4 v[50:53], v174, s[50:51]
	v_lshl_add_u32 v175, v163, 10, v167
	global_load_dwordx4 v[54:57], v175, s[50:51]
	ds_read_b128 v[180:183], v169
	ds_read_b128 v[184:187], v170
	s_waitcnt lgkmcnt(4)
	v_mfma_f32_16x16x32_fp8_fp8 v[200:203], v[188:189], v[134:135], 0
	v_mfma_f32_16x16x32_fp8_fp8 v[200:203], v[190:191], v[136:137], v[200:203]
	v_mfma_f32_16x16x32_fp8_fp8 v[200:203], v[192:193], v[138:139], v[200:203]
	v_mfma_f32_16x16x32_fp8_fp8 v[200:203], v[194:195], v[140:141], v[200:203]
	v_cndmask_b32_e64 v226, v196, v198, s[54:55]
	v_cndmask_b32_e64 v227, v197, v199, s[54:55]
	s_waitcnt vmcnt(16)
	ds_write_b128 v168, v[58:61]
	ds_write_b128 v168, v[62:65] offset:1024
	v_lshl_add_u32 v176, v164, 10, v166
	global_load_dwordx4 v[58:61], v176, s[50:51]
	v_lshl_add_u32 v177, v165, 10, v167
	global_load_dwordx4 v[62:65], v177, s[50:51]
	ds_read_b128 v[188:191], v169
	ds_read_b128 v[192:195], v170
	s_waitcnt lgkmcnt(4)
	v_mfma_f32_16x16x32_fp8_fp8 v[204:207], v[180:181], v[134:135], 0
	v_mfma_f32_16x16x32_fp8_fp8 v[204:207], v[182:183], v[136:137], v[204:207]
	v_mfma_f32_16x16x32_fp8_fp8 v[204:207], v[184:185], v[138:139], v[204:207]
	v_mfma_f32_16x16x32_fp8_fp8 v[204:207], v[186:187], v[140:141], v[204:207]
	v_cndmask_b32_e64 v228, v200, v202, s[54:55]
	v_cndmask_b32_e64 v229, v201, v203, s[54:55]
	v_cndmask_b32_e64 v234, v226, v228, s[56:57]
	v_cndmask_b32_e64 v235, v227, v229, s[56:57]
	s_waitcnt lgkmcnt(0)
	v_mfma_f32_16x16x32_fp8_fp8 v[216:219], v[188:189], v[134:135], 0
	v_mfma_f32_16x16x32_fp8_fp8 v[216:219], v[190:191], v[136:137], v[216:219]
	v_mfma_f32_16x16x32_fp8_fp8 v[216:219], v[192:193], v[138:139], v[216:219]
	v_mfma_f32_16x16x32_fp8_fp8 v[216:219], v[194:195], v[140:141], v[216:219]
	v_add_u32_e32 v0, 5120, v172
	ds_read2_b32 v[150:151], v0 offset0:0 offset1:8
	ds_read2_b32 v[152:153], v0 offset0:16 offset1:24
	ds_read2_b32 v[154:155], v0 offset0:32 offset1:40
	ds_read2_b32 v[156:157], v0 offset0:48 offset1:56
	ds_read2_b32 v[158:159], v0 offset0:64 offset1:72
	ds_read2_b32 v[160:161], v0 offset0:80 offset1:88
	ds_read2_b32 v[162:163], v0 offset0:96 offset1:104
	ds_read2_b32 v[164:165], v0 offset0:112 offset1:120
	v_add_u32_e32 v171, s80, v171
	global_load_dwordx4 v[134:137], v171, s[52:53]
	global_load_dwordx4 v[138:141], v171, s[52:53] offset:16
	v_cndmask_b32_e64 v226, v204, v206, s[54:55]
	v_cndmask_b32_e64 v227, v205, v207, s[54:55]
	v_cndmask_b32_e64 v228, v216, v218, s[54:55]
	v_cndmask_b32_e64 v229, v217, v219, s[54:55]
	v_cndmask_b32_e64 v236, v226, v228, s[56:57]
	v_cndmask_b32_e64 v237, v227, v229, s[56:57]
	v_cndmask_b32_e64 v226, v230, v232, s[58:59]
	v_cndmask_b32_e64 v228, v234, v236, s[58:59]
	v_cndmask_b32_e64 v227, v231, v233, s[58:59]
	v_cndmask_b32_e64 v229, v235, v237, s[58:59]
	v_cndmask_b32_e64 v226, v226, v228, s[60:61]
	v_cndmask_b32_e64 v227, v227, v229, s[60:61]
	v_add_f32_e32 v98, v98, v226
	v_add_f32_e32 v99, v99, v227
	s_waitcnt vmcnt(16)
	ds_write_b128 v168, v[2:5]
	ds_write_b128 v168, v[6:9] offset:1024
	s_waitcnt lgkmcnt(2)
	v_lshl_add_u32 v174, v150, 10, v166
	global_load_dwordx4 v[2:5], v174, s[50:51]
	v_lshl_add_u32 v175, v151, 10, v167
	global_load_dwordx4 v[6:9], v175, s[50:51]
	ds_read_b128 v[180:183], v169
	ds_read_b128 v[184:187], v170
	s_waitcnt vmcnt(16)
	ds_write_b128 v168, v[10:13]
	ds_write_b128 v168, v[14:17] offset:1024
	v_lshl_add_u32 v176, v152, 10, v166
	global_load_dwordx4 v[10:13], v176, s[50:51]
	v_lshl_add_u32 v177, v153, 10, v167
	global_load_dwordx4 v[14:17], v177, s[50:51]
	ds_read_b128 v[188:191], v169
	ds_read_b128 v[192:195], v170
	s_waitcnt lgkmcnt(4)
	v_mfma_f32_16x16x32_fp8_fp8 v[196:199], v[180:181], v[142:143], 0
	v_mfma_f32_16x16x32_fp8_fp8 v[196:199], v[182:183], v[144:145], v[196:199]
	v_mfma_f32_16x16x32_fp8_fp8 v[196:199], v[184:185], v[146:147], v[196:199]
	v_mfma_f32_16x16x32_fp8_fp8 v[196:199], v[186:187], v[148:149], v[196:199]
	s_waitcnt vmcnt(16)
	ds_write_b128 v168, v[18:21]
	ds_write_b128 v168, v[22:25] offset:1024
	v_lshl_add_u32 v174, v154, 10, v166
	global_load_dwordx4 v[18:21], v174, s[50:51]
	v_lshl_add_u32 v175, v155, 10, v167
	global_load_dwordx4 v[22:25], v175, s[50:51]
	ds_read_b128 v[180:183], v169
	ds_read_b128 v[184:187], v170
	s_waitcnt lgkmcnt(4)
	v_mfma_f32_16x16x32_fp8_fp8 v[200:203], v[188:189], v[142:143], 0
	v_mfma_f32_16x16x32_fp8_fp8 v[200:203], v[190:191], v[144:145], v[200:203]
	v_mfma_f32_16x16x32_fp8_fp8 v[200:203], v[192:193], v[146:147], v[200:203]
	v_mfma_f32_16x16x32_fp8_fp8 v[200:203], v[194:195], v[148:149], v[200:203]
	v_cndmask_b32_e64 v226, v196, v198, s[54:55]
	v_cndmask_b32_e64 v227, v197, v199, s[54:55]
	s_waitcnt vmcnt(16)
	ds_write_b128 v168, v[26:29]
	ds_write_b128 v168, v[30:33] offset:1024
	v_lshl_add_u32 v176, v156, 10, v166
	global_load_dwordx4 v[26:29], v176, s[50:51]
	v_lshl_add_u32 v177, v157, 10, v167
	global_load_dwordx4 v[30:33], v177, s[50:51]
	ds_read_b128 v[188:191], v169
	ds_read_b128 v[192:195], v170
	s_waitcnt lgkmcnt(4)
	v_mfma_f32_16x16x32_fp8_fp8 v[204:207], v[180:181], v[142:143], 0
	v_mfma_f32_16x16x32_fp8_fp8 v[204:207], v[182:183], v[144:145], v[204:207]
	v_mfma_f32_16x16x32_fp8_fp8 v[204:207], v[184:185], v[146:147], v[204:207]
	v_mfma_f32_16x16x32_fp8_fp8 v[204:207], v[186:187], v[148:149], v[204:207]
	v_cndmask_b32_e64 v228, v200, v202, s[54:55]
	v_cndmask_b32_e64 v229, v201, v203, s[54:55]
	v_cndmask_b32_e64 v230, v226, v228, s[56:57]
	v_cndmask_b32_e64 v231, v227, v229, s[56:57]
	s_waitcnt vmcnt(16)
	ds_write_b128 v168, v[34:37]
	ds_write_b128 v168, v[38:41] offset:1024
	v_lshl_add_u32 v174, v158, 10, v166
	global_load_dwordx4 v[34:37], v174, s[50:51]
	v_lshl_add_u32 v175, v159, 10, v167
	global_load_dwordx4 v[38:41], v175, s[50:51]
	ds_read_b128 v[180:183], v169
	ds_read_b128 v[184:187], v170
	s_waitcnt lgkmcnt(4)
	v_mfma_f32_16x16x32_fp8_fp8 v[216:219], v[188:189], v[142:143], 0
	v_mfma_f32_16x16x32_fp8_fp8 v[216:219], v[190:191], v[144:145], v[216:219]
	v_mfma_f32_16x16x32_fp8_fp8 v[216:219], v[192:193], v[146:147], v[216:219]
	v_mfma_f32_16x16x32_fp8_fp8 v[216:219], v[194:195], v[148:149], v[216:219]
	v_cndmask_b32_e64 v226, v204, v206, s[54:55]
	v_cndmask_b32_e64 v227, v205, v207, s[54:55]
	s_waitcnt vmcnt(16)
	ds_write_b128 v168, v[42:45]
	ds_write_b128 v168, v[46:49] offset:1024
	v_lshl_add_u32 v176, v160, 10, v166
	global_load_dwordx4 v[42:45], v176, s[50:51]
	v_lshl_add_u32 v177, v161, 10, v167
	global_load_dwordx4 v[46:49], v177, s[50:51]
	ds_read_b128 v[188:191], v169
	ds_read_b128 v[192:195], v170
	s_waitcnt lgkmcnt(4)
	v_mfma_f32_16x16x32_fp8_fp8 v[196:199], v[180:181], v[142:143], 0
	v_mfma_f32_16x16x32_fp8_fp8 v[196:199], v[182:183], v[144:145], v[196:199]
	v_mfma_f32_16x16x32_fp8_fp8 v[196:199], v[184:185], v[146:147], v[196:199]
	v_mfma_f32_16x16x32_fp8_fp8 v[196:199], v[186:187], v[148:149], v[196:199]
	v_cndmask_b32_e64 v228, v216, v218, s[54:55]
	v_cndmask_b32_e64 v229, v217, v219, s[54:55]
	v_cndmask_b32_e64 v232, v226, v228, s[56:57]
	v_cndmask_b32_e64 v233, v227, v229, s[56:57]
	s_waitcnt vmcnt(16)
	ds_write_b128 v168, v[50:53]
	ds_write_b128 v168, v[54:57] offset:1024
	v_lshl_add_u32 v174, v162, 10, v166
	global_load_dwordx4 v[50:53], v174, s[50:51]
	v_lshl_add_u32 v175, v163, 10, v167
	global_load_dwordx4 v[54:57], v175, s[50:51]
	ds_read_b128 v[180:183], v169
	ds_read_b128 v[184:187], v170
	s_waitcnt lgkmcnt(4)
	v_mfma_f32_16x16x32_fp8_fp8 v[200:203], v[188:189], v[142:143], 0
	v_mfma_f32_16x16x32_fp8_fp8 v[200:203], v[190:191], v[144:145], v[200:203]
	v_mfma_f32_16x16x32_fp8_fp8 v[200:203], v[192:193], v[146:147], v[200:203]
	v_mfma_f32_16x16x32_fp8_fp8 v[200:203], v[194:195], v[148:149], v[200:203]
	v_cndmask_b32_e64 v226, v196, v198, s[54:55]
	v_cndmask_b32_e64 v227, v197, v199, s[54:55]
	s_waitcnt vmcnt(16)
	ds_write_b128 v168, v[58:61]
	ds_write_b128 v168, v[62:65] offset:1024
	v_lshl_add_u32 v176, v164, 10, v166
	global_load_dwordx4 v[58:61], v176, s[50:51]
	v_lshl_add_u32 v177, v165, 10, v167
	global_load_dwordx4 v[62:65], v177, s[50:51]
	ds_read_b128 v[188:191], v169
	ds_read_b128 v[192:195], v170
	s_waitcnt lgkmcnt(4)
	v_mfma_f32_16x16x32_fp8_fp8 v[204:207], v[180:181], v[142:143], 0
	v_mfma_f32_16x16x32_fp8_fp8 v[204:207], v[182:183], v[144:145], v[204:207]
	v_mfma_f32_16x16x32_fp8_fp8 v[204:207], v[184:185], v[146:147], v[204:207]
	v_mfma_f32_16x16x32_fp8_fp8 v[204:207], v[186:187], v[148:149], v[204:207]
	v_cndmask_b32_e64 v228, v200, v202, s[54:55]
	v_cndmask_b32_e64 v229, v201, v203, s[54:55]
	v_cndmask_b32_e64 v234, v226, v228, s[56:57]
	v_cndmask_b32_e64 v235, v227, v229, s[56:57]
	s_waitcnt lgkmcnt(0)
	v_mfma_f32_16x16x32_fp8_fp8 v[216:219], v[188:189], v[142:143], 0
	v_mfma_f32_16x16x32_fp8_fp8 v[216:219], v[190:191], v[144:145], v[216:219]
	v_mfma_f32_16x16x32_fp8_fp8 v[216:219], v[192:193], v[146:147], v[216:219]
	v_mfma_f32_16x16x32_fp8_fp8 v[216:219], v[194:195], v[148:149], v[216:219]
	v_add_u32_e32 v0, 5632, v172
	ds_read2_b32 v[150:151], v0 offset0:0 offset1:8
	ds_read2_b32 v[152:153], v0 offset0:16 offset1:24
	ds_read2_b32 v[154:155], v0 offset0:32 offset1:40
	ds_read2_b32 v[156:157], v0 offset0:48 offset1:56
	ds_read2_b32 v[158:159], v0 offset0:64 offset1:72
	ds_read2_b32 v[160:161], v0 offset0:80 offset1:88
	ds_read2_b32 v[162:163], v0 offset0:96 offset1:104
	ds_read2_b32 v[164:165], v0 offset0:112 offset1:120
	v_add_u32_e32 v171, s80, v171
	global_load_dwordx4 v[142:145], v171, s[52:53]
	global_load_dwordx4 v[146:149], v171, s[52:53] offset:16
	v_cndmask_b32_e64 v226, v204, v206, s[54:55]
	v_cndmask_b32_e64 v227, v205, v207, s[54:55]
	v_cndmask_b32_e64 v228, v216, v218, s[54:55]
	v_cndmask_b32_e64 v229, v217, v219, s[54:55]
	v_cndmask_b32_e64 v236, v226, v228, s[56:57]
	v_cndmask_b32_e64 v237, v227, v229, s[56:57]
	v_cndmask_b32_e64 v226, v230, v232, s[58:59]
	v_cndmask_b32_e64 v228, v234, v236, s[58:59]
	v_cndmask_b32_e64 v227, v231, v233, s[58:59]
	v_cndmask_b32_e64 v229, v235, v237, s[58:59]
	v_cndmask_b32_e64 v226, v226, v228, s[60:61]
	v_cndmask_b32_e64 v227, v227, v229, s[60:61]
	v_add_f32_e32 v100, v100, v226
	v_add_f32_e32 v101, v101, v227
	s_waitcnt vmcnt(16)
	ds_write_b128 v168, v[2:5]
	ds_write_b128 v168, v[6:9] offset:1024
	s_waitcnt lgkmcnt(2)
	v_lshl_add_u32 v174, v150, 10, v166
	global_load_dwordx4 v[2:5], v174, s[50:51]
	v_lshl_add_u32 v175, v151, 10, v167
	global_load_dwordx4 v[6:9], v175, s[50:51]
	ds_read_b128 v[180:183], v169
	ds_read_b128 v[184:187], v170
	s_waitcnt vmcnt(16)
	ds_write_b128 v168, v[10:13]
	ds_write_b128 v168, v[14:17] offset:1024
	v_lshl_add_u32 v176, v152, 10, v166
	global_load_dwordx4 v[10:13], v176, s[50:51]
	v_lshl_add_u32 v177, v153, 10, v167
	global_load_dwordx4 v[14:17], v177, s[50:51]
	ds_read_b128 v[188:191], v169
	ds_read_b128 v[192:195], v170
	s_waitcnt lgkmcnt(4)
	v_mfma_f32_16x16x32_fp8_fp8 v[196:199], v[180:181], v[134:135], 0
	v_mfma_f32_16x16x32_fp8_fp8 v[196:199], v[182:183], v[136:137], v[196:199]
	v_mfma_f32_16x16x32_fp8_fp8 v[196:199], v[184:185], v[138:139], v[196:199]
	v_mfma_f32_16x16x32_fp8_fp8 v[196:199], v[186:187], v[140:141], v[196:199]
	s_waitcnt vmcnt(16)
	ds_write_b128 v168, v[18:21]
	ds_write_b128 v168, v[22:25] offset:1024
	v_lshl_add_u32 v174, v154, 10, v166
	global_load_dwordx4 v[18:21], v174, s[50:51]
	v_lshl_add_u32 v175, v155, 10, v167
	global_load_dwordx4 v[22:25], v175, s[50:51]
	ds_read_b128 v[180:183], v169
	ds_read_b128 v[184:187], v170
	s_waitcnt lgkmcnt(4)
	v_mfma_f32_16x16x32_fp8_fp8 v[200:203], v[188:189], v[134:135], 0
	v_mfma_f32_16x16x32_fp8_fp8 v[200:203], v[190:191], v[136:137], v[200:203]
	v_mfma_f32_16x16x32_fp8_fp8 v[200:203], v[192:193], v[138:139], v[200:203]
	v_mfma_f32_16x16x32_fp8_fp8 v[200:203], v[194:195], v[140:141], v[200:203]
	v_cndmask_b32_e64 v226, v196, v198, s[54:55]
	v_cndmask_b32_e64 v227, v197, v199, s[54:55]
	s_waitcnt vmcnt(16)
	ds_write_b128 v168, v[26:29]
	ds_write_b128 v168, v[30:33] offset:1024
	v_lshl_add_u32 v176, v156, 10, v166
	global_load_dwordx4 v[26:29], v176, s[50:51]
	v_lshl_add_u32 v177, v157, 10, v167
	global_load_dwordx4 v[30:33], v177, s[50:51]
	ds_read_b128 v[188:191], v169
	ds_read_b128 v[192:195], v170
	s_waitcnt lgkmcnt(4)
	v_mfma_f32_16x16x32_fp8_fp8 v[204:207], v[180:181], v[134:135], 0
	v_mfma_f32_16x16x32_fp8_fp8 v[204:207], v[182:183], v[136:137], v[204:207]
	v_mfma_f32_16x16x32_fp8_fp8 v[204:207], v[184:185], v[138:139], v[204:207]
	v_mfma_f32_16x16x32_fp8_fp8 v[204:207], v[186:187], v[140:141], v[204:207]
	v_cndmask_b32_e64 v228, v200, v202, s[54:55]
	v_cndmask_b32_e64 v229, v201, v203, s[54:55]
	v_cndmask_b32_e64 v230, v226, v228, s[56:57]
	v_cndmask_b32_e64 v231, v227, v229, s[56:57]
	s_waitcnt vmcnt(16)
	ds_write_b128 v168, v[34:37]
	ds_write_b128 v168, v[38:41] offset:1024
	v_lshl_add_u32 v174, v158, 10, v166
	global_load_dwordx4 v[34:37], v174, s[50:51]
	v_lshl_add_u32 v175, v159, 10, v167
	global_load_dwordx4 v[38:41], v175, s[50:51]
	ds_read_b128 v[180:183], v169
	ds_read_b128 v[184:187], v170
	s_waitcnt lgkmcnt(4)
	v_mfma_f32_16x16x32_fp8_fp8 v[216:219], v[188:189], v[134:135], 0
	v_mfma_f32_16x16x32_fp8_fp8 v[216:219], v[190:191], v[136:137], v[216:219]
	v_mfma_f32_16x16x32_fp8_fp8 v[216:219], v[192:193], v[138:139], v[216:219]
	v_mfma_f32_16x16x32_fp8_fp8 v[216:219], v[194:195], v[140:141], v[216:219]
	v_cndmask_b32_e64 v226, v204, v206, s[54:55]
	v_cndmask_b32_e64 v227, v205, v207, s[54:55]
	s_waitcnt vmcnt(16)
	ds_write_b128 v168, v[42:45]
	ds_write_b128 v168, v[46:49] offset:1024
	v_lshl_add_u32 v176, v160, 10, v166
	global_load_dwordx4 v[42:45], v176, s[50:51]
	v_lshl_add_u32 v177, v161, 10, v167
	global_load_dwordx4 v[46:49], v177, s[50:51]
	ds_read_b128 v[188:191], v169
	ds_read_b128 v[192:195], v170
	s_waitcnt lgkmcnt(4)
	v_mfma_f32_16x16x32_fp8_fp8 v[196:199], v[180:181], v[134:135], 0
	v_mfma_f32_16x16x32_fp8_fp8 v[196:199], v[182:183], v[136:137], v[196:199]
	v_mfma_f32_16x16x32_fp8_fp8 v[196:199], v[184:185], v[138:139], v[196:199]
	v_mfma_f32_16x16x32_fp8_fp8 v[196:199], v[186:187], v[140:141], v[196:199]
	v_cndmask_b32_e64 v228, v216, v218, s[54:55]
	v_cndmask_b32_e64 v229, v217, v219, s[54:55]
	v_cndmask_b32_e64 v232, v226, v228, s[56:57]
	v_cndmask_b32_e64 v233, v227, v229, s[56:57]
	s_waitcnt vmcnt(16)
	ds_write_b128 v168, v[50:53]
	ds_write_b128 v168, v[54:57] offset:1024
	v_lshl_add_u32 v174, v162, 10, v166
	global_load_dwordx4 v[50:53], v174, s[50:51]
	v_lshl_add_u32 v175, v163, 10, v167
	global_load_dwordx4 v[54:57], v175, s[50:51]
	ds_read_b128 v[180:183], v169
	ds_read_b128 v[184:187], v170
	s_waitcnt lgkmcnt(4)
	v_mfma_f32_16x16x32_fp8_fp8 v[200:203], v[188:189], v[134:135], 0
	v_mfma_f32_16x16x32_fp8_fp8 v[200:203], v[190:191], v[136:137], v[200:203]
	v_mfma_f32_16x16x32_fp8_fp8 v[200:203], v[192:193], v[138:139], v[200:203]
	v_mfma_f32_16x16x32_fp8_fp8 v[200:203], v[194:195], v[140:141], v[200:203]
	v_cndmask_b32_e64 v226, v196, v198, s[54:55]
	v_cndmask_b32_e64 v227, v197, v199, s[54:55]
	s_waitcnt vmcnt(16)
	ds_write_b128 v168, v[58:61]
	ds_write_b128 v168, v[62:65] offset:1024
	v_lshl_add_u32 v176, v164, 10, v166
	global_load_dwordx4 v[58:61], v176, s[50:51]
	v_lshl_add_u32 v177, v165, 10, v167
	global_load_dwordx4 v[62:65], v177, s[50:51]
	ds_read_b128 v[188:191], v169
	ds_read_b128 v[192:195], v170
	s_waitcnt lgkmcnt(4)
	v_mfma_f32_16x16x32_fp8_fp8 v[204:207], v[180:181], v[134:135], 0
	v_mfma_f32_16x16x32_fp8_fp8 v[204:207], v[182:183], v[136:137], v[204:207]
	v_mfma_f32_16x16x32_fp8_fp8 v[204:207], v[184:185], v[138:139], v[204:207]
	v_mfma_f32_16x16x32_fp8_fp8 v[204:207], v[186:187], v[140:141], v[204:207]
	v_cndmask_b32_e64 v228, v200, v202, s[54:55]
	v_cndmask_b32_e64 v229, v201, v203, s[54:55]
	v_cndmask_b32_e64 v234, v226, v228, s[56:57]
	v_cndmask_b32_e64 v235, v227, v229, s[56:57]
	s_waitcnt lgkmcnt(0)
	v_mfma_f32_16x16x32_fp8_fp8 v[216:219], v[188:189], v[134:135], 0
	v_mfma_f32_16x16x32_fp8_fp8 v[216:219], v[190:191], v[136:137], v[216:219]
	v_mfma_f32_16x16x32_fp8_fp8 v[216:219], v[192:193], v[138:139], v[216:219]
	v_mfma_f32_16x16x32_fp8_fp8 v[216:219], v[194:195], v[140:141], v[216:219]
	v_add_u32_e32 v0, 0, v172
	ds_read2_b32 v[150:151], v0 offset0:0 offset1:8
	ds_read2_b32 v[152:153], v0 offset0:16 offset1:24
	ds_read2_b32 v[154:155], v0 offset0:32 offset1:40
	ds_read2_b32 v[156:157], v0 offset0:48 offset1:56
	ds_read2_b32 v[158:159], v0 offset0:64 offset1:72
	ds_read2_b32 v[160:161], v0 offset0:80 offset1:88
	ds_read2_b32 v[162:163], v0 offset0:96 offset1:104
	ds_read2_b32 v[164:165], v0 offset0:112 offset1:120
	v_add_u32_e32 v171, s81, v171
	global_load_dwordx4 v[134:137], v171, s[52:53]
	global_load_dwordx4 v[138:141], v171, s[52:53] offset:16
	v_cndmask_b32_e64 v226, v204, v206, s[54:55]
	v_cndmask_b32_e64 v227, v205, v207, s[54:55]
	v_cndmask_b32_e64 v228, v216, v218, s[54:55]
	v_cndmask_b32_e64 v229, v217, v219, s[54:55]
	v_cndmask_b32_e64 v236, v226, v228, s[56:57]
	v_cndmask_b32_e64 v237, v227, v229, s[56:57]
	v_cndmask_b32_e64 v226, v230, v232, s[58:59]
	v_cndmask_b32_e64 v228, v234, v236, s[58:59]
	v_cndmask_b32_e64 v227, v231, v233, s[58:59]
	v_cndmask_b32_e64 v229, v235, v237, s[58:59]
	v_cndmask_b32_e64 v226, v226, v228, s[60:61]
	v_cndmask_b32_e64 v227, v227, v229, s[60:61]
	v_add_f32_e32 v66, v66, v226
	v_add_f32_e32 v67, v67, v227
	v_add_u32_e32 v166, 0x80, v166
	v_add_u32_e32 v167, 0x80, v167
	s_waitcnt vmcnt(16)
	ds_write_b128 v168, v[2:5]
	ds_write_b128 v168, v[6:9] offset:1024
	s_waitcnt lgkmcnt(2)
	v_lshl_add_u32 v174, v150, 10, v166
	global_load_dwordx4 v[2:5], v174, s[50:51]
	v_lshl_add_u32 v175, v151, 10, v167
	global_load_dwordx4 v[6:9], v175, s[50:51]
	ds_read_b128 v[180:183], v169
	ds_read_b128 v[184:187], v170
	s_waitcnt vmcnt(16)
	ds_write_b128 v168, v[10:13]
	ds_write_b128 v168, v[14:17] offset:1024
	v_lshl_add_u32 v176, v152, 10, v166
	global_load_dwordx4 v[10:13], v176, s[50:51]
	v_lshl_add_u32 v177, v153, 10, v167
	global_load_dwordx4 v[14:17], v177, s[50:51]
	ds_read_b128 v[188:191], v169
	ds_read_b128 v[192:195], v170
	s_waitcnt lgkmcnt(4)
	v_mfma_f32_16x16x32_fp8_fp8 v[196:199], v[180:181], v[142:143], 0
	v_mfma_f32_16x16x32_fp8_fp8 v[196:199], v[182:183], v[144:145], v[196:199]
	v_mfma_f32_16x16x32_fp8_fp8 v[196:199], v[184:185], v[146:147], v[196:199]
	v_mfma_f32_16x16x32_fp8_fp8 v[196:199], v[186:187], v[148:149], v[196:199]
	s_waitcnt vmcnt(16)
	ds_write_b128 v168, v[18:21]
	ds_write_b128 v168, v[22:25] offset:1024
	v_lshl_add_u32 v174, v154, 10, v166
	global_load_dwordx4 v[18:21], v174, s[50:51]
	v_lshl_add_u32 v175, v155, 10, v167
	global_load_dwordx4 v[22:25], v175, s[50:51]
	ds_read_b128 v[180:183], v169
	ds_read_b128 v[184:187], v170
	s_waitcnt lgkmcnt(4)
	v_mfma_f32_16x16x32_fp8_fp8 v[200:203], v[188:189], v[142:143], 0
	v_mfma_f32_16x16x32_fp8_fp8 v[200:203], v[190:191], v[144:145], v[200:203]
	v_mfma_f32_16x16x32_fp8_fp8 v[200:203], v[192:193], v[146:147], v[200:203]
	v_mfma_f32_16x16x32_fp8_fp8 v[200:203], v[194:195], v[148:149], v[200:203]
	v_cndmask_b32_e64 v226, v196, v198, s[54:55]
	v_cndmask_b32_e64 v227, v197, v199, s[54:55]
	s_waitcnt vmcnt(16)
	ds_write_b128 v168, v[26:29]
	ds_write_b128 v168, v[30:33] offset:1024
	v_lshl_add_u32 v176, v156, 10, v166
	global_load_dwordx4 v[26:29], v176, s[50:51]
	v_lshl_add_u32 v177, v157, 10, v167
	global_load_dwordx4 v[30:33], v177, s[50:51]
	ds_read_b128 v[188:191], v169
	ds_read_b128 v[192:195], v170
	s_waitcnt lgkmcnt(4)
	v_mfma_f32_16x16x32_fp8_fp8 v[204:207], v[180:181], v[142:143], 0
	v_mfma_f32_16x16x32_fp8_fp8 v[204:207], v[182:183], v[144:145], v[204:207]
	v_mfma_f32_16x16x32_fp8_fp8 v[204:207], v[184:185], v[146:147], v[204:207]
	v_mfma_f32_16x16x32_fp8_fp8 v[204:207], v[186:187], v[148:149], v[204:207]
	v_cndmask_b32_e64 v228, v200, v202, s[54:55]
	v_cndmask_b32_e64 v229, v201, v203, s[54:55]
	v_cndmask_b32_e64 v230, v226, v228, s[56:57]
	v_cndmask_b32_e64 v231, v227, v229, s[56:57]
	s_waitcnt vmcnt(16)
	ds_write_b128 v168, v[34:37]
	ds_write_b128 v168, v[38:41] offset:1024
	v_lshl_add_u32 v174, v158, 10, v166
	global_load_dwordx4 v[34:37], v174, s[50:51]
	v_lshl_add_u32 v175, v159, 10, v167
	global_load_dwordx4 v[38:41], v175, s[50:51]
	ds_read_b128 v[180:183], v169
	ds_read_b128 v[184:187], v170
	s_waitcnt lgkmcnt(4)
	v_mfma_f32_16x16x32_fp8_fp8 v[216:219], v[188:189], v[142:143], 0
	v_mfma_f32_16x16x32_fp8_fp8 v[216:219], v[190:191], v[144:145], v[216:219]
	v_mfma_f32_16x16x32_fp8_fp8 v[216:219], v[192:193], v[146:147], v[216:219]
	v_mfma_f32_16x16x32_fp8_fp8 v[216:219], v[194:195], v[148:149], v[216:219]
	v_cndmask_b32_e64 v226, v204, v206, s[54:55]
	v_cndmask_b32_e64 v227, v205, v207, s[54:55]
	s_waitcnt vmcnt(16)
	ds_write_b128 v168, v[42:45]
	ds_write_b128 v168, v[46:49] offset:1024
	v_lshl_add_u32 v176, v160, 10, v166
	global_load_dwordx4 v[42:45], v176, s[50:51]
	v_lshl_add_u32 v177, v161, 10, v167
	global_load_dwordx4 v[46:49], v177, s[50:51]
	ds_read_b128 v[188:191], v169
	ds_read_b128 v[192:195], v170
	s_waitcnt lgkmcnt(4)
	v_mfma_f32_16x16x32_fp8_fp8 v[196:199], v[180:181], v[142:143], 0
	v_mfma_f32_16x16x32_fp8_fp8 v[196:199], v[182:183], v[144:145], v[196:199]
	v_mfma_f32_16x16x32_fp8_fp8 v[196:199], v[184:185], v[146:147], v[196:199]
	v_mfma_f32_16x16x32_fp8_fp8 v[196:199], v[186:187], v[148:149], v[196:199]
	v_cndmask_b32_e64 v228, v216, v218, s[54:55]
	v_cndmask_b32_e64 v229, v217, v219, s[54:55]
	v_cndmask_b32_e64 v232, v226, v228, s[56:57]
	v_cndmask_b32_e64 v233, v227, v229, s[56:57]
	s_waitcnt vmcnt(16)
	ds_write_b128 v168, v[50:53]
	ds_write_b128 v168, v[54:57] offset:1024
	v_lshl_add_u32 v174, v162, 10, v166
	global_load_dwordx4 v[50:53], v174, s[50:51]
	v_lshl_add_u32 v175, v163, 10, v167
	global_load_dwordx4 v[54:57], v175, s[50:51]
	ds_read_b128 v[180:183], v169
	ds_read_b128 v[184:187], v170
	s_waitcnt lgkmcnt(4)
	v_mfma_f32_16x16x32_fp8_fp8 v[200:203], v[188:189], v[142:143], 0
	v_mfma_f32_16x16x32_fp8_fp8 v[200:203], v[190:191], v[144:145], v[200:203]
	v_mfma_f32_16x16x32_fp8_fp8 v[200:203], v[192:193], v[146:147], v[200:203]
	v_mfma_f32_16x16x32_fp8_fp8 v[200:203], v[194:195], v[148:149], v[200:203]
	v_cndmask_b32_e64 v226, v196, v198, s[54:55]
	v_cndmask_b32_e64 v227, v197, v199, s[54:55]
	s_waitcnt vmcnt(16)
	ds_write_b128 v168, v[58:61]
	ds_write_b128 v168, v[62:65] offset:1024
	v_lshl_add_u32 v176, v164, 10, v166
	global_load_dwordx4 v[58:61], v176, s[50:51]
	v_lshl_add_u32 v177, v165, 10, v167
	global_load_dwordx4 v[62:65], v177, s[50:51]
	ds_read_b128 v[188:191], v169
	ds_read_b128 v[192:195], v170
	s_waitcnt lgkmcnt(4)
	v_mfma_f32_16x16x32_fp8_fp8 v[204:207], v[180:181], v[142:143], 0
	v_mfma_f32_16x16x32_fp8_fp8 v[204:207], v[182:183], v[144:145], v[204:207]
	v_mfma_f32_16x16x32_fp8_fp8 v[204:207], v[184:185], v[146:147], v[204:207]
	v_mfma_f32_16x16x32_fp8_fp8 v[204:207], v[186:187], v[148:149], v[204:207]
	v_cndmask_b32_e64 v228, v200, v202, s[54:55]
	v_cndmask_b32_e64 v229, v201, v203, s[54:55]
	v_cndmask_b32_e64 v234, v226, v228, s[56:57]
	v_cndmask_b32_e64 v235, v227, v229, s[56:57]
	s_waitcnt lgkmcnt(0)
	v_mfma_f32_16x16x32_fp8_fp8 v[216:219], v[188:189], v[142:143], 0
	v_mfma_f32_16x16x32_fp8_fp8 v[216:219], v[190:191], v[144:145], v[216:219]
	v_mfma_f32_16x16x32_fp8_fp8 v[216:219], v[192:193], v[146:147], v[216:219]
	v_mfma_f32_16x16x32_fp8_fp8 v[216:219], v[194:195], v[148:149], v[216:219]
	v_add_u32_e32 v0, 512, v172
	ds_read2_b32 v[150:151], v0 offset0:0 offset1:8
	ds_read2_b32 v[152:153], v0 offset0:16 offset1:24
	ds_read2_b32 v[154:155], v0 offset0:32 offset1:40
	ds_read2_b32 v[156:157], v0 offset0:48 offset1:56
	ds_read2_b32 v[158:159], v0 offset0:64 offset1:72
	ds_read2_b32 v[160:161], v0 offset0:80 offset1:88
	ds_read2_b32 v[162:163], v0 offset0:96 offset1:104
	ds_read2_b32 v[164:165], v0 offset0:112 offset1:120
	v_add_u32_e32 v171, s80, v171
	global_load_dwordx4 v[142:145], v171, s[52:53]
	global_load_dwordx4 v[146:149], v171, s[52:53] offset:16
	v_cndmask_b32_e64 v226, v204, v206, s[54:55]
	v_cndmask_b32_e64 v227, v205, v207, s[54:55]
	v_cndmask_b32_e64 v228, v216, v218, s[54:55]
	v_cndmask_b32_e64 v229, v217, v219, s[54:55]
	v_cndmask_b32_e64 v236, v226, v228, s[56:57]
	v_cndmask_b32_e64 v237, v227, v229, s[56:57]
	v_cndmask_b32_e64 v226, v230, v232, s[58:59]
	v_cndmask_b32_e64 v228, v234, v236, s[58:59]
	v_cndmask_b32_e64 v227, v231, v233, s[58:59]
	v_cndmask_b32_e64 v229, v235, v237, s[58:59]
	v_cndmask_b32_e64 v226, v226, v228, s[60:61]
	v_cndmask_b32_e64 v227, v227, v229, s[60:61]
	v_add_f32_e32 v68, v68, v226
	v_add_f32_e32 v69, v69, v227
	s_add_i32 s49, s49, 1
	s_cmp_lt_u32 s49, 8
	s_cbranch_scc1 .Lu_cloop
	s_waitcnt vmcnt(0)
	v_lshrrev_b32_e32 v202, 1, v209
	v_lshlrev_b32_e32 v202, 4, v202
	v_lshl_add_u32 v202, v103, 2, v202
	v_and_b32_e32 v203, 1, v209
	v_lshl_add_u32 v202, v203, 1, v202
	v_lshlrev_b32_e32 v196, 2, v202
	v_lshrrev_b32_e32 v203, 6, v179
	v_mul_u32_u24_e32 v203, 0x3000, v203
	v_add_u32_e32 v198, v203, v196
	v_lshl_add_u32 v197, v202, 3, v203
	ds_read_b64 v[2:3], v198 offset:0
	ds_read_b64 v[4:5], v198 offset:512
	ds_read_b64 v[6:7], v198 offset:1024
	ds_read_b64 v[8:9], v198 offset:1536
	ds_read_b64 v[10:11], v198 offset:2048
	ds_read_b64 v[12:13], v198 offset:2560
	ds_read_b64 v[14:15], v198 offset:3072
	ds_read_b64 v[16:17], v198 offset:3584
	ds_read_b64 v[18:19], v198 offset:4096
	ds_read_b64 v[20:21], v198 offset:4608
	ds_read_b64 v[22:23], v198 offset:5120
	ds_read_b64 v[24:25], v198 offset:5632
	v_readfirstlane_b32 s20, v78
	v_readfirstlane_b32 s21, v79
	s_mov_b32 s8, 0x378e98ab
	s_mov_b32 s9, 0x3b7cd369
	s_mov_b32 s13, 0xbcc618b2
	s_mov_b32 s32, 0x3dda74e4
	s_mov_b32 s38, 0x3f228afd
	s_mov_b32 s49, 0x3e03c728
	s_mov_b32 s50, 0x42ce8ed0
	s_mov_b32 s51, 0xc2b17218
	v_mov_b32_e32 v199, v70
	s_waitcnt lgkmcnt(0)
	v_lshlrev_b32_e32 v202, 2, v199
	global_load_dword v26, v202, s[42:43]
	v_lshl_add_u32 v203, v199, 9, v196
	global_load_dwordx2 v[28:29], v203, s[20:21]
	v_lshlrev_b32_e32 v200, 2, v2
	v_lshlrev_b32_e32 v201, 2, v3
	global_load_dword v30, v200, s[6:7]
	global_load_dword v31, v201, s[6:7]
	global_load_dword v32, v200, s[22:23]
	global_load_dword v33, v201, s[22:23]
	v_add_u32_e32 v199, s30, v199
	v_lshlrev_b32_e32 v202, 2, v199
	global_load_dword v34, v202, s[42:43]
	v_lshl_add_u32 v203, v199, 9, v196
	global_load_dwordx2 v[36:37], v203, s[20:21]
	v_lshlrev_b32_e32 v200, 2, v4
	v_lshlrev_b32_e32 v201, 2, v5
	global_load_dword v38, v200, s[6:7]
	global_load_dword v39, v201, s[6:7]
	global_load_dword v40, v200, s[22:23]
	global_load_dword v41, v201, s[22:23]
	v_add_u32_e32 v199, s30, v199
	v_lshlrev_b32_e32 v202, 2, v199
	global_load_dword v42, v202, s[42:43]
	v_lshl_add_u32 v203, v199, 9, v196
	global_load_dwordx2 v[44:45], v203, s[20:21]
	v_lshlrev_b32_e32 v200, 2, v6
	v_lshlrev_b32_e32 v201, 2, v7
	global_load_dword v46, v200, s[6:7]
	global_load_dword v47, v201, s[6:7]
	global_load_dword v48, v200, s[22:23]
	global_load_dword v49, v201, s[22:23]
	v_add_u32_e32 v199, s30, v199
	v_lshlrev_b32_e32 v202, 2, v199
	global_load_dword v50, v202, s[42:43]
	v_lshl_add_u32 v203, v199, 9, v196
	global_load_dwordx2 v[52:53], v203, s[20:21]
	v_lshlrev_b32_e32 v200, 2, v8
	v_lshlrev_b32_e32 v201, 2, v9
	global_load_dword v54, v200, s[6:7]
	global_load_dword v55, v201, s[6:7]
	global_load_dword v56, v200, s[22:23]
	global_load_dword v57, v201, s[22:23]
	v_add_u32_e32 v199, s30, v199
	v_lshlrev_b32_e32 v202, 2, v199
	global_load_dword v58, v202, s[42:43]
	v_lshl_add_u32 v203, v199, 9, v196
	global_load_dwordx2 v[60:61], v203, s[20:21]
	v_lshlrev_b32_e32 v200, 2, v10
	v_lshlrev_b32_e32 v201, 2, v11
	global_load_dword v62, v200, s[6:7]
	global_load_dword v63, v201, s[6:7]
	global_load_dword v64, v200, s[22:23]
	global_load_dword v65, v201, s[22:23]
	v_add_u32_e32 v199, s30, v199
	v_lshlrev_b32_e32 v202, 2, v199
	global_load_dword v134, v202, s[42:43]
	v_lshl_add_u32 v203, v199, 9, v196
	global_load_dwordx2 v[136:137], v203, s[20:21]
	v_lshlrev_b32_e32 v200, 2, v12
	v_lshlrev_b32_e32 v201, 2, v13
	global_load_dword v138, v200, s[6:7]
	global_load_dword v139, v201, s[6:7]
	global_load_dword v140, v200, s[22:23]
	global_load_dword v141, v201, s[22:23]
	v_add_u32_e32 v199, s30, v199
	v_lshlrev_b32_e32 v202, 2, v199
	global_load_dword v142, v202, s[42:43]
	v_lshl_add_u32 v203, v199, 9, v196
	global_load_dwordx2 v[144:145], v203, s[20:21]
	v_lshlrev_b32_e32 v200, 2, v14
	v_lshlrev_b32_e32 v201, 2, v15
	global_load_dword v146, v200, s[6:7]
	global_load_dword v147, v201, s[6:7]
	global_load_dword v148, v200, s[22:23]
	global_load_dword v149, v201, s[22:23]
	v_add_u32_e32 v199, s30, v199
	v_lshlrev_b32_e32 v202, 2, v199
	global_load_dword v150, v202, s[42:43]
	v_lshl_add_u32 v203, v199, 9, v196
	global_load_dwordx2 v[152:153], v203, s[20:21]
	v_lshlrev_b32_e32 v200, 2, v16
	v_lshlrev_b32_e32 v201, 2, v17
	global_load_dword v154, v200, s[6:7]
	global_load_dword v155, v201, s[6:7]
	global_load_dword v156, v200, s[22:23]
	global_load_dword v157, v201, s[22:23]
	v_add_u32_e32 v199, s30, v199
	s_waitcnt vmcnt(42)
	v_mov_b32_e32 v204, v2
	v_mov_b32_e32 v206, v3
	v_mul_f32_e32 v229, v242, v26
	v_mul_f32_e32 v229, v229, v30
	v_mul_f32_e32 v216, 0x3f3504f3, v229
	v_fma_f32 v217, |v216|, s8, v223
	v_fma_f32 v217, |v216|, v217, s9
	v_fma_f32 v217, |v216|, v217, s13
	v_fma_f32 v217, |v216|, v217, s32
	v_fma_f32 v217, |v216|, v217, s38
	v_fma_f32 v217, |v216|, v217, s49
	v_fma_f32 v217, |v216|, v217, |v216|
	v_mul_f32_e32 v218, 0xbfb8aa3b, v217
	v_fma_f32 v219, v217, s27, -v218
	v_rndne_f32_e32 v226, v218
	v_fmac_f32_e32 v219, 0xb2a5705f, v217
	v_sub_f32_e32 v218, v218, v226
	v_add_f32_e32 v218, v218, v219
	v_cvt_i32_f32_e32 v219, v226
	v_exp_f32_e32 v218, v218
	v_cmp_nlt_f32_e32 vcc, s50, v217
	v_mul_f32_e32 v227, v216, v216
	v_ldexp_f32 v218, v218, v219
	v_fmamk_f32 v228, v227, 0xba1345e1, v212
	v_cndmask_b32_e32 v218, 0, v218, vcc
	v_cmp_ngt_f32_e32 vcc, s51, v217
	v_fmaak_f32 v228, v227, v228, 0xbcdac9b8
	v_fmaak_f32 v228, v227, v228, 0x3de703be
	v_cndmask_b32_e32 v217, v224, v218, vcc
	v_fmaak_f32 v228, v227, v228, 0xbec09330
	v_sub_f32_e32 v217, 1.0, v217
	v_fmaak_f32 v227, v227, v228, 0x3e0375d0
	v_cmp_nlt_f32_e64 vcc, |v216|, 1.0
	v_fma_f32 v227, |v216|, v227, |v216|
	v_mul_f32_e32 v229, 0.5, v229
	v_cndmask_b32_e32 v217, v227, v217, vcc
	v_bfi_b32 v217, s78, v217, v216
	v_add_f32_e32 v217, 1.0, v217
	v_mul_f32_e32 v229, v229, v217
	v_mul_f32_e32 v229, v28, v229
	v_mul_f32_e32 v205, v32, v229
	v_mul_f32_e32 v229, v243, v26
	v_mul_f32_e32 v229, v229, v31
	v_mul_f32_e32 v216, 0x3f3504f3, v229
	v_fma_f32 v217, |v216|, s8, v223
	v_fma_f32 v217, |v216|, v217, s9
	v_fma_f32 v217, |v216|, v217, s13
	v_fma_f32 v217, |v216|, v217, s32
	v_fma_f32 v217, |v216|, v217, s38
	v_fma_f32 v217, |v216|, v217, s49
	v_fma_f32 v217, |v216|, v217, |v216|
	v_mul_f32_e32 v218, 0xbfb8aa3b, v217
	v_fma_f32 v219, v217, s27, -v218
	v_rndne_f32_e32 v226, v218
	v_fmac_f32_e32 v219, 0xb2a5705f, v217
	v_sub_f32_e32 v218, v218, v226
	v_add_f32_e32 v218, v218, v219
	v_cvt_i32_f32_e32 v219, v226
	v_exp_f32_e32 v218, v218
	v_cmp_nlt_f32_e32 vcc, s50, v217
	v_mul_f32_e32 v227, v216, v216
	v_ldexp_f32 v218, v218, v219
	v_fmamk_f32 v228, v227, 0xba1345e1, v212
	v_cndmask_b32_e32 v218, 0, v218, vcc
	v_cmp_ngt_f32_e32 vcc, s51, v217
	v_fmaak_f32 v228, v227, v228, 0xbcdac9b8
	v_fmaak_f32 v228, v227, v228, 0x3de703be
	v_cndmask_b32_e32 v217, v224, v218, vcc
	v_fmaak_f32 v228, v227, v228, 0xbec09330
	v_sub_f32_e32 v217, 1.0, v217
	v_fmaak_f32 v227, v227, v228, 0x3e0375d0
	v_cmp_nlt_f32_e64 vcc, |v216|, 1.0
	v_fma_f32 v227, |v216|, v227, |v216|
	v_mul_f32_e32 v229, 0.5, v229
	v_cndmask_b32_e32 v217, v227, v217, vcc
	v_bfi_b32 v217, s78, v217, v216
	v_add_f32_e32 v217, 1.0, v217
	v_mul_f32_e32 v229, v229, v217
	v_mul_f32_e32 v229, v29, v229
	v_mul_f32_e32 v207, v33, v229
	ds_write_b128 v197, v[204:207] offset:0
	v_lshlrev_b32_e32 v202, 2, v199
	global_load_dword v158, v202, s[42:43]
	v_lshl_add_u32 v203, v199, 9, v196
	global_load_dwordx2 v[160:161], v203, s[20:21]
	v_lshlrev_b32_e32 v200, 2, v18
	v_lshlrev_b32_e32 v201, 2, v19
	global_load_dword v162, v200, s[6:7]
	global_load_dword v163, v201, s[6:7]
	global_load_dword v164, v200, s[22:23]
	global_load_dword v165, v201, s[22:23]
	v_add_u32_e32 v199, s30, v199
	s_waitcnt vmcnt(42)
	v_mov_b32_e32 v204, v4
	v_mov_b32_e32 v206, v5
	v_mul_f32_e32 v229, v244, v34
	v_mul_f32_e32 v229, v229, v38
	v_mul_f32_e32 v216, 0x3f3504f3, v229
	v_fma_f32 v217, |v216|, s8, v223
	v_fma_f32 v217, |v216|, v217, s9
	v_fma_f32 v217, |v216|, v217, s13
	v_fma_f32 v217, |v216|, v217, s32
	v_fma_f32 v217, |v216|, v217, s38
	v_fma_f32 v217, |v216|, v217, s49
	v_fma_f32 v217, |v216|, v217, |v216|
	v_mul_f32_e32 v218, 0xbfb8aa3b, v217
	v_fma_f32 v219, v217, s27, -v218
	v_rndne_f32_e32 v226, v218
	v_fmac_f32_e32 v219, 0xb2a5705f, v217
	v_sub_f32_e32 v218, v218, v226
	v_add_f32_e32 v218, v218, v219
	v_cvt_i32_f32_e32 v219, v226
	v_exp_f32_e32 v218, v218
	v_cmp_nlt_f32_e32 vcc, s50, v217
	v_mul_f32_e32 v227, v216, v216
	v_ldexp_f32 v218, v218, v219
	v_fmamk_f32 v228, v227, 0xba1345e1, v212
	v_cndmask_b32_e32 v218, 0, v218, vcc
	v_cmp_ngt_f32_e32 vcc, s51, v217
	v_fmaak_f32 v228, v227, v228, 0xbcdac9b8
	v_fmaak_f32 v228, v227, v228, 0x3de703be
	v_cndmask_b32_e32 v217, v224, v218, vcc
	v_fmaak_f32 v228, v227, v228, 0xbec09330
	v_sub_f32_e32 v217, 1.0, v217
	v_fmaak_f32 v227, v227, v228, 0x3e0375d0
	v_cmp_nlt_f32_e64 vcc, |v216|, 1.0
	v_fma_f32 v227, |v216|, v227, |v216|
	v_mul_f32_e32 v229, 0.5, v229
	v_cndmask_b32_e32 v217, v227, v217, vcc
	v_bfi_b32 v217, s78, v217, v216
	v_add_f32_e32 v217, 1.0, v217
	v_mul_f32_e32 v229, v229, v217
	v_mul_f32_e32 v229, v36, v229
	v_mul_f32_e32 v205, v40, v229
	v_mul_f32_e32 v229, v245, v34
	v_mul_f32_e32 v229, v229, v39
	v_mul_f32_e32 v216, 0x3f3504f3, v229
	v_fma_f32 v217, |v216|, s8, v223
	v_fma_f32 v217, |v216|, v217, s9
	v_fma_f32 v217, |v216|, v217, s13
	v_fma_f32 v217, |v216|, v217, s32
	v_fma_f32 v217, |v216|, v217, s38
	v_fma_f32 v217, |v216|, v217, s49
	v_fma_f32 v217, |v216|, v217, |v216|
	v_mul_f32_e32 v218, 0xbfb8aa3b, v217
	v_fma_f32 v219, v217, s27, -v218
	v_rndne_f32_e32 v226, v218
	v_fmac_f32_e32 v219, 0xb2a5705f, v217
	v_sub_f32_e32 v218, v218, v226
	v_add_f32_e32 v218, v218, v219
	v_cvt_i32_f32_e32 v219, v226
	v_exp_f32_e32 v218, v218
	v_cmp_nlt_f32_e32 vcc, s50, v217
	v_mul_f32_e32 v227, v216, v216
	v_ldexp_f32 v218, v218, v219
	v_fmamk_f32 v228, v227, 0xba1345e1, v212
	v_cndmask_b32_e32 v218, 0, v218, vcc
	v_cmp_ngt_f32_e32 vcc, s51, v217
	v_fmaak_f32 v228, v227, v228, 0xbcdac9b8
	v_fmaak_f32 v228, v227, v228, 0x3de703be
	v_cndmask_b32_e32 v217, v224, v218, vcc
	v_fmaak_f32 v228, v227, v228, 0xbec09330
	v_sub_f32_e32 v217, 1.0, v217
	v_fmaak_f32 v227, v227, v228, 0x3e0375d0
	v_cmp_nlt_f32_e64 vcc, |v216|, 1.0
	v_fma_f32 v227, |v216|, v227, |v216|
	v_mul_f32_e32 v229, 0.5, v229
	v_cndmask_b32_e32 v217, v227, v217, vcc
	v_bfi_b32 v217, s78, v217, v216
	v_add_f32_e32 v217, 1.0, v217
	v_mul_f32_e32 v229, v229, v217
	v_mul_f32_e32 v229, v37, v229
	v_mul_f32_e32 v207, v41, v229
	ds_write_b128 v197, v[204:207] offset:1024
	v_lshlrev_b32_e32 v202, 2, v199
	global_load_dword v166, v202, s[42:43]
	v_lshl_add_u32 v203, v199, 9, v196
	global_load_dwordx2 v[168:169], v203, s[20:21]
	v_lshlrev_b32_e32 v200, 2, v20
	v_lshlrev_b32_e32 v201, 2, v21
	global_load_dword v170, v200, s[6:7]
	global_load_dword v171, v201, s[6:7]
	global_load_dword v172, v200, s[22:23]
	global_load_dword v173, v201, s[22:23]
	v_add_u32_e32 v199, s30, v199
	s_waitcnt vmcnt(42)
	v_mov_b32_e32 v204, v6
	v_mov_b32_e32 v206, v7
	v_mul_f32_e32 v229, v246, v42
	v_mul_f32_e32 v229, v229, v46
	v_mul_f32_e32 v216, 0x3f3504f3, v229
	v_fma_f32 v217, |v216|, s8, v223
	v_fma_f32 v217, |v216|, v217, s9
	v_fma_f32 v217, |v216|, v217, s13
	v_fma_f32 v217, |v216|, v217, s32
	v_fma_f32 v217, |v216|, v217, s38
	v_fma_f32 v217, |v216|, v217, s49
	v_fma_f32 v217, |v216|, v217, |v216|
	v_mul_f32_e32 v218, 0xbfb8aa3b, v217
	v_fma_f32 v219, v217, s27, -v218
	v_rndne_f32_e32 v226, v218
	v_fmac_f32_e32 v219, 0xb2a5705f, v217
	v_sub_f32_e32 v218, v218, v226
	v_add_f32_e32 v218, v218, v219
	v_cvt_i32_f32_e32 v219, v226
	v_exp_f32_e32 v218, v218
	v_cmp_nlt_f32_e32 vcc, s50, v217
	v_mul_f32_e32 v227, v216, v216
	v_ldexp_f32 v218, v218, v219
	v_fmamk_f32 v228, v227, 0xba1345e1, v212
	v_cndmask_b32_e32 v218, 0, v218, vcc
	v_cmp_ngt_f32_e32 vcc, s51, v217
	v_fmaak_f32 v228, v227, v228, 0xbcdac9b8
	v_fmaak_f32 v228, v227, v228, 0x3de703be
	v_cndmask_b32_e32 v217, v224, v218, vcc
	v_fmaak_f32 v228, v227, v228, 0xbec09330
	v_sub_f32_e32 v217, 1.0, v217
	v_fmaak_f32 v227, v227, v228, 0x3e0375d0
	v_cmp_nlt_f32_e64 vcc, |v216|, 1.0
	v_fma_f32 v227, |v216|, v227, |v216|
	v_mul_f32_e32 v229, 0.5, v229
	v_cndmask_b32_e32 v217, v227, v217, vcc
	v_bfi_b32 v217, s78, v217, v216
	v_add_f32_e32 v217, 1.0, v217
	v_mul_f32_e32 v229, v229, v217
	v_mul_f32_e32 v229, v44, v229
	v_mul_f32_e32 v205, v48, v229
	v_mul_f32_e32 v229, v247, v42
	v_mul_f32_e32 v229, v229, v47
	v_mul_f32_e32 v216, 0x3f3504f3, v229
	v_fma_f32 v217, |v216|, s8, v223
	v_fma_f32 v217, |v216|, v217, s9
	v_fma_f32 v217, |v216|, v217, s13
	v_fma_f32 v217, |v216|, v217, s32
	v_fma_f32 v217, |v216|, v217, s38
	v_fma_f32 v217, |v216|, v217, s49
	v_fma_f32 v217, |v216|, v217, |v216|
	v_mul_f32_e32 v218, 0xbfb8aa3b, v217
	v_fma_f32 v219, v217, s27, -v218
	v_rndne_f32_e32 v226, v218
	v_fmac_f32_e32 v219, 0xb2a5705f, v217
	v_sub_f32_e32 v218, v218, v226
	v_add_f32_e32 v218, v218, v219
	v_cvt_i32_f32_e32 v219, v226
	v_exp_f32_e32 v218, v218
	v_cmp_nlt_f32_e32 vcc, s50, v217
	v_mul_f32_e32 v227, v216, v216
	v_ldexp_f32 v218, v218, v219
	v_fmamk_f32 v228, v227, 0xba1345e1, v212
	v_cndmask_b32_e32 v218, 0, v218, vcc
	v_cmp_ngt_f32_e32 vcc, s51, v217
	v_fmaak_f32 v228, v227, v228, 0xbcdac9b8
	v_fmaak_f32 v228, v227, v228, 0x3de703be
	v_cndmask_b32_e32 v217, v224, v218, vcc
	v_fmaak_f32 v228, v227, v228, 0xbec09330
	v_sub_f32_e32 v217, 1.0, v217
	v_fmaak_f32 v227, v227, v228, 0x3e0375d0
	v_cmp_nlt_f32_e64 vcc, |v216|, 1.0
	v_fma_f32 v227, |v216|, v227, |v216|
	v_mul_f32_e32 v229, 0.5, v229
	v_cndmask_b32_e32 v217, v227, v217, vcc
	v_bfi_b32 v217, s78, v217, v216
	v_add_f32_e32 v217, 1.0, v217
	v_mul_f32_e32 v229, v229, v217
	v_mul_f32_e32 v229, v45, v229
	v_mul_f32_e32 v207, v49, v229
	ds_write_b128 v197, v[204:207] offset:2048
	v_lshlrev_b32_e32 v202, 2, v199
	global_load_dword v180, v202, s[42:43]
	v_lshl_add_u32 v203, v199, 9, v196
	global_load_dwordx2 v[182:183], v203, s[20:21]
	v_lshlrev_b32_e32 v200, 2, v22
	v_lshlrev_b32_e32 v201, 2, v23
	global_load_dword v184, v200, s[6:7]
	global_load_dword v185, v201, s[6:7]
	global_load_dword v186, v200, s[22:23]
	global_load_dword v187, v201, s[22:23]
	v_add_u32_e32 v199, s30, v199
	s_waitcnt vmcnt(42)
	v_mov_b32_e32 v204, v8
	v_mov_b32_e32 v206, v9
	v_mul_f32_e32 v229, v248, v50
	v_mul_f32_e32 v229, v229, v54
	v_mul_f32_e32 v216, 0x3f3504f3, v229
	v_fma_f32 v217, |v216|, s8, v223
	v_fma_f32 v217, |v216|, v217, s9
	v_fma_f32 v217, |v216|, v217, s13
	v_fma_f32 v217, |v216|, v217, s32
	v_fma_f32 v217, |v216|, v217, s38
	v_fma_f32 v217, |v216|, v217, s49
	v_fma_f32 v217, |v216|, v217, |v216|
	v_mul_f32_e32 v218, 0xbfb8aa3b, v217
	v_fma_f32 v219, v217, s27, -v218
	v_rndne_f32_e32 v226, v218
	v_fmac_f32_e32 v219, 0xb2a5705f, v217
	v_sub_f32_e32 v218, v218, v226
	v_add_f32_e32 v218, v218, v219
	v_cvt_i32_f32_e32 v219, v226
	v_exp_f32_e32 v218, v218
	v_cmp_nlt_f32_e32 vcc, s50, v217
	v_mul_f32_e32 v227, v216, v216
	v_ldexp_f32 v218, v218, v219
	v_fmamk_f32 v228, v227, 0xba1345e1, v212
	v_cndmask_b32_e32 v218, 0, v218, vcc
	v_cmp_ngt_f32_e32 vcc, s51, v217
	v_fmaak_f32 v228, v227, v228, 0xbcdac9b8
	v_fmaak_f32 v228, v227, v228, 0x3de703be
	v_cndmask_b32_e32 v217, v224, v218, vcc
	v_fmaak_f32 v228, v227, v228, 0xbec09330
	v_sub_f32_e32 v217, 1.0, v217
	v_fmaak_f32 v227, v227, v228, 0x3e0375d0
	v_cmp_nlt_f32_e64 vcc, |v216|, 1.0
	v_fma_f32 v227, |v216|, v227, |v216|
	v_mul_f32_e32 v229, 0.5, v229
	v_cndmask_b32_e32 v217, v227, v217, vcc
	v_bfi_b32 v217, s78, v217, v216
	v_add_f32_e32 v217, 1.0, v217
	v_mul_f32_e32 v229, v229, v217
	v_mul_f32_e32 v229, v52, v229
	v_mul_f32_e32 v205, v56, v229
	v_mul_f32_e32 v229, v249, v50
	v_mul_f32_e32 v229, v229, v55
	v_mul_f32_e32 v216, 0x3f3504f3, v229
	v_fma_f32 v217, |v216|, s8, v223
	v_fma_f32 v217, |v216|, v217, s9
	v_fma_f32 v217, |v216|, v217, s13
	v_fma_f32 v217, |v216|, v217, s32
	v_fma_f32 v217, |v216|, v217, s38
	v_fma_f32 v217, |v216|, v217, s49
	v_fma_f32 v217, |v216|, v217, |v216|
	v_mul_f32_e32 v218, 0xbfb8aa3b, v217
	v_fma_f32 v219, v217, s27, -v218
	v_rndne_f32_e32 v226, v218
	v_fmac_f32_e32 v219, 0xb2a5705f, v217
	v_sub_f32_e32 v218, v218, v226
	v_add_f32_e32 v218, v218, v219
	v_cvt_i32_f32_e32 v219, v226
	v_exp_f32_e32 v218, v218
	v_cmp_nlt_f32_e32 vcc, s50, v217
	v_mul_f32_e32 v227, v216, v216
	v_ldexp_f32 v218, v218, v219
	v_fmamk_f32 v228, v227, 0xba1345e1, v212
	v_cndmask_b32_e32 v218, 0, v218, vcc
	v_cmp_ngt_f32_e32 vcc, s51, v217
	v_fmaak_f32 v228, v227, v228, 0xbcdac9b8
	v_fmaak_f32 v228, v227, v228, 0x3de703be
	v_cndmask_b32_e32 v217, v224, v218, vcc
	v_fmaak_f32 v228, v227, v228, 0xbec09330
	v_sub_f32_e32 v217, 1.0, v217
	v_fmaak_f32 v227, v227, v228, 0x3e0375d0
	v_cmp_nlt_f32_e64 vcc, |v216|, 1.0
	v_fma_f32 v227, |v216|, v227, |v216|
	v_mul_f32_e32 v229, 0.5, v229
	v_cndmask_b32_e32 v217, v227, v217, vcc
	v_bfi_b32 v217, s78, v217, v216
	v_add_f32_e32 v217, 1.0, v217
	v_mul_f32_e32 v229, v229, v217
	v_mul_f32_e32 v229, v53, v229
	v_mul_f32_e32 v207, v57, v229
	ds_write_b128 v197, v[204:207] offset:3072
	v_lshlrev_b32_e32 v202, 2, v199
	global_load_dword v188, v202, s[42:43]
	v_lshl_add_u32 v203, v199, 9, v196
	global_load_dwordx2 v[190:191], v203, s[20:21]
	v_lshlrev_b32_e32 v200, 2, v24
	v_lshlrev_b32_e32 v201, 2, v25
	global_load_dword v192, v200, s[6:7]
	global_load_dword v193, v201, s[6:7]
	global_load_dword v194, v200, s[22:23]
	global_load_dword v195, v201, s[22:23]
	v_add_u32_e32 v199, s30, v199
	s_waitcnt vmcnt(42)
	v_mov_b32_e32 v204, v10
	v_mov_b32_e32 v206, v11
	v_mul_f32_e32 v229, v238, v58
	v_mul_f32_e32 v229, v229, v62
	v_mul_f32_e32 v216, 0x3f3504f3, v229
	v_fma_f32 v217, |v216|, s8, v223
	v_fma_f32 v217, |v216|, v217, s9
	v_fma_f32 v217, |v216|, v217, s13
	v_fma_f32 v217, |v216|, v217, s32
	v_fma_f32 v217, |v216|, v217, s38
	v_fma_f32 v217, |v216|, v217, s49
	v_fma_f32 v217, |v216|, v217, |v216|
	v_mul_f32_e32 v218, 0xbfb8aa3b, v217
	v_fma_f32 v219, v217, s27, -v218
	v_rndne_f32_e32 v226, v218
	v_fmac_f32_e32 v219, 0xb2a5705f, v217
	v_sub_f32_e32 v218, v218, v226
	v_add_f32_e32 v218, v218, v219
	v_cvt_i32_f32_e32 v219, v226
	v_exp_f32_e32 v218, v218
	v_cmp_nlt_f32_e32 vcc, s50, v217
	v_mul_f32_e32 v227, v216, v216
	v_ldexp_f32 v218, v218, v219
	v_fmamk_f32 v228, v227, 0xba1345e1, v212
	v_cndmask_b32_e32 v218, 0, v218, vcc
	v_cmp_ngt_f32_e32 vcc, s51, v217
	v_fmaak_f32 v228, v227, v228, 0xbcdac9b8
	v_fmaak_f32 v228, v227, v228, 0x3de703be
	v_cndmask_b32_e32 v217, v224, v218, vcc
	v_fmaak_f32 v228, v227, v228, 0xbec09330
	v_sub_f32_e32 v217, 1.0, v217
	v_fmaak_f32 v227, v227, v228, 0x3e0375d0
	v_cmp_nlt_f32_e64 vcc, |v216|, 1.0
	v_fma_f32 v227, |v216|, v227, |v216|
	v_mul_f32_e32 v229, 0.5, v229
	v_cndmask_b32_e32 v217, v227, v217, vcc
	v_bfi_b32 v217, s78, v217, v216
	v_add_f32_e32 v217, 1.0, v217
	v_mul_f32_e32 v229, v229, v217
	v_mul_f32_e32 v229, v60, v229
	v_mul_f32_e32 v205, v64, v229
	v_mul_f32_e32 v229, v239, v58
	v_mul_f32_e32 v229, v229, v63
	v_mul_f32_e32 v216, 0x3f3504f3, v229
	v_fma_f32 v217, |v216|, s8, v223
	v_fma_f32 v217, |v216|, v217, s9
	v_fma_f32 v217, |v216|, v217, s13
	v_fma_f32 v217, |v216|, v217, s32
	v_fma_f32 v217, |v216|, v217, s38
	v_fma_f32 v217, |v216|, v217, s49
	v_fma_f32 v217, |v216|, v217, |v216|
	v_mul_f32_e32 v218, 0xbfb8aa3b, v217
	v_fma_f32 v219, v217, s27, -v218
	v_rndne_f32_e32 v226, v218
	v_fmac_f32_e32 v219, 0xb2a5705f, v217
	v_sub_f32_e32 v218, v218, v226
	v_add_f32_e32 v218, v218, v219
	v_cvt_i32_f32_e32 v219, v226
	v_exp_f32_e32 v218, v218
	v_cmp_nlt_f32_e32 vcc, s50, v217
	v_mul_f32_e32 v227, v216, v216
	v_ldexp_f32 v218, v218, v219
	v_fmamk_f32 v228, v227, 0xba1345e1, v212
	v_cndmask_b32_e32 v218, 0, v218, vcc
	v_cmp_ngt_f32_e32 vcc, s51, v217
	v_fmaak_f32 v228, v227, v228, 0xbcdac9b8
	v_fmaak_f32 v228, v227, v228, 0x3de703be
	v_cndmask_b32_e32 v217, v224, v218, vcc
	v_fmaak_f32 v228, v227, v228, 0xbec09330
	v_sub_f32_e32 v217, 1.0, v217
	v_fmaak_f32 v227, v227, v228, 0x3e0375d0
	v_cmp_nlt_f32_e64 vcc, |v216|, 1.0
	v_fma_f32 v227, |v216|, v227, |v216|
	v_mul_f32_e32 v229, 0.5, v229
	v_cndmask_b32_e32 v217, v227, v217, vcc
	v_bfi_b32 v217, s78, v217, v216
	v_add_f32_e32 v217, 1.0, v217
	v_mul_f32_e32 v229, v229, v217
	v_mul_f32_e32 v229, v61, v229
	v_mul_f32_e32 v207, v65, v229
	ds_write_b128 v197, v[204:207] offset:4096
	s_waitcnt vmcnt(36)
	v_mov_b32_e32 v204, v12
	v_mov_b32_e32 v206, v13
	v_mul_f32_e32 v229, v240, v134
	v_mul_f32_e32 v229, v229, v138
	v_mul_f32_e32 v216, 0x3f3504f3, v229
	v_fma_f32 v217, |v216|, s8, v223
	v_fma_f32 v217, |v216|, v217, s9
	v_fma_f32 v217, |v216|, v217, s13
	v_fma_f32 v217, |v216|, v217, s32
	v_fma_f32 v217, |v216|, v217, s38
	v_fma_f32 v217, |v216|, v217, s49
	v_fma_f32 v217, |v216|, v217, |v216|
	v_mul_f32_e32 v218, 0xbfb8aa3b, v217
	v_fma_f32 v219, v217, s27, -v218
	v_rndne_f32_e32 v226, v218
	v_fmac_f32_e32 v219, 0xb2a5705f, v217
	v_sub_f32_e32 v218, v218, v226
	v_add_f32_e32 v218, v218, v219
	v_cvt_i32_f32_e32 v219, v226
	v_exp_f32_e32 v218, v218
	v_cmp_nlt_f32_e32 vcc, s50, v217
	v_mul_f32_e32 v227, v216, v216
	v_ldexp_f32 v218, v218, v219
	v_fmamk_f32 v228, v227, 0xba1345e1, v212
	v_cndmask_b32_e32 v218, 0, v218, vcc
	v_cmp_ngt_f32_e32 vcc, s51, v217
	v_fmaak_f32 v228, v227, v228, 0xbcdac9b8
	v_fmaak_f32 v228, v227, v228, 0x3de703be
	v_cndmask_b32_e32 v217, v224, v218, vcc
	v_fmaak_f32 v228, v227, v228, 0xbec09330
	v_sub_f32_e32 v217, 1.0, v217
	v_fmaak_f32 v227, v227, v228, 0x3e0375d0
	v_cmp_nlt_f32_e64 vcc, |v216|, 1.0
	v_fma_f32 v227, |v216|, v227, |v216|
	v_mul_f32_e32 v229, 0.5, v229
	v_cndmask_b32_e32 v217, v227, v217, vcc
	v_bfi_b32 v217, s78, v217, v216
	v_add_f32_e32 v217, 1.0, v217
	v_mul_f32_e32 v229, v229, v217
	v_mul_f32_e32 v229, v136, v229
	v_mul_f32_e32 v205, v140, v229
	v_mul_f32_e32 v229, v241, v134
	v_mul_f32_e32 v229, v229, v139
	v_mul_f32_e32 v216, 0x3f3504f3, v229
	v_fma_f32 v217, |v216|, s8, v223
	v_fma_f32 v217, |v216|, v217, s9
	v_fma_f32 v217, |v216|, v217, s13
	v_fma_f32 v217, |v216|, v217, s32
	v_fma_f32 v217, |v216|, v217, s38
	v_fma_f32 v217, |v216|, v217, s49
	v_fma_f32 v217, |v216|, v217, |v216|
	v_mul_f32_e32 v218, 0xbfb8aa3b, v217
	v_fma_f32 v219, v217, s27, -v218
	v_rndne_f32_e32 v226, v218
	v_fmac_f32_e32 v219, 0xb2a5705f, v217
	v_sub_f32_e32 v218, v218, v226
	v_add_f32_e32 v218, v218, v219
	v_cvt_i32_f32_e32 v219, v226
	v_exp_f32_e32 v218, v218
	v_cmp_nlt_f32_e32 vcc, s50, v217
	v_mul_f32_e32 v227, v216, v216
	v_ldexp_f32 v218, v218, v219
	v_fmamk_f32 v228, v227, 0xba1345e1, v212
	v_cndmask_b32_e32 v218, 0, v218, vcc
	v_cmp_ngt_f32_e32 vcc, s51, v217
	v_fmaak_f32 v228, v227, v228, 0xbcdac9b8
	v_fmaak_f32 v228, v227, v228, 0x3de703be
	v_cndmask_b32_e32 v217, v224, v218, vcc
	v_fmaak_f32 v228, v227, v228, 0xbec09330
	v_sub_f32_e32 v217, 1.0, v217
	v_fmaak_f32 v227, v227, v228, 0x3e0375d0
	v_cmp_nlt_f32_e64 vcc, |v216|, 1.0
	v_fma_f32 v227, |v216|, v227, |v216|
	v_mul_f32_e32 v229, 0.5, v229
	v_cndmask_b32_e32 v217, v227, v217, vcc
	v_bfi_b32 v217, s78, v217, v216
	v_add_f32_e32 v217, 1.0, v217
	v_mul_f32_e32 v229, v229, v217
	v_mul_f32_e32 v229, v137, v229
	v_mul_f32_e32 v207, v141, v229
	ds_write_b128 v197, v[204:207] offset:5120
	s_waitcnt vmcnt(30)
	v_mov_b32_e32 v204, v14
	v_mov_b32_e32 v206, v15
	v_mul_f32_e32 v229, v94, v142
	v_mul_f32_e32 v229, v229, v146
	v_mul_f32_e32 v216, 0x3f3504f3, v229
	v_fma_f32 v217, |v216|, s8, v223
	v_fma_f32 v217, |v216|, v217, s9
	v_fma_f32 v217, |v216|, v217, s13
	v_fma_f32 v217, |v216|, v217, s32
	v_fma_f32 v217, |v216|, v217, s38
	v_fma_f32 v217, |v216|, v217, s49
	v_fma_f32 v217, |v216|, v217, |v216|
	v_mul_f32_e32 v218, 0xbfb8aa3b, v217
	v_fma_f32 v219, v217, s27, -v218
	v_rndne_f32_e32 v226, v218
	v_fmac_f32_e32 v219, 0xb2a5705f, v217
	v_sub_f32_e32 v218, v218, v226
	v_add_f32_e32 v218, v218, v219
	v_cvt_i32_f32_e32 v219, v226
	v_exp_f32_e32 v218, v218
	v_cmp_nlt_f32_e32 vcc, s50, v217
	v_mul_f32_e32 v227, v216, v216
	v_ldexp_f32 v218, v218, v219
	v_fmamk_f32 v228, v227, 0xba1345e1, v212
	v_cndmask_b32_e32 v218, 0, v218, vcc
	v_cmp_ngt_f32_e32 vcc, s51, v217
	v_fmaak_f32 v228, v227, v228, 0xbcdac9b8
	v_fmaak_f32 v228, v227, v228, 0x3de703be
	v_cndmask_b32_e32 v217, v224, v218, vcc
	v_fmaak_f32 v228, v227, v228, 0xbec09330
	v_sub_f32_e32 v217, 1.0, v217
	v_fmaak_f32 v227, v227, v228, 0x3e0375d0
	v_cmp_nlt_f32_e64 vcc, |v216|, 1.0
	v_fma_f32 v227, |v216|, v227, |v216|
	v_mul_f32_e32 v229, 0.5, v229
	v_cndmask_b32_e32 v217, v227, v217, vcc
	v_bfi_b32 v217, s78, v217, v216
	v_add_f32_e32 v217, 1.0, v217
	v_mul_f32_e32 v229, v229, v217
	v_mul_f32_e32 v229, v144, v229
	v_mul_f32_e32 v205, v148, v229
	v_mul_f32_e32 v229, v95, v142
	v_mul_f32_e32 v229, v229, v147
	v_mul_f32_e32 v216, 0x3f3504f3, v229
	v_fma_f32 v217, |v216|, s8, v223
	v_fma_f32 v217, |v216|, v217, s9
	v_fma_f32 v217, |v216|, v217, s13
	v_fma_f32 v217, |v216|, v217, s32
	v_fma_f32 v217, |v216|, v217, s38
	v_fma_f32 v217, |v216|, v217, s49
	v_fma_f32 v217, |v216|, v217, |v216|
	v_mul_f32_e32 v218, 0xbfb8aa3b, v217
	v_fma_f32 v219, v217, s27, -v218
	v_rndne_f32_e32 v226, v218
	v_fmac_f32_e32 v219, 0xb2a5705f, v217
	v_sub_f32_e32 v218, v218, v226
	v_add_f32_e32 v218, v218, v219
	v_cvt_i32_f32_e32 v219, v226
	v_exp_f32_e32 v218, v218
	v_cmp_nlt_f32_e32 vcc, s50, v217
	v_mul_f32_e32 v227, v216, v216
	v_ldexp_f32 v218, v218, v219
	v_fmamk_f32 v228, v227, 0xba1345e1, v212
	v_cndmask_b32_e32 v218, 0, v218, vcc
	v_cmp_ngt_f32_e32 vcc, s51, v217
	v_fmaak_f32 v228, v227, v228, 0xbcdac9b8
	v_fmaak_f32 v228, v227, v228, 0x3de703be
	v_cndmask_b32_e32 v217, v224, v218, vcc
	v_fmaak_f32 v228, v227, v228, 0xbec09330
	v_sub_f32_e32 v217, 1.0, v217
	v_fmaak_f32 v227, v227, v228, 0x3e0375d0
	v_cmp_nlt_f32_e64 vcc, |v216|, 1.0
	v_fma_f32 v227, |v216|, v227, |v216|
	v_mul_f32_e32 v229, 0.5, v229
	v_cndmask_b32_e32 v217, v227, v217, vcc
	v_bfi_b32 v217, s78, v217, v216
	v_add_f32_e32 v217, 1.0, v217
	v_mul_f32_e32 v229, v229, v217
	v_mul_f32_e32 v229, v145, v229
	v_mul_f32_e32 v207, v149, v229
	ds_write_b128 v197, v[204:207] offset:6144
	s_waitcnt vmcnt(24)
	v_mov_b32_e32 v204, v16
	v_mov_b32_e32 v206, v17
	v_mul_f32_e32 v229, v96, v150
	v_mul_f32_e32 v229, v229, v154
	v_mul_f32_e32 v216, 0x3f3504f3, v229
	v_fma_f32 v217, |v216|, s8, v223
	v_fma_f32 v217, |v216|, v217, s9
	v_fma_f32 v217, |v216|, v217, s13
	v_fma_f32 v217, |v216|, v217, s32
	v_fma_f32 v217, |v216|, v217, s38
	v_fma_f32 v217, |v216|, v217, s49
	v_fma_f32 v217, |v216|, v217, |v216|
	v_mul_f32_e32 v218, 0xbfb8aa3b, v217
	v_fma_f32 v219, v217, s27, -v218
	v_rndne_f32_e32 v226, v218
	v_fmac_f32_e32 v219, 0xb2a5705f, v217
	v_sub_f32_e32 v218, v218, v226
	v_add_f32_e32 v218, v218, v219
	v_cvt_i32_f32_e32 v219, v226
	v_exp_f32_e32 v218, v218
	v_cmp_nlt_f32_e32 vcc, s50, v217
	v_mul_f32_e32 v227, v216, v216
	v_ldexp_f32 v218, v218, v219
	v_fmamk_f32 v228, v227, 0xba1345e1, v212
	v_cndmask_b32_e32 v218, 0, v218, vcc
	v_cmp_ngt_f32_e32 vcc, s51, v217
	v_fmaak_f32 v228, v227, v228, 0xbcdac9b8
	v_fmaak_f32 v228, v227, v228, 0x3de703be
	v_cndmask_b32_e32 v217, v224, v218, vcc
	v_fmaak_f32 v228, v227, v228, 0xbec09330
	v_sub_f32_e32 v217, 1.0, v217
	v_fmaak_f32 v227, v227, v228, 0x3e0375d0
	v_cmp_nlt_f32_e64 vcc, |v216|, 1.0
	v_fma_f32 v227, |v216|, v227, |v216|
	v_mul_f32_e32 v229, 0.5, v229
	v_cndmask_b32_e32 v217, v227, v217, vcc
	v_bfi_b32 v217, s78, v217, v216
	v_add_f32_e32 v217, 1.0, v217
	v_mul_f32_e32 v229, v229, v217
	v_mul_f32_e32 v229, v152, v229
	v_mul_f32_e32 v205, v156, v229
	v_mul_f32_e32 v229, v97, v150
	v_mul_f32_e32 v229, v229, v155
	v_mul_f32_e32 v216, 0x3f3504f3, v229
	v_fma_f32 v217, |v216|, s8, v223
	v_fma_f32 v217, |v216|, v217, s9
	v_fma_f32 v217, |v216|, v217, s13
	v_fma_f32 v217, |v216|, v217, s32
	v_fma_f32 v217, |v216|, v217, s38
	v_fma_f32 v217, |v216|, v217, s49
	v_fma_f32 v217, |v216|, v217, |v216|
	v_mul_f32_e32 v218, 0xbfb8aa3b, v217
	v_fma_f32 v219, v217, s27, -v218
	v_rndne_f32_e32 v226, v218
	v_fmac_f32_e32 v219, 0xb2a5705f, v217
	v_sub_f32_e32 v218, v218, v226
	v_add_f32_e32 v218, v218, v219
	v_cvt_i32_f32_e32 v219, v226
	v_exp_f32_e32 v218, v218
	v_cmp_nlt_f32_e32 vcc, s50, v217
	v_mul_f32_e32 v227, v216, v216
	v_ldexp_f32 v218, v218, v219
	v_fmamk_f32 v228, v227, 0xba1345e1, v212
	v_cndmask_b32_e32 v218, 0, v218, vcc
	v_cmp_ngt_f32_e32 vcc, s51, v217
	v_fmaak_f32 v228, v227, v228, 0xbcdac9b8
	v_fmaak_f32 v228, v227, v228, 0x3de703be
	v_cndmask_b32_e32 v217, v224, v218, vcc
	v_fmaak_f32 v228, v227, v228, 0xbec09330
	v_sub_f32_e32 v217, 1.0, v217
	v_fmaak_f32 v227, v227, v228, 0x3e0375d0
	v_cmp_nlt_f32_e64 vcc, |v216|, 1.0
	v_fma_f32 v227, |v216|, v227, |v216|
	v_mul_f32_e32 v229, 0.5, v229
	v_cndmask_b32_e32 v217, v227, v217, vcc
	v_bfi_b32 v217, s78, v217, v216
	v_add_f32_e32 v217, 1.0, v217
	v_mul_f32_e32 v229, v229, v217
	v_mul_f32_e32 v229, v153, v229
	v_mul_f32_e32 v207, v157, v229
	ds_write_b128 v197, v[204:207] offset:7168
	s_waitcnt vmcnt(18)
	v_mov_b32_e32 v204, v18
	v_mov_b32_e32 v206, v19
	v_mul_f32_e32 v229, v98, v158
	v_mul_f32_e32 v229, v229, v162
	v_mul_f32_e32 v216, 0x3f3504f3, v229
	v_fma_f32 v217, |v216|, s8, v223
	v_fma_f32 v217, |v216|, v217, s9
	v_fma_f32 v217, |v216|, v217, s13
	v_fma_f32 v217, |v216|, v217, s32
	v_fma_f32 v217, |v216|, v217, s38
	v_fma_f32 v217, |v216|, v217, s49
	v_fma_f32 v217, |v216|, v217, |v216|
	v_mul_f32_e32 v218, 0xbfb8aa3b, v217
	v_fma_f32 v219, v217, s27, -v218
	v_rndne_f32_e32 v226, v218
	v_fmac_f32_e32 v219, 0xb2a5705f, v217
	v_sub_f32_e32 v218, v218, v226
	v_add_f32_e32 v218, v218, v219
	v_cvt_i32_f32_e32 v219, v226
	v_exp_f32_e32 v218, v218
	v_cmp_nlt_f32_e32 vcc, s50, v217
	v_mul_f32_e32 v227, v216, v216
	v_ldexp_f32 v218, v218, v219
	v_fmamk_f32 v228, v227, 0xba1345e1, v212
	v_cndmask_b32_e32 v218, 0, v218, vcc
	v_cmp_ngt_f32_e32 vcc, s51, v217
	v_fmaak_f32 v228, v227, v228, 0xbcdac9b8
	v_fmaak_f32 v228, v227, v228, 0x3de703be
	v_cndmask_b32_e32 v217, v224, v218, vcc
	v_fmaak_f32 v228, v227, v228, 0xbec09330
	v_sub_f32_e32 v217, 1.0, v217
	v_fmaak_f32 v227, v227, v228, 0x3e0375d0
	v_cmp_nlt_f32_e64 vcc, |v216|, 1.0
	v_fma_f32 v227, |v216|, v227, |v216|
	v_mul_f32_e32 v229, 0.5, v229
	v_cndmask_b32_e32 v217, v227, v217, vcc
	v_bfi_b32 v217, s78, v217, v216
	v_add_f32_e32 v217, 1.0, v217
	v_mul_f32_e32 v229, v229, v217
	v_mul_f32_e32 v229, v160, v229
	v_mul_f32_e32 v205, v164, v229
	v_mul_f32_e32 v229, v99, v158
	v_mul_f32_e32 v229, v229, v163
	v_mul_f32_e32 v216, 0x3f3504f3, v229
	v_fma_f32 v217, |v216|, s8, v223
	v_fma_f32 v217, |v216|, v217, s9
	v_fma_f32 v217, |v216|, v217, s13
	v_fma_f32 v217, |v216|, v217, s32
	v_fma_f32 v217, |v216|, v217, s38
	v_fma_f32 v217, |v216|, v217, s49
	v_fma_f32 v217, |v216|, v217, |v216|
	v_mul_f32_e32 v218, 0xbfb8aa3b, v217
	v_fma_f32 v219, v217, s27, -v218
	v_rndne_f32_e32 v226, v218
	v_fmac_f32_e32 v219, 0xb2a5705f, v217
	v_sub_f32_e32 v218, v218, v226
	v_add_f32_e32 v218, v218, v219
	v_cvt_i32_f32_e32 v219, v226
	v_exp_f32_e32 v218, v218
	v_cmp_nlt_f32_e32 vcc, s50, v217
	v_mul_f32_e32 v227, v216, v216
	v_ldexp_f32 v218, v218, v219
	v_fmamk_f32 v228, v227, 0xba1345e1, v212
	v_cndmask_b32_e32 v218, 0, v218, vcc
	v_cmp_ngt_f32_e32 vcc, s51, v217
	v_fmaak_f32 v228, v227, v228, 0xbcdac9b8
	v_fmaak_f32 v228, v227, v228, 0x3de703be
	v_cndmask_b32_e32 v217, v224, v218, vcc
	v_fmaak_f32 v228, v227, v228, 0xbec09330
	v_sub_f32_e32 v217, 1.0, v217
	v_fmaak_f32 v227, v227, v228, 0x3e0375d0
	v_cmp_nlt_f32_e64 vcc, |v216|, 1.0
	v_fma_f32 v227, |v216|, v227, |v216|
	v_mul_f32_e32 v229, 0.5, v229
	v_cndmask_b32_e32 v217, v227, v217, vcc
	v_bfi_b32 v217, s78, v217, v216
	v_add_f32_e32 v217, 1.0, v217
	v_mul_f32_e32 v229, v229, v217
	v_mul_f32_e32 v229, v161, v229
	v_mul_f32_e32 v207, v165, v229
	ds_write_b128 v197, v[204:207] offset:8192
	s_waitcnt vmcnt(12)
	v_mov_b32_e32 v204, v20
	v_mov_b32_e32 v206, v21
	v_mul_f32_e32 v229, v100, v166
	v_mul_f32_e32 v229, v229, v170
	v_mul_f32_e32 v216, 0x3f3504f3, v229
	v_fma_f32 v217, |v216|, s8, v223
	v_fma_f32 v217, |v216|, v217, s9
	v_fma_f32 v217, |v216|, v217, s13
	v_fma_f32 v217, |v216|, v217, s32
	v_fma_f32 v217, |v216|, v217, s38
	v_fma_f32 v217, |v216|, v217, s49
	v_fma_f32 v217, |v216|, v217, |v216|
	v_mul_f32_e32 v218, 0xbfb8aa3b, v217
	v_fma_f32 v219, v217, s27, -v218
	v_rndne_f32_e32 v226, v218
	v_fmac_f32_e32 v219, 0xb2a5705f, v217
	v_sub_f32_e32 v218, v218, v226
	v_add_f32_e32 v218, v218, v219
	v_cvt_i32_f32_e32 v219, v226
	v_exp_f32_e32 v218, v218
	v_cmp_nlt_f32_e32 vcc, s50, v217
	v_mul_f32_e32 v227, v216, v216
	v_ldexp_f32 v218, v218, v219
	v_fmamk_f32 v228, v227, 0xba1345e1, v212
	v_cndmask_b32_e32 v218, 0, v218, vcc
	v_cmp_ngt_f32_e32 vcc, s51, v217
	v_fmaak_f32 v228, v227, v228, 0xbcdac9b8
	v_fmaak_f32 v228, v227, v228, 0x3de703be
	v_cndmask_b32_e32 v217, v224, v218, vcc
	v_fmaak_f32 v228, v227, v228, 0xbec09330
	v_sub_f32_e32 v217, 1.0, v217
	v_fmaak_f32 v227, v227, v228, 0x3e0375d0
	v_cmp_nlt_f32_e64 vcc, |v216|, 1.0
	v_fma_f32 v227, |v216|, v227, |v216|
	v_mul_f32_e32 v229, 0.5, v229
	v_cndmask_b32_e32 v217, v227, v217, vcc
	v_bfi_b32 v217, s78, v217, v216
	v_add_f32_e32 v217, 1.0, v217
	v_mul_f32_e32 v229, v229, v217
	v_mul_f32_e32 v229, v168, v229
	v_mul_f32_e32 v205, v172, v229
	v_mul_f32_e32 v229, v101, v166
	v_mul_f32_e32 v229, v229, v171
	v_mul_f32_e32 v216, 0x3f3504f3, v229
	v_fma_f32 v217, |v216|, s8, v223
	v_fma_f32 v217, |v216|, v217, s9
	v_fma_f32 v217, |v216|, v217, s13
	v_fma_f32 v217, |v216|, v217, s32
	v_fma_f32 v217, |v216|, v217, s38
	v_fma_f32 v217, |v216|, v217, s49
	v_fma_f32 v217, |v216|, v217, |v216|
	v_mul_f32_e32 v218, 0xbfb8aa3b, v217
	v_fma_f32 v219, v217, s27, -v218
	v_rndne_f32_e32 v226, v218
	v_fmac_f32_e32 v219, 0xb2a5705f, v217
	v_sub_f32_e32 v218, v218, v226
	v_add_f32_e32 v218, v218, v219
	v_cvt_i32_f32_e32 v219, v226
	v_exp_f32_e32 v218, v218
	v_cmp_nlt_f32_e32 vcc, s50, v217
	v_mul_f32_e32 v227, v216, v216
	v_ldexp_f32 v218, v218, v219
	v_fmamk_f32 v228, v227, 0xba1345e1, v212
	v_cndmask_b32_e32 v218, 0, v218, vcc
	v_cmp_ngt_f32_e32 vcc, s51, v217
	v_fmaak_f32 v228, v227, v228, 0xbcdac9b8
	v_fmaak_f32 v228, v227, v228, 0x3de703be
	v_cndmask_b32_e32 v217, v224, v218, vcc
	v_fmaak_f32 v228, v227, v228, 0xbec09330
	v_sub_f32_e32 v217, 1.0, v217
	v_fmaak_f32 v227, v227, v228, 0x3e0375d0
	v_cmp_nlt_f32_e64 vcc, |v216|, 1.0
	v_fma_f32 v227, |v216|, v227, |v216|
	v_mul_f32_e32 v229, 0.5, v229
	v_cndmask_b32_e32 v217, v227, v217, vcc
	v_bfi_b32 v217, s78, v217, v216
	v_add_f32_e32 v217, 1.0, v217
	v_mul_f32_e32 v229, v229, v217
	v_mul_f32_e32 v229, v169, v229
	v_mul_f32_e32 v207, v173, v229
	ds_write_b128 v197, v[204:207] offset:9216
	s_waitcnt vmcnt(6)
	v_mov_b32_e32 v204, v22
	v_mov_b32_e32 v206, v23
	v_mul_f32_e32 v229, v66, v180
	v_mul_f32_e32 v229, v229, v184
	v_mul_f32_e32 v216, 0x3f3504f3, v229
	v_fma_f32 v217, |v216|, s8, v223
	v_fma_f32 v217, |v216|, v217, s9
	v_fma_f32 v217, |v216|, v217, s13
	v_fma_f32 v217, |v216|, v217, s32
	v_fma_f32 v217, |v216|, v217, s38
	v_fma_f32 v217, |v216|, v217, s49
	v_fma_f32 v217, |v216|, v217, |v216|
	v_mul_f32_e32 v218, 0xbfb8aa3b, v217
	v_fma_f32 v219, v217, s27, -v218
	v_rndne_f32_e32 v226, v218
	v_fmac_f32_e32 v219, 0xb2a5705f, v217
	v_sub_f32_e32 v218, v218, v226
	v_add_f32_e32 v218, v218, v219
	v_cvt_i32_f32_e32 v219, v226
	v_exp_f32_e32 v218, v218
	v_cmp_nlt_f32_e32 vcc, s50, v217
	v_mul_f32_e32 v227, v216, v216
	v_ldexp_f32 v218, v218, v219
	v_fmamk_f32 v228, v227, 0xba1345e1, v212
	v_cndmask_b32_e32 v218, 0, v218, vcc
	v_cmp_ngt_f32_e32 vcc, s51, v217
	v_fmaak_f32 v228, v227, v228, 0xbcdac9b8
	v_fmaak_f32 v228, v227, v228, 0x3de703be
	v_cndmask_b32_e32 v217, v224, v218, vcc
	v_fmaak_f32 v228, v227, v228, 0xbec09330
	v_sub_f32_e32 v217, 1.0, v217
	v_fmaak_f32 v227, v227, v228, 0x3e0375d0
	v_cmp_nlt_f32_e64 vcc, |v216|, 1.0
	v_fma_f32 v227, |v216|, v227, |v216|
	v_mul_f32_e32 v229, 0.5, v229
	v_cndmask_b32_e32 v217, v227, v217, vcc
	v_bfi_b32 v217, s78, v217, v216
	v_add_f32_e32 v217, 1.0, v217
	v_mul_f32_e32 v229, v229, v217
	v_mul_f32_e32 v229, v182, v229
	v_mul_f32_e32 v205, v186, v229
	v_mul_f32_e32 v229, v67, v180
	v_mul_f32_e32 v229, v229, v185
	v_mul_f32_e32 v216, 0x3f3504f3, v229
	v_fma_f32 v217, |v216|, s8, v223
	v_fma_f32 v217, |v216|, v217, s9
	v_fma_f32 v217, |v216|, v217, s13
	v_fma_f32 v217, |v216|, v217, s32
	v_fma_f32 v217, |v216|, v217, s38
	v_fma_f32 v217, |v216|, v217, s49
	v_fma_f32 v217, |v216|, v217, |v216|
	v_mul_f32_e32 v218, 0xbfb8aa3b, v217
	v_fma_f32 v219, v217, s27, -v218
	v_rndne_f32_e32 v226, v218
	v_fmac_f32_e32 v219, 0xb2a5705f, v217
	v_sub_f32_e32 v218, v218, v226
	v_add_f32_e32 v218, v218, v219
	v_cvt_i32_f32_e32 v219, v226
	v_exp_f32_e32 v218, v218
	v_cmp_nlt_f32_e32 vcc, s50, v217
	v_mul_f32_e32 v227, v216, v216
	v_ldexp_f32 v218, v218, v219
	v_fmamk_f32 v228, v227, 0xba1345e1, v212
	v_cndmask_b32_e32 v218, 0, v218, vcc
	v_cmp_ngt_f32_e32 vcc, s51, v217
	v_fmaak_f32 v228, v227, v228, 0xbcdac9b8
	v_fmaak_f32 v228, v227, v228, 0x3de703be
	v_cndmask_b32_e32 v217, v224, v218, vcc
	v_fmaak_f32 v228, v227, v228, 0xbec09330
	v_sub_f32_e32 v217, 1.0, v217
	v_fmaak_f32 v227, v227, v228, 0x3e0375d0
	v_cmp_nlt_f32_e64 vcc, |v216|, 1.0
	v_fma_f32 v227, |v216|, v227, |v216|
	v_mul_f32_e32 v229, 0.5, v229
	v_cndmask_b32_e32 v217, v227, v217, vcc
	v_bfi_b32 v217, s78, v217, v216
	v_add_f32_e32 v217, 1.0, v217
	v_mul_f32_e32 v229, v229, v217
	v_mul_f32_e32 v229, v183, v229
	v_mul_f32_e32 v207, v187, v229
	ds_write_b128 v197, v[204:207] offset:10240
	s_waitcnt vmcnt(0)
	v_mov_b32_e32 v204, v24
	v_mov_b32_e32 v206, v25
	v_mul_f32_e32 v229, v68, v188
	v_mul_f32_e32 v229, v229, v192
	v_mul_f32_e32 v216, 0x3f3504f3, v229
	v_fma_f32 v217, |v216|, s8, v223
	v_fma_f32 v217, |v216|, v217, s9
	v_fma_f32 v217, |v216|, v217, s13
	v_fma_f32 v217, |v216|, v217, s32
	v_fma_f32 v217, |v216|, v217, s38
	v_fma_f32 v217, |v216|, v217, s49
	v_fma_f32 v217, |v216|, v217, |v216|
	v_mul_f32_e32 v218, 0xbfb8aa3b, v217
	v_fma_f32 v219, v217, s27, -v218
	v_rndne_f32_e32 v226, v218
	v_fmac_f32_e32 v219, 0xb2a5705f, v217
	v_sub_f32_e32 v218, v218, v226
	v_add_f32_e32 v218, v218, v219
	v_cvt_i32_f32_e32 v219, v226
	v_exp_f32_e32 v218, v218
	v_cmp_nlt_f32_e32 vcc, s50, v217
	v_mul_f32_e32 v227, v216, v216
	v_ldexp_f32 v218, v218, v219
	v_fmamk_f32 v228, v227, 0xba1345e1, v212
	v_cndmask_b32_e32 v218, 0, v218, vcc
	v_cmp_ngt_f32_e32 vcc, s51, v217
	v_fmaak_f32 v228, v227, v228, 0xbcdac9b8
	v_fmaak_f32 v228, v227, v228, 0x3de703be
	v_cndmask_b32_e32 v217, v224, v218, vcc
	v_fmaak_f32 v228, v227, v228, 0xbec09330
	v_sub_f32_e32 v217, 1.0, v217
	v_fmaak_f32 v227, v227, v228, 0x3e0375d0
	v_cmp_nlt_f32_e64 vcc, |v216|, 1.0
	v_fma_f32 v227, |v216|, v227, |v216|
	v_mul_f32_e32 v229, 0.5, v229
	v_cndmask_b32_e32 v217, v227, v217, vcc
	v_bfi_b32 v217, s78, v217, v216
	v_add_f32_e32 v217, 1.0, v217
	v_mul_f32_e32 v229, v229, v217
	v_mul_f32_e32 v229, v190, v229
	v_mul_f32_e32 v205, v194, v229
	v_mul_f32_e32 v229, v69, v188
	v_mul_f32_e32 v229, v229, v193
	v_mul_f32_e32 v216, 0x3f3504f3, v229
	v_fma_f32 v217, |v216|, s8, v223
	v_fma_f32 v217, |v216|, v217, s9
	v_fma_f32 v217, |v216|, v217, s13
	v_fma_f32 v217, |v216|, v217, s32
	v_fma_f32 v217, |v216|, v217, s38
	v_fma_f32 v217, |v216|, v217, s49
	v_fma_f32 v217, |v216|, v217, |v216|
	v_mul_f32_e32 v218, 0xbfb8aa3b, v217
	v_fma_f32 v219, v217, s27, -v218
	v_rndne_f32_e32 v226, v218
	v_fmac_f32_e32 v219, 0xb2a5705f, v217
	v_sub_f32_e32 v218, v218, v226
	v_add_f32_e32 v218, v218, v219
	v_cvt_i32_f32_e32 v219, v226
	v_exp_f32_e32 v218, v218
	v_cmp_nlt_f32_e32 vcc, s50, v217
	v_mul_f32_e32 v227, v216, v216
	v_ldexp_f32 v218, v218, v219
	v_fmamk_f32 v228, v227, 0xba1345e1, v212
	v_cndmask_b32_e32 v218, 0, v218, vcc
	v_cmp_ngt_f32_e32 vcc, s51, v217
	v_fmaak_f32 v228, v227, v228, 0xbcdac9b8
	v_fmaak_f32 v228, v227, v228, 0x3de703be
	v_cndmask_b32_e32 v217, v224, v218, vcc
	v_fmaak_f32 v228, v227, v228, 0xbec09330
	v_sub_f32_e32 v217, 1.0, v217
	v_fmaak_f32 v227, v227, v228, 0x3e0375d0
	v_cmp_nlt_f32_e64 vcc, |v216|, 1.0
	v_fma_f32 v227, |v216|, v227, |v216|
	v_mul_f32_e32 v229, 0.5, v229
	v_cndmask_b32_e32 v217, v227, v217, vcc
	v_bfi_b32 v217, s78, v217, v216
	v_add_f32_e32 v217, 1.0, v217
	v_mul_f32_e32 v229, v229, v217
	v_mul_f32_e32 v229, v191, v229
	v_mul_f32_e32 v207, v195, v229
	ds_write_b128 v197, v[204:207] offset:11264
	s_waitcnt lgkmcnt(0)
	s_mov_b32 s10, 0
	s_branch .LBB0_2135
